# k-step pairing per accumulator, pairs ordered so consecutive pairs share the B fragment
# speedup vs baseline: 1.0012x; 1.0012x over previous
.LBB0_257:
	s_or_b64 exec, exec, s[50:51]
	s_add_u32 s0, s12, s6
	ds_read_b128 v[146:149], v137
	ds_read_b128 v[150:153], v137 offset:1024
	ds_read_b128 v[154:157], v137 offset:2048
	ds_read_b128 v[158:161], v137 offset:3072
	ds_read_b128 v[162:165], v138
	ds_read_b128 v[166:169], v138 offset:1024
	ds_read_b128 v[170:173], v138 offset:2048
	ds_read_b128 v[174:177], v138 offset:3072
	s_addc_u32 s1, s13, s7
	s_add_u32 s50, s0, 0x20000
	s_addc_u32 s51, s1, 0
	s_add_u32 s52, s93, s6
	s_addc_u32 s53, s94, s7
	s_cmp_eq_u32 s6, 0x60000
	s_cselect_b32 s62, s95, s50
	s_cselect_b32 s63, s31, s51
	s_cselect_b32 s51, s29, s53
	s_cselect_b32 s50, s96, s52
	s_add_u32 s52, s62, 0x8000
	s_addc_u32 s53, s63, 0
	s_add_u32 s54, s50, 0x8000
	s_addc_u32 s55, s51, 0
	ds_read_b128 v[178:181], v139
	ds_read_b128 v[182:185], v139 offset:1024
	ds_read_b128 v[186:189], v139 offset:2048
	ds_read_b128 v[190:193], v139 offset:3072
	ds_read_b128 v[198:201], v139 offset:4096
	ds_read_b128 v[202:205], v139 offset:5120
	ds_read_b128 v[206:209], v139 offset:6144
	ds_read_b128 v[212:215], v139 offset:7168
	s_add_u32 s0, s0, 0x1c000
	s_addc_u32 s1, s1, 0
	s_mov_b32 m0, s78
	s_nop 0
	global_load_lds_dwordx4 v134, s[0:1]
	s_add_u32 m0, s78, 0x2000
	s_nop 0
	global_load_lds_dwordx4 v135, s[0:1]
	s_waitcnt vmcnt(8)
	s_waitcnt lgkmcnt(0)
	s_setprio 1
	s_barrier
	v_mfma_f32_16x16x32_bf16 v[122:125], v[146:149], v[178:181], v[122:125]
	v_mfma_f32_16x16x32_bf16 v[122:125], v[150:153], v[182:185], v[122:125]
	s_waitcnt lgkmcnt(5)
	v_mfma_f32_16x16x32_bf16 v[106:109], v[146:149], v[186:189], v[106:109]
	v_mfma_f32_16x16x32_bf16 v[106:109], v[150:153], v[190:193], v[106:109]
	s_waitcnt lgkmcnt(3)
	v_mfma_f32_16x16x32_bf16 v[90:93], v[146:149], v[198:201], v[90:93]
	v_mfma_f32_16x16x32_bf16 v[90:93], v[150:153], v[202:205], v[90:93]
	s_waitcnt lgkmcnt(1)
	v_mfma_f32_16x16x32_bf16 v[74:77], v[146:149], v[206:209], v[74:77]
	v_mfma_f32_16x16x32_bf16 v[74:77], v[150:153], v[212:215], v[74:77]
	v_mfma_f32_16x16x32_bf16 v[114:117], v[154:157], v[178:181], v[114:117]
	v_mfma_f32_16x16x32_bf16 v[114:117], v[158:161], v[182:185], v[114:117]
	v_mfma_f32_16x16x32_bf16 v[98:101], v[154:157], v[186:189], v[98:101]
	v_mfma_f32_16x16x32_bf16 v[98:101], v[158:161], v[190:193], v[98:101]
	v_mfma_f32_16x16x32_bf16 v[82:85], v[154:157], v[198:201], v[82:85]
	v_mfma_f32_16x16x32_bf16 v[82:85], v[158:161], v[202:205], v[82:85]
	s_waitcnt lgkmcnt(0)
	v_mfma_f32_16x16x32_bf16 v[66:69], v[154:157], v[206:209], v[66:69]
	v_mfma_f32_16x16x32_bf16 v[66:69], v[158:161], v[212:215], v[66:69]
	s_setprio 0
	s_setprio 1
	v_mfma_f32_16x16x32_bf16 v[126:129], v[162:165], v[178:181], v[126:129]
	v_mfma_f32_16x16x32_bf16 v[126:129], v[166:169], v[182:185], v[126:129]
	v_mfma_f32_16x16x32_bf16 v[110:113], v[162:165], v[186:189], v[110:113]
	v_mfma_f32_16x16x32_bf16 v[110:113], v[166:169], v[190:193], v[110:113]
	v_mfma_f32_16x16x32_bf16 v[94:97], v[162:165], v[198:201], v[94:97]
	v_mfma_f32_16x16x32_bf16 v[94:97], v[166:169], v[202:205], v[94:97]
	v_mfma_f32_16x16x32_bf16 v[78:81], v[162:165], v[206:209], v[78:81]
	v_mfma_f32_16x16x32_bf16 v[78:81], v[166:169], v[212:215], v[78:81]
	v_mfma_f32_16x16x32_bf16 v[118:121], v[170:173], v[178:181], v[118:121]
	v_mfma_f32_16x16x32_bf16 v[118:121], v[174:177], v[182:185], v[118:121]
	v_mfma_f32_16x16x32_bf16 v[102:105], v[170:173], v[186:189], v[102:105]
	v_mfma_f32_16x16x32_bf16 v[102:105], v[174:177], v[190:193], v[102:105]
	v_mfma_f32_16x16x32_bf16 v[86:89], v[170:173], v[198:201], v[86:89]
	v_mfma_f32_16x16x32_bf16 v[86:89], v[174:177], v[202:205], v[86:89]
	s_setprio 2
	s_barrier
	v_mfma_f32_16x16x32_bf16 v[70:73], v[170:173], v[206:209], v[70:73]
	v_mfma_f32_16x16x32_bf16 v[70:73], v[174:177], v[212:215], v[70:73]
	s_setprio 0
	s_nop 0
	ds_read_b128 v[178:181], v139 offset:16384
	ds_read_b128 v[182:185], v139 offset:17408
	ds_read_b128 v[186:189], v139 offset:18432
	ds_read_b128 v[190:193], v139 offset:19456
	ds_read_b128 v[198:201], v139 offset:20480
	ds_read_b128 v[202:205], v139 offset:21504
	ds_read_b128 v[206:209], v139 offset:22528
	ds_read_b128 v[212:215], v139 offset:23552
	s_mov_b32 m0, s11
	s_nop 0
	global_load_lds_dwordx4 v134, s[50:51]
	s_add_u32 m0, s11, 0x2000
	s_nop 0
	global_load_lds_dwordx4 v135, s[50:51]
	s_add_u32 s0, s50, 0x4000
	s_addc_u32 s1, s51, 0
	s_mov_b32 m0, s68
	s_nop 0
	global_load_lds_dwordx4 v134, s[0:1]
	s_add_u32 m0, s68, 0x2000
	s_nop 0
	global_load_lds_dwordx4 v135, s[0:1]
	s_nop 0
	s_mov_b32 m0, s65
	s_nop 0
	global_load_lds_dwordx4 v134, s[62:63]
	s_add_u32 m0, s65, 0x2000
	s_nop 0
	global_load_lds_dwordx4 v135, s[62:63]
	s_waitcnt vmcnt(8)
	s_waitcnt lgkmcnt(0)
	s_setprio 1
	s_barrier
	v_mfma_f32_16x16x32_bf16 v[58:61], v[146:149], v[178:181], v[58:61]
	v_mfma_f32_16x16x32_bf16 v[58:61], v[150:153], v[182:185], v[58:61]
	s_waitcnt lgkmcnt(5)
	v_mfma_f32_16x16x32_bf16 v[42:45], v[146:149], v[186:189], v[42:45]
	v_mfma_f32_16x16x32_bf16 v[42:45], v[150:153], v[190:193], v[42:45]
	s_waitcnt lgkmcnt(3)
	v_mfma_f32_16x16x32_bf16 v[26:29], v[146:149], v[198:201], v[26:29]
	v_mfma_f32_16x16x32_bf16 v[26:29], v[150:153], v[202:205], v[26:29]
	s_waitcnt lgkmcnt(1)
	v_mfma_f32_16x16x32_bf16 v[10:13], v[146:149], v[206:209], v[10:13]
	v_mfma_f32_16x16x32_bf16 v[10:13], v[150:153], v[212:215], v[10:13]
	v_mfma_f32_16x16x32_bf16 v[50:53], v[154:157], v[178:181], v[50:53]
	v_mfma_f32_16x16x32_bf16 v[50:53], v[158:161], v[182:185], v[50:53]
	v_mfma_f32_16x16x32_bf16 v[34:37], v[154:157], v[186:189], v[34:37]
	v_mfma_f32_16x16x32_bf16 v[34:37], v[158:161], v[190:193], v[34:37]
	v_mfma_f32_16x16x32_bf16 v[18:21], v[154:157], v[198:201], v[18:21]
	v_mfma_f32_16x16x32_bf16 v[18:21], v[158:161], v[202:205], v[18:21]
	s_waitcnt lgkmcnt(0)
	v_mfma_f32_16x16x32_bf16 v[2:5], v[154:157], v[206:209], v[2:5]
	v_mfma_f32_16x16x32_bf16 v[2:5], v[158:161], v[212:215], v[2:5]
	s_setprio 0
	s_setprio 1
	v_mfma_f32_16x16x32_bf16 v[62:65], v[162:165], v[178:181], v[62:65]
	v_mfma_f32_16x16x32_bf16 v[62:65], v[166:169], v[182:185], v[62:65]
	v_mfma_f32_16x16x32_bf16 v[46:49], v[162:165], v[186:189], v[46:49]
	v_mfma_f32_16x16x32_bf16 v[46:49], v[166:169], v[190:193], v[46:49]
	v_mfma_f32_16x16x32_bf16 v[30:33], v[162:165], v[198:201], v[30:33]
	v_mfma_f32_16x16x32_bf16 v[30:33], v[166:169], v[202:205], v[30:33]
	v_mfma_f32_16x16x32_bf16 v[14:17], v[162:165], v[206:209], v[14:17]
	v_mfma_f32_16x16x32_bf16 v[14:17], v[166:169], v[212:215], v[14:17]
	v_mfma_f32_16x16x32_bf16 v[54:57], v[170:173], v[178:181], v[54:57]
	v_mfma_f32_16x16x32_bf16 v[54:57], v[174:177], v[182:185], v[54:57]
	v_mfma_f32_16x16x32_bf16 v[38:41], v[170:173], v[186:189], v[38:41]
	v_mfma_f32_16x16x32_bf16 v[38:41], v[174:177], v[190:193], v[38:41]
	v_mfma_f32_16x16x32_bf16 v[22:25], v[170:173], v[198:201], v[22:25]
	v_mfma_f32_16x16x32_bf16 v[22:25], v[174:177], v[202:205], v[22:25]
	s_setprio 2
	s_barrier
	v_mfma_f32_16x16x32_bf16 v[6:9], v[170:173], v[206:209], v[6:9]
	v_mfma_f32_16x16x32_bf16 v[6:9], v[174:177], v[212:215], v[6:9]
	s_setprio 0
	s_nop 0
	ds_read_b128 v[146:149], v140
	ds_read_b128 v[150:153], v140 offset:1024
	ds_read_b128 v[154:157], v140 offset:2048
	ds_read_b128 v[158:161], v140 offset:3072
	ds_read_b128 v[162:165], v141
	ds_read_b128 v[166:169], v141 offset:1024
	ds_read_b128 v[170:173], v141 offset:2048
	ds_read_b128 v[174:177], v141 offset:3072
	ds_read_b128 v[178:181], v139 offset:32768
	ds_read_b128 v[182:185], v139 offset:33792
	ds_read_b128 v[186:189], v139 offset:34816
	ds_read_b128 v[190:193], v139 offset:35840
	ds_read_b128 v[198:201], v139 offset:36864
	ds_read_b128 v[202:205], v139 offset:37888
	ds_read_b128 v[206:209], v139 offset:38912
	ds_read_b128 v[212:215], v139 offset:39936
	s_add_u32 s0, s62, 0x4000
	s_addc_u32 s1, s63, 0
	s_mov_b32 m0, s69
	s_nop 0
	global_load_lds_dwordx4 v134, s[0:1]
	s_add_u32 m0, s69, 0x2000
	s_nop 0
	global_load_lds_dwordx4 v135, s[0:1]
	s_waitcnt vmcnt(8)
	s_waitcnt lgkmcnt(0)
	s_setprio 1
	s_barrier
	v_mfma_f32_16x16x32_bf16 v[122:125], v[146:149], v[178:181], v[122:125]
	v_mfma_f32_16x16x32_bf16 v[122:125], v[150:153], v[182:185], v[122:125]
	s_waitcnt lgkmcnt(5)
	v_mfma_f32_16x16x32_bf16 v[106:109], v[146:149], v[186:189], v[106:109]
	v_mfma_f32_16x16x32_bf16 v[106:109], v[150:153], v[190:193], v[106:109]
	s_waitcnt lgkmcnt(3)
	v_mfma_f32_16x16x32_bf16 v[90:93], v[146:149], v[198:201], v[90:93]
	v_mfma_f32_16x16x32_bf16 v[90:93], v[150:153], v[202:205], v[90:93]
	s_waitcnt lgkmcnt(1)
	v_mfma_f32_16x16x32_bf16 v[74:77], v[146:149], v[206:209], v[74:77]
	v_mfma_f32_16x16x32_bf16 v[74:77], v[150:153], v[212:215], v[74:77]
	v_mfma_f32_16x16x32_bf16 v[114:117], v[154:157], v[178:181], v[114:117]
	v_mfma_f32_16x16x32_bf16 v[114:117], v[158:161], v[182:185], v[114:117]
	v_mfma_f32_16x16x32_bf16 v[98:101], v[154:157], v[186:189], v[98:101]
	v_mfma_f32_16x16x32_bf16 v[98:101], v[158:161], v[190:193], v[98:101]
	v_mfma_f32_16x16x32_bf16 v[82:85], v[154:157], v[198:201], v[82:85]
	v_mfma_f32_16x16x32_bf16 v[82:85], v[158:161], v[202:205], v[82:85]
	s_waitcnt lgkmcnt(0)
	v_mfma_f32_16x16x32_bf16 v[66:69], v[154:157], v[206:209], v[66:69]
	v_mfma_f32_16x16x32_bf16 v[66:69], v[158:161], v[212:215], v[66:69]
	s_setprio 0
	s_setprio 1
	v_mfma_f32_16x16x32_bf16 v[126:129], v[162:165], v[178:181], v[126:129]
	v_mfma_f32_16x16x32_bf16 v[126:129], v[166:169], v[182:185], v[126:129]
	v_mfma_f32_16x16x32_bf16 v[110:113], v[162:165], v[186:189], v[110:113]
	v_mfma_f32_16x16x32_bf16 v[110:113], v[166:169], v[190:193], v[110:113]
	v_mfma_f32_16x16x32_bf16 v[94:97], v[162:165], v[198:201], v[94:97]
	v_mfma_f32_16x16x32_bf16 v[94:97], v[166:169], v[202:205], v[94:97]
	v_mfma_f32_16x16x32_bf16 v[78:81], v[162:165], v[206:209], v[78:81]
	v_mfma_f32_16x16x32_bf16 v[78:81], v[166:169], v[212:215], v[78:81]
	v_mfma_f32_16x16x32_bf16 v[118:121], v[170:173], v[178:181], v[118:121]
	v_mfma_f32_16x16x32_bf16 v[118:121], v[174:177], v[182:185], v[118:121]
	v_mfma_f32_16x16x32_bf16 v[102:105], v[170:173], v[186:189], v[102:105]
	v_mfma_f32_16x16x32_bf16 v[102:105], v[174:177], v[190:193], v[102:105]
	v_mfma_f32_16x16x32_bf16 v[86:89], v[170:173], v[198:201], v[86:89]
	v_mfma_f32_16x16x32_bf16 v[86:89], v[174:177], v[202:205], v[86:89]
	s_setprio 2
	s_barrier
	v_mfma_f32_16x16x32_bf16 v[70:73], v[170:173], v[206:209], v[70:73]
	v_mfma_f32_16x16x32_bf16 v[70:73], v[174:177], v[212:215], v[70:73]
	s_setprio 0
	s_nop 0
	ds_read_b128 v[178:181], v139 offset:49152
	ds_read_b128 v[182:185], v139 offset:50176
	ds_read_b128 v[186:189], v139 offset:51200
	ds_read_b128 v[190:193], v139 offset:52224
	ds_read_b128 v[198:201], v139 offset:53248
	ds_read_b128 v[202:205], v139 offset:54272
	ds_read_b128 v[206:209], v139 offset:55296
	ds_read_b128 v[212:215], v139 offset:56320
	s_mov_b32 m0, s74
	s_nop 0
	global_load_lds_dwordx4 v134, s[54:55]
	s_add_u32 m0, s74, 0x2000
	s_nop 0
	global_load_lds_dwordx4 v135, s[54:55]
	s_add_u32 s0, s50, 0xc000
	s_addc_u32 s1, s51, 0
	s_mov_b32 m0, s77
	s_nop 0
	global_load_lds_dwordx4 v134, s[0:1]
	s_add_u32 m0, s77, 0x2000
	s_nop 0
	global_load_lds_dwordx4 v135, s[0:1]
	s_nop 0
	s_mov_b32 m0, s76
	s_nop 0
	global_load_lds_dwordx4 v134, s[52:53]
	s_add_u32 m0, s76, 0x2000
	s_nop 0
	global_load_lds_dwordx4 v135, s[52:53]
	s_waitcnt vmcnt(8)
	s_waitcnt lgkmcnt(0)
	s_setprio 1
	s_barrier
	v_mfma_f32_16x16x32_bf16 v[58:61], v[146:149], v[178:181], v[58:61]
	v_mfma_f32_16x16x32_bf16 v[58:61], v[150:153], v[182:185], v[58:61]
	s_waitcnt lgkmcnt(5)
	v_mfma_f32_16x16x32_bf16 v[42:45], v[146:149], v[186:189], v[42:45]
	v_mfma_f32_16x16x32_bf16 v[42:45], v[150:153], v[190:193], v[42:45]
	s_waitcnt lgkmcnt(3)
	v_mfma_f32_16x16x32_bf16 v[26:29], v[146:149], v[198:201], v[26:29]
	v_mfma_f32_16x16x32_bf16 v[26:29], v[150:153], v[202:205], v[26:29]
	s_waitcnt lgkmcnt(1)
	v_mfma_f32_16x16x32_bf16 v[10:13], v[146:149], v[206:209], v[10:13]
	v_mfma_f32_16x16x32_bf16 v[10:13], v[150:153], v[212:215], v[10:13]
	v_mfma_f32_16x16x32_bf16 v[50:53], v[154:157], v[178:181], v[50:53]
	v_mfma_f32_16x16x32_bf16 v[50:53], v[158:161], v[182:185], v[50:53]
	v_mfma_f32_16x16x32_bf16 v[34:37], v[154:157], v[186:189], v[34:37]
	v_mfma_f32_16x16x32_bf16 v[34:37], v[158:161], v[190:193], v[34:37]
	v_mfma_f32_16x16x32_bf16 v[18:21], v[154:157], v[198:201], v[18:21]
	v_mfma_f32_16x16x32_bf16 v[18:21], v[158:161], v[202:205], v[18:21]
	s_waitcnt lgkmcnt(0)
	v_mfma_f32_16x16x32_bf16 v[2:5], v[154:157], v[206:209], v[2:5]
	v_mfma_f32_16x16x32_bf16 v[2:5], v[158:161], v[212:215], v[2:5]
	s_setprio 0
	s_setprio 1
	v_mfma_f32_16x16x32_bf16 v[62:65], v[162:165], v[178:181], v[62:65]
	v_mfma_f32_16x16x32_bf16 v[62:65], v[166:169], v[182:185], v[62:65]
	v_mfma_f32_16x16x32_bf16 v[46:49], v[162:165], v[186:189], v[46:49]
	v_mfma_f32_16x16x32_bf16 v[46:49], v[166:169], v[190:193], v[46:49]
	v_mfma_f32_16x16x32_bf16 v[30:33], v[162:165], v[198:201], v[30:33]
	v_mfma_f32_16x16x32_bf16 v[30:33], v[166:169], v[202:205], v[30:33]
	v_mfma_f32_16x16x32_bf16 v[14:17], v[162:165], v[206:209], v[14:17]
	v_mfma_f32_16x16x32_bf16 v[14:17], v[166:169], v[212:215], v[14:17]
	v_mfma_f32_16x16x32_bf16 v[54:57], v[170:173], v[178:181], v[54:57]
	v_mfma_f32_16x16x32_bf16 v[54:57], v[174:177], v[182:185], v[54:57]
	v_mfma_f32_16x16x32_bf16 v[38:41], v[170:173], v[186:189], v[38:41]
	v_mfma_f32_16x16x32_bf16 v[38:41], v[174:177], v[190:193], v[38:41]
	v_mfma_f32_16x16x32_bf16 v[22:25], v[170:173], v[198:201], v[22:25]
	v_mfma_f32_16x16x32_bf16 v[22:25], v[174:177], v[202:205], v[22:25]
	s_setprio 2
	s_barrier
	v_mfma_f32_16x16x32_bf16 v[6:9], v[170:173], v[206:209], v[6:9]
	v_mfma_f32_16x16x32_bf16 v[6:9], v[174:177], v[212:215], v[6:9]
	s_setprio 0
	s_nop 0
	s_add_i32 s97, s97, 2
	s_add_u32 s6, s6, 0x10000
	s_addc_u32 s7, s7, 0
	s_cmp_gt_u32 s97, 13
	s_cbranch_scc1 .LBB0_259
	v_mov_b32_e32 v145, v130
	s_branch .LBB0_255

.LBB0_364:
	s_add_i32 s26, s93, 2
	s_lshl_b64 s[62:63], s[26:27], 15
	s_add_u32 s64, s18, s62
	s_addc_u32 s65, s19, s63
	s_and_b64 s[52:53], s[50:51], exec
	s_cselect_b32 s53, s65, s39
	s_cselect_b32 s52, s64, s38
	s_add_u32 s62, s20, s62
	s_waitcnt vmcnt(8)
	s_addc_u32 s63, s21, s63
	s_waitcnt lgkmcnt(0)
	s_and_b64 s[50:51], s[50:51], exec
	s_cselect_b32 s51, s63, s49
	s_cselect_b32 s50, s62, s48
	s_setprio 1
	s_barrier
	v_mfma_f32_16x16x32_bf16 v[126:129], v[146:149], v[186:189], v[126:129]
	v_mfma_f32_16x16x32_bf16 v[126:129], v[150:153], v[190:193], v[126:129]
	s_waitcnt lgkmcnt(5)
	v_mfma_f32_16x16x32_bf16 v[118:121], v[146:149], v[178:181], v[118:121]
	v_mfma_f32_16x16x32_bf16 v[118:121], v[150:153], v[182:185], v[118:121]
	s_waitcnt lgkmcnt(3)
	v_mfma_f32_16x16x32_bf16 v[110:113], v[146:149], v[170:173], v[110:113]
	v_mfma_f32_16x16x32_bf16 v[110:113], v[150:153], v[174:177], v[110:113]
	s_waitcnt lgkmcnt(1)
	v_mfma_f32_16x16x32_bf16 v[102:105], v[146:149], v[162:165], v[102:105]
	v_mfma_f32_16x16x32_bf16 v[102:105], v[150:153], v[166:169], v[102:105]
	v_mfma_f32_16x16x32_bf16 v[122:125], v[154:157], v[186:189], v[122:125]
	v_mfma_f32_16x16x32_bf16 v[122:125], v[158:161], v[190:193], v[122:125]
	v_mfma_f32_16x16x32_bf16 v[114:117], v[154:157], v[178:181], v[114:117]
	v_mfma_f32_16x16x32_bf16 v[114:117], v[158:161], v[182:185], v[114:117]
	v_mfma_f32_16x16x32_bf16 v[106:109], v[154:157], v[170:173], v[106:109]
	v_mfma_f32_16x16x32_bf16 v[106:109], v[158:161], v[174:177], v[106:109]
	s_waitcnt lgkmcnt(0)
	v_mfma_f32_16x16x32_bf16 v[98:101], v[154:157], v[162:165], v[98:101]
	v_mfma_f32_16x16x32_bf16 v[98:101], v[158:161], v[166:169], v[98:101]
	s_setprio 0
	s_setprio 1
	v_mfma_f32_16x16x32_bf16 v[94:97], v[130:133], v[186:189], v[94:97]
	v_mfma_f32_16x16x32_bf16 v[94:97], v[134:137], v[190:193], v[94:97]
	v_mfma_f32_16x16x32_bf16 v[86:89], v[130:133], v[178:181], v[86:89]
	v_mfma_f32_16x16x32_bf16 v[86:89], v[134:137], v[182:185], v[86:89]
	v_mfma_f32_16x16x32_bf16 v[78:81], v[130:133], v[170:173], v[78:81]
	v_mfma_f32_16x16x32_bf16 v[78:81], v[134:137], v[174:177], v[78:81]
	v_mfma_f32_16x16x32_bf16 v[70:73], v[130:133], v[162:165], v[70:73]
	v_mfma_f32_16x16x32_bf16 v[70:73], v[134:137], v[166:169], v[70:73]
	v_mfma_f32_16x16x32_bf16 v[90:93], v[138:141], v[186:189], v[90:93]
	v_mfma_f32_16x16x32_bf16 v[90:93], v[142:145], v[190:193], v[90:93]
	v_mfma_f32_16x16x32_bf16 v[82:85], v[138:141], v[178:181], v[82:85]
	v_mfma_f32_16x16x32_bf16 v[82:85], v[142:145], v[182:185], v[82:85]
	v_mfma_f32_16x16x32_bf16 v[74:77], v[138:141], v[170:173], v[74:77]
	v_mfma_f32_16x16x32_bf16 v[74:77], v[142:145], v[174:177], v[74:77]
	s_setprio 2
	s_barrier
	v_mfma_f32_16x16x32_bf16 v[66:69], v[138:141], v[162:165], v[66:69]
	v_mfma_f32_16x16x32_bf16 v[66:69], v[142:145], v[166:169], v[66:69]
	s_setprio 0
	s_nop 0
	ds_read_b128 v[186:189], v219 offset:16384
	ds_read_b128 v[190:193], v219 offset:17408
	ds_read_b128 v[178:181], v219 offset:18432
	ds_read_b128 v[182:185], v219 offset:19456
	ds_read_b128 v[170:173], v219 offset:20480
	ds_read_b128 v[174:177], v219 offset:21504
	ds_read_b128 v[162:165], v219 offset:22528
	ds_read_b128 v[166:169], v219 offset:23552
	s_mov_b32 m0, s74
	s_nop 0
	global_load_lds_dwordx4 v195, s[50:51]
	s_add_u32 m0, s74, 0x2000
	s_nop 0
	global_load_lds_dwordx4 v212, s[50:51]
	s_add_u32 s62, s50, 0x4000
	s_addc_u32 s63, s51, 0
	s_mov_b32 m0, s75
	s_nop 0
	global_load_lds_dwordx4 v195, s[62:63]
	s_add_u32 m0, s75, 0x2000
	s_nop 0
	global_load_lds_dwordx4 v212, s[62:63]
	s_andn2_b64 vcc, exec, s[54:55]
	s_mov_b32 m0, s73
	s_nop 0
	global_load_lds_dwordx4 v195, s[52:53]
	s_add_u32 m0, s73, 0x2000
	s_nop 0
	global_load_lds_dwordx4 v212, s[52:53]
	s_cbranch_vccnz .LBB0_366
	v_mov_b32_e32 v2, 0
	v_mov_b32_e32 v3, v2
	v_mov_b32_e32 v4, v2
	v_mov_b32_e32 v5, v2
	v_mov_b32_e32 v6, v2
	v_mov_b32_e32 v7, v2
	v_mov_b32_e32 v8, v2
	v_mov_b32_e32 v9, v2
	v_mov_b32_e32 v10, v2
	v_mov_b32_e32 v11, v2
	v_mov_b32_e32 v12, v2
	v_mov_b32_e32 v13, v2
	v_mov_b32_e32 v14, v2
	v_mov_b32_e32 v15, v2
	v_mov_b32_e32 v16, v2
	v_mov_b32_e32 v17, v2
	v_mov_b32_e32 v18, v2
	v_mov_b32_e32 v19, v2
	v_mov_b32_e32 v20, v2
	v_mov_b32_e32 v21, v2
	v_mov_b32_e32 v22, v2
	v_mov_b32_e32 v23, v2
	v_mov_b32_e32 v24, v2
	v_mov_b32_e32 v25, v2
	v_mov_b32_e32 v26, v2
	v_mov_b32_e32 v27, v2
	v_mov_b32_e32 v28, v2
	v_mov_b32_e32 v29, v2
	v_mov_b32_e32 v30, v2
	v_mov_b32_e32 v31, v2
	v_mov_b32_e32 v32, v2
	v_mov_b32_e32 v33, v2
	v_mov_b32_e32 v34, v2
	v_mov_b32_e32 v35, v2
	v_mov_b32_e32 v36, v2
	v_mov_b32_e32 v37, v2
	v_mov_b32_e32 v38, v2
	v_mov_b32_e32 v39, v2
	v_mov_b32_e32 v40, v2
	v_mov_b32_e32 v41, v2
	v_mov_b32_e32 v42, v2
	v_mov_b32_e32 v43, v2
	v_mov_b32_e32 v44, v2
	v_mov_b32_e32 v45, v2
	v_mov_b32_e32 v46, v2
	v_mov_b32_e32 v47, v2
	v_mov_b32_e32 v48, v2
	v_mov_b32_e32 v49, v2
	v_mov_b32_e32 v50, v2
	v_mov_b32_e32 v51, v2
	v_mov_b32_e32 v52, v2
	v_mov_b32_e32 v53, v2
	v_mov_b32_e32 v54, v2
	v_mov_b32_e32 v55, v2
	v_mov_b32_e32 v56, v2
	v_mov_b32_e32 v57, v2
	v_mov_b32_e32 v58, v2
	v_mov_b32_e32 v59, v2
	v_mov_b32_e32 v60, v2
	v_mov_b32_e32 v61, v2
	v_mov_b32_e32 v62, v2
	v_mov_b32_e32 v63, v2
	v_mov_b32_e32 v64, v2
	v_mov_b32_e32 v65, v2
.LBB0_366:
	s_waitcnt vmcnt(8)
	s_add_u32 s54, s52, 0x8000
	s_waitcnt lgkmcnt(0)
	s_addc_u32 s55, s53, 0
	s_add_u32 s62, s50, 0x8000
	s_addc_u32 s63, s51, 0
	s_setprio 1
	s_barrier
	v_mfma_f32_16x16x32_bf16 v[62:65], v[146:149], v[186:189], v[62:65]
	v_mfma_f32_16x16x32_bf16 v[62:65], v[150:153], v[190:193], v[62:65]
	s_waitcnt lgkmcnt(5)
	v_mfma_f32_16x16x32_bf16 v[54:57], v[146:149], v[178:181], v[54:57]
	v_mfma_f32_16x16x32_bf16 v[54:57], v[150:153], v[182:185], v[54:57]
	s_waitcnt lgkmcnt(3)
	v_mfma_f32_16x16x32_bf16 v[46:49], v[146:149], v[170:173], v[46:49]
	v_mfma_f32_16x16x32_bf16 v[46:49], v[150:153], v[174:177], v[46:49]
	s_waitcnt lgkmcnt(1)
	v_mfma_f32_16x16x32_bf16 v[38:41], v[146:149], v[162:165], v[38:41]
	v_mfma_f32_16x16x32_bf16 v[38:41], v[150:153], v[166:169], v[38:41]
	v_mfma_f32_16x16x32_bf16 v[58:61], v[154:157], v[186:189], v[58:61]
	v_mfma_f32_16x16x32_bf16 v[58:61], v[158:161], v[190:193], v[58:61]
	v_mfma_f32_16x16x32_bf16 v[50:53], v[154:157], v[178:181], v[50:53]
	v_mfma_f32_16x16x32_bf16 v[50:53], v[158:161], v[182:185], v[50:53]
	v_mfma_f32_16x16x32_bf16 v[42:45], v[154:157], v[170:173], v[42:45]
	v_mfma_f32_16x16x32_bf16 v[42:45], v[158:161], v[174:177], v[42:45]
	s_waitcnt lgkmcnt(0)
	v_mfma_f32_16x16x32_bf16 v[34:37], v[154:157], v[162:165], v[34:37]
	v_mfma_f32_16x16x32_bf16 v[34:37], v[158:161], v[166:169], v[34:37]
	s_setprio 0
	s_setprio 1
	v_mfma_f32_16x16x32_bf16 v[30:33], v[130:133], v[186:189], v[30:33]
	v_mfma_f32_16x16x32_bf16 v[30:33], v[134:137], v[190:193], v[30:33]
	v_mfma_f32_16x16x32_bf16 v[22:25], v[130:133], v[178:181], v[22:25]
	v_mfma_f32_16x16x32_bf16 v[22:25], v[134:137], v[182:185], v[22:25]
	v_mfma_f32_16x16x32_bf16 v[14:17], v[130:133], v[170:173], v[14:17]
	v_mfma_f32_16x16x32_bf16 v[14:17], v[134:137], v[174:177], v[14:17]
	v_mfma_f32_16x16x32_bf16 v[6:9], v[130:133], v[162:165], v[6:9]
	v_mfma_f32_16x16x32_bf16 v[6:9], v[134:137], v[166:169], v[6:9]
	v_mfma_f32_16x16x32_bf16 v[26:29], v[138:141], v[186:189], v[26:29]
	v_mfma_f32_16x16x32_bf16 v[26:29], v[142:145], v[190:193], v[26:29]
	v_mfma_f32_16x16x32_bf16 v[18:21], v[138:141], v[178:181], v[18:21]
	v_mfma_f32_16x16x32_bf16 v[18:21], v[142:145], v[182:185], v[18:21]
	v_mfma_f32_16x16x32_bf16 v[10:13], v[138:141], v[170:173], v[10:13]
	v_mfma_f32_16x16x32_bf16 v[10:13], v[142:145], v[174:177], v[10:13]
	s_setprio 2
	s_barrier
	v_mfma_f32_16x16x32_bf16 v[2:5], v[138:141], v[162:165], v[2:5]
	v_mfma_f32_16x16x32_bf16 v[2:5], v[142:145], v[166:169], v[2:5]
	s_setprio 0
	s_nop 0
	v_add_u32_e32 v142, 0x18000, v218
	v_add_u32_e32 v158, 0x1c000, v218
	ds_read_b128 v[130:133], v142
	ds_read_b128 v[134:137], v142 offset:1024
	ds_read_b128 v[138:141], v142 offset:2048
	ds_read_b128 v[142:145], v142 offset:3072
	ds_read_b128 v[146:149], v158
	ds_read_b128 v[150:153], v158 offset:1024
	ds_read_b128 v[154:157], v158 offset:2048
	ds_read_b128 v[158:161], v158 offset:3072
	ds_read_b128 v[162:165], v219 offset:32768
	ds_read_b128 v[166:169], v219 offset:33792
	ds_read_b128 v[170:173], v219 offset:34816
	ds_read_b128 v[174:177], v219 offset:35840
	ds_read_b128 v[178:181], v219 offset:36864
	ds_read_b128 v[182:185], v219 offset:37888
	ds_read_b128 v[186:189], v219 offset:38912
	ds_read_b128 v[190:193], v219 offset:39936
	s_add_u32 s52, s52, 0x4000
	s_addc_u32 s53, s53, 0
	s_mov_b32 m0, s76
	s_nop 0
	global_load_lds_dwordx4 v195, s[52:53]
	s_add_u32 m0, s76, 0x2000
	s_nop 0
	global_load_lds_dwordx4 v212, s[52:53]
	s_waitcnt vmcnt(8)
	s_waitcnt lgkmcnt(0)
	s_setprio 1
	s_barrier
	v_mfma_f32_16x16x32_bf16 v[126:129], v[130:133], v[162:165], v[126:129]
	v_mfma_f32_16x16x32_bf16 v[126:129], v[134:137], v[166:169], v[126:129]
	s_waitcnt lgkmcnt(5)
	v_mfma_f32_16x16x32_bf16 v[118:121], v[130:133], v[170:173], v[118:121]
	v_mfma_f32_16x16x32_bf16 v[118:121], v[134:137], v[174:177], v[118:121]
	s_waitcnt lgkmcnt(3)
	v_mfma_f32_16x16x32_bf16 v[110:113], v[130:133], v[178:181], v[110:113]
	v_mfma_f32_16x16x32_bf16 v[110:113], v[134:137], v[182:185], v[110:113]
	s_waitcnt lgkmcnt(1)
	v_mfma_f32_16x16x32_bf16 v[102:105], v[130:133], v[186:189], v[102:105]
	v_mfma_f32_16x16x32_bf16 v[102:105], v[134:137], v[190:193], v[102:105]
	v_mfma_f32_16x16x32_bf16 v[122:125], v[138:141], v[162:165], v[122:125]
	v_mfma_f32_16x16x32_bf16 v[122:125], v[142:145], v[166:169], v[122:125]
	v_mfma_f32_16x16x32_bf16 v[114:117], v[138:141], v[170:173], v[114:117]
	v_mfma_f32_16x16x32_bf16 v[114:117], v[142:145], v[174:177], v[114:117]
	v_mfma_f32_16x16x32_bf16 v[106:109], v[138:141], v[178:181], v[106:109]
	v_mfma_f32_16x16x32_bf16 v[106:109], v[142:145], v[182:185], v[106:109]
	s_waitcnt lgkmcnt(0)
	v_mfma_f32_16x16x32_bf16 v[98:101], v[138:141], v[186:189], v[98:101]
	v_mfma_f32_16x16x32_bf16 v[98:101], v[142:145], v[190:193], v[98:101]
	s_setprio 0
	s_setprio 1
	v_mfma_f32_16x16x32_bf16 v[94:97], v[146:149], v[162:165], v[94:97]
	v_mfma_f32_16x16x32_bf16 v[94:97], v[150:153], v[166:169], v[94:97]
	v_mfma_f32_16x16x32_bf16 v[86:89], v[146:149], v[170:173], v[86:89]
	v_mfma_f32_16x16x32_bf16 v[86:89], v[150:153], v[174:177], v[86:89]
	v_mfma_f32_16x16x32_bf16 v[78:81], v[146:149], v[178:181], v[78:81]
	v_mfma_f32_16x16x32_bf16 v[78:81], v[150:153], v[182:185], v[78:81]
	v_mfma_f32_16x16x32_bf16 v[70:73], v[146:149], v[186:189], v[70:73]
	v_mfma_f32_16x16x32_bf16 v[70:73], v[150:153], v[190:193], v[70:73]
	v_mfma_f32_16x16x32_bf16 v[90:93], v[154:157], v[162:165], v[90:93]
	v_mfma_f32_16x16x32_bf16 v[90:93], v[158:161], v[166:169], v[90:93]
	v_mfma_f32_16x16x32_bf16 v[82:85], v[154:157], v[170:173], v[82:85]
	v_mfma_f32_16x16x32_bf16 v[82:85], v[158:161], v[174:177], v[82:85]
	v_mfma_f32_16x16x32_bf16 v[74:77], v[154:157], v[178:181], v[74:77]
	v_mfma_f32_16x16x32_bf16 v[74:77], v[158:161], v[182:185], v[74:77]
	s_setprio 2
	s_barrier
	v_mfma_f32_16x16x32_bf16 v[66:69], v[154:157], v[186:189], v[66:69]
	v_mfma_f32_16x16x32_bf16 v[66:69], v[158:161], v[190:193], v[66:69]
	s_setprio 0
	s_nop 0
	ds_read_b128 v[162:165], v219 offset:49152
	ds_read_b128 v[166:169], v219 offset:50176
	ds_read_b128 v[170:173], v219 offset:51200
	ds_read_b128 v[174:177], v219 offset:52224
	ds_read_b128 v[178:181], v219 offset:53248
	ds_read_b128 v[182:185], v219 offset:54272
	ds_read_b128 v[186:189], v219 offset:55296
	ds_read_b128 v[190:193], v219 offset:56320
	s_mov_b32 m0, s80
	s_nop 0
	global_load_lds_dwordx4 v195, s[62:63]
	s_add_u32 m0, s80, 0x2000
	s_nop 0
	global_load_lds_dwordx4 v212, s[62:63]
	s_add_u32 s50, s50, 0xc000
	s_addc_u32 s51, s51, 0
	s_mov_b32 m0, s82
	s_nop 0
	global_load_lds_dwordx4 v195, s[50:51]
	s_add_u32 m0, s82, 0x2000
	s_nop 0
	global_load_lds_dwordx4 v212, s[50:51]
	s_nop 0
	s_mov_b32 m0, s81
	s_nop 0
	global_load_lds_dwordx4 v195, s[54:55]
	s_add_u32 m0, s81, 0x2000
	s_nop 0
	global_load_lds_dwordx4 v212, s[54:55]
	s_waitcnt vmcnt(8)
	s_waitcnt lgkmcnt(0)
	s_setprio 1
	s_barrier
	v_mfma_f32_16x16x32_bf16 v[62:65], v[130:133], v[162:165], v[62:65]
	v_mfma_f32_16x16x32_bf16 v[62:65], v[134:137], v[166:169], v[62:65]
	s_waitcnt lgkmcnt(5)
	v_mfma_f32_16x16x32_bf16 v[54:57], v[130:133], v[170:173], v[54:57]
	v_mfma_f32_16x16x32_bf16 v[54:57], v[134:137], v[174:177], v[54:57]
	s_waitcnt lgkmcnt(3)
	v_mfma_f32_16x16x32_bf16 v[46:49], v[130:133], v[178:181], v[46:49]
	v_mfma_f32_16x16x32_bf16 v[46:49], v[134:137], v[182:185], v[46:49]
	s_waitcnt lgkmcnt(1)
	v_mfma_f32_16x16x32_bf16 v[38:41], v[130:133], v[186:189], v[38:41]
	v_mfma_f32_16x16x32_bf16 v[38:41], v[134:137], v[190:193], v[38:41]
	v_mfma_f32_16x16x32_bf16 v[58:61], v[138:141], v[162:165], v[58:61]
	v_mfma_f32_16x16x32_bf16 v[58:61], v[142:145], v[166:169], v[58:61]
	v_mfma_f32_16x16x32_bf16 v[50:53], v[138:141], v[170:173], v[50:53]
	v_mfma_f32_16x16x32_bf16 v[50:53], v[142:145], v[174:177], v[50:53]
	v_mfma_f32_16x16x32_bf16 v[42:45], v[138:141], v[178:181], v[42:45]
	v_mfma_f32_16x16x32_bf16 v[42:45], v[142:145], v[182:185], v[42:45]
	s_waitcnt lgkmcnt(0)
	v_mfma_f32_16x16x32_bf16 v[34:37], v[138:141], v[186:189], v[34:37]
	v_mfma_f32_16x16x32_bf16 v[34:37], v[142:145], v[190:193], v[34:37]
	s_setprio 0
	s_setprio 1
	v_mfma_f32_16x16x32_bf16 v[30:33], v[146:149], v[162:165], v[30:33]
	v_mfma_f32_16x16x32_bf16 v[30:33], v[150:153], v[166:169], v[30:33]
	v_mfma_f32_16x16x32_bf16 v[22:25], v[146:149], v[170:173], v[22:25]
	v_mfma_f32_16x16x32_bf16 v[22:25], v[150:153], v[174:177], v[22:25]
	v_mfma_f32_16x16x32_bf16 v[14:17], v[146:149], v[178:181], v[14:17]
	v_mfma_f32_16x16x32_bf16 v[14:17], v[150:153], v[182:185], v[14:17]
	v_mfma_f32_16x16x32_bf16 v[6:9], v[146:149], v[186:189], v[6:9]
	v_mfma_f32_16x16x32_bf16 v[6:9], v[150:153], v[190:193], v[6:9]
	v_mfma_f32_16x16x32_bf16 v[26:29], v[154:157], v[162:165], v[26:29]
	v_mfma_f32_16x16x32_bf16 v[26:29], v[158:161], v[166:169], v[26:29]
	v_mfma_f32_16x16x32_bf16 v[18:21], v[154:157], v[170:173], v[18:21]
	v_mfma_f32_16x16x32_bf16 v[18:21], v[158:161], v[174:177], v[18:21]
	v_mfma_f32_16x16x32_bf16 v[10:13], v[154:157], v[178:181], v[10:13]
	v_mfma_f32_16x16x32_bf16 v[10:13], v[158:161], v[182:185], v[10:13]
	s_setprio 2
	s_barrier
	v_mfma_f32_16x16x32_bf16 v[2:5], v[154:157], v[186:189], v[2:5]
	v_mfma_f32_16x16x32_bf16 v[2:5], v[158:161], v[190:193], v[2:5]
	s_setprio 0
	s_nop 0
	s_cmp_gt_u32 s93, 41
	s_cbranch_scc1 .LBB0_368
	v_mov_b32_e32 v130, v198
	s_mov_b32 s93, s26
	s_branch .LBB0_343

.LBB0_519:
	ds_read_b128 v[130:133], v141
	ds_read_b128 v[134:137], v141 offset:1024
	ds_read_b128 v[146:149], v141 offset:2048
	ds_read_b128 v[150:153], v141 offset:3072
	ds_read_b128 v[154:157], v142
	ds_read_b128 v[158:161], v142 offset:1024
	ds_read_b128 v[162:165], v142 offset:2048
	ds_read_b128 v[166:169], v142 offset:3072
	s_add_u32 s24, s26, 0x10000
	s_addc_u32 s25, s27, 0
	s_cmp_eq_u32 s77, 12
	s_cselect_b32 s48, s17, s24
	s_cselect_b32 s49, s1, s25
	s_cselect_b32 s30, s23, s75
	s_cselect_b32 s31, s15, s76
	s_add_u32 s28, s48, 0x8000
	s_addc_u32 s29, s49, 0
	ds_read_b128 v[170:173], v143
	ds_read_b128 v[174:177], v143 offset:1024
	ds_read_b128 v[178:181], v143 offset:2048
	ds_read_b128 v[182:185], v143 offset:3072
	ds_read_b128 v[186:189], v143 offset:4096
	ds_read_b128 v[190:193], v143 offset:5120
	ds_read_b128 v[198:201], v143 offset:6144
	ds_read_b128 v[202:205], v143 offset:7168
	s_add_u32 s38, s30, 0x8000
	s_addc_u32 s39, s31, 0
	s_add_u32 s26, s26, 0xc000
	s_addc_u32 s27, s27, 0
	s_mov_b32 m0, s72
	s_nop 0
	global_load_lds_dwordx4 v195, s[26:27]
	s_add_u32 m0, s72, 0x2000
	s_nop 0
	global_load_lds_dwordx4 v212, s[26:27]
	s_waitcnt vmcnt(8)
	s_waitcnt lgkmcnt(0)
	s_setprio 1
	s_barrier
	v_mfma_f32_16x16x32_bf16 v[122:125], v[130:133], v[170:173], v[122:125]
	v_mfma_f32_16x16x32_bf16 v[122:125], v[134:137], v[174:177], v[122:125]
	s_waitcnt lgkmcnt(5)
	v_mfma_f32_16x16x32_bf16 v[110:113], v[130:133], v[178:181], v[110:113]
	v_mfma_f32_16x16x32_bf16 v[110:113], v[134:137], v[182:185], v[110:113]
	s_waitcnt lgkmcnt(3)
	v_mfma_f32_16x16x32_bf16 v[94:97], v[130:133], v[186:189], v[94:97]
	v_mfma_f32_16x16x32_bf16 v[94:97], v[134:137], v[190:193], v[94:97]
	s_waitcnt lgkmcnt(1)
	v_mfma_f32_16x16x32_bf16 v[78:81], v[130:133], v[198:201], v[78:81]
	v_mfma_f32_16x16x32_bf16 v[78:81], v[134:137], v[202:205], v[78:81]
	v_mfma_f32_16x16x32_bf16 v[126:129], v[146:149], v[170:173], v[126:129]
	v_mfma_f32_16x16x32_bf16 v[126:129], v[150:153], v[174:177], v[126:129]
	v_mfma_f32_16x16x32_bf16 v[106:109], v[146:149], v[178:181], v[106:109]
	v_mfma_f32_16x16x32_bf16 v[106:109], v[150:153], v[182:185], v[106:109]
	v_mfma_f32_16x16x32_bf16 v[90:93], v[146:149], v[186:189], v[90:93]
	v_mfma_f32_16x16x32_bf16 v[90:93], v[150:153], v[190:193], v[90:93]
	s_waitcnt lgkmcnt(0)
	v_mfma_f32_16x16x32_bf16 v[74:77], v[146:149], v[198:201], v[74:77]
	v_mfma_f32_16x16x32_bf16 v[74:77], v[150:153], v[202:205], v[74:77]
	s_setprio 0
	s_setprio 1
	v_mfma_f32_16x16x32_bf16 v[114:117], v[154:157], v[170:173], v[114:117]
	v_mfma_f32_16x16x32_bf16 v[114:117], v[158:161], v[174:177], v[114:117]
	v_mfma_f32_16x16x32_bf16 v[98:101], v[154:157], v[178:181], v[98:101]
	v_mfma_f32_16x16x32_bf16 v[98:101], v[158:161], v[182:185], v[98:101]
	v_mfma_f32_16x16x32_bf16 v[82:85], v[154:157], v[186:189], v[82:85]
	v_mfma_f32_16x16x32_bf16 v[82:85], v[158:161], v[190:193], v[82:85]
	v_mfma_f32_16x16x32_bf16 v[66:69], v[154:157], v[198:201], v[66:69]
	v_mfma_f32_16x16x32_bf16 v[66:69], v[158:161], v[202:205], v[66:69]
	v_mfma_f32_16x16x32_bf16 v[118:121], v[162:165], v[170:173], v[118:121]
	v_mfma_f32_16x16x32_bf16 v[118:121], v[166:169], v[174:177], v[118:121]
	v_mfma_f32_16x16x32_bf16 v[102:105], v[162:165], v[178:181], v[102:105]
	v_mfma_f32_16x16x32_bf16 v[102:105], v[166:169], v[182:185], v[102:105]
	v_mfma_f32_16x16x32_bf16 v[86:89], v[162:165], v[186:189], v[86:89]
	v_mfma_f32_16x16x32_bf16 v[86:89], v[166:169], v[190:193], v[86:89]
	s_setprio 2
	s_barrier
	v_mfma_f32_16x16x32_bf16 v[70:73], v[162:165], v[198:201], v[70:73]
	v_mfma_f32_16x16x32_bf16 v[70:73], v[166:169], v[202:205], v[70:73]
	s_setprio 0
	s_nop 0
	ds_read_b128 v[170:173], v143 offset:16384
	ds_read_b128 v[174:177], v143 offset:17408
	ds_read_b128 v[178:181], v143 offset:18432
	ds_read_b128 v[182:185], v143 offset:19456
	ds_read_b128 v[186:189], v143 offset:20480
	ds_read_b128 v[190:193], v143 offset:21504
	ds_read_b128 v[198:201], v143 offset:22528
	ds_read_b128 v[202:205], v143 offset:23552
	s_mov_b32 m0, s55
	s_nop 0
	global_load_lds_dwordx4 v195, s[30:31]
	s_add_u32 m0, s55, 0x2000
	s_nop 0
	global_load_lds_dwordx4 v212, s[30:31]
	s_add_u32 s26, s30, 0x4000
	s_addc_u32 s27, s31, 0
	s_mov_b32 m0, s62
	s_nop 0
	global_load_lds_dwordx4 v195, s[26:27]
	s_add_u32 m0, s62, 0x2000
	s_nop 0
	global_load_lds_dwordx4 v212, s[26:27]
	s_nop 0
	s_mov_b32 m0, s54
	s_nop 0
	global_load_lds_dwordx4 v195, s[48:49]
	s_add_u32 m0, s54, 0x2000
	s_nop 0
	global_load_lds_dwordx4 v212, s[48:49]
	s_waitcnt vmcnt(8)
	s_waitcnt lgkmcnt(0)
	s_setprio 1
	s_barrier
	v_mfma_f32_16x16x32_bf16 v[62:65], v[130:133], v[170:173], v[62:65]
	v_mfma_f32_16x16x32_bf16 v[62:65], v[134:137], v[174:177], v[62:65]
	s_waitcnt lgkmcnt(5)
	v_mfma_f32_16x16x32_bf16 v[46:49], v[130:133], v[178:181], v[46:49]
	v_mfma_f32_16x16x32_bf16 v[46:49], v[134:137], v[182:185], v[46:49]
	s_waitcnt lgkmcnt(3)
	v_mfma_f32_16x16x32_bf16 v[30:33], v[130:133], v[186:189], v[30:33]
	v_mfma_f32_16x16x32_bf16 v[30:33], v[134:137], v[190:193], v[30:33]
	s_waitcnt lgkmcnt(1)
	v_mfma_f32_16x16x32_bf16 v[14:17], v[130:133], v[198:201], v[14:17]
	v_mfma_f32_16x16x32_bf16 v[14:17], v[134:137], v[202:205], v[14:17]
	v_mfma_f32_16x16x32_bf16 v[58:61], v[146:149], v[170:173], v[58:61]
	v_mfma_f32_16x16x32_bf16 v[58:61], v[150:153], v[174:177], v[58:61]
	v_mfma_f32_16x16x32_bf16 v[42:45], v[146:149], v[178:181], v[42:45]
	v_mfma_f32_16x16x32_bf16 v[42:45], v[150:153], v[182:185], v[42:45]
	v_mfma_f32_16x16x32_bf16 v[26:29], v[146:149], v[186:189], v[26:29]
	v_mfma_f32_16x16x32_bf16 v[26:29], v[150:153], v[190:193], v[26:29]
	s_waitcnt lgkmcnt(0)
	v_mfma_f32_16x16x32_bf16 v[10:13], v[146:149], v[198:201], v[10:13]
	v_mfma_f32_16x16x32_bf16 v[10:13], v[150:153], v[202:205], v[10:13]
	s_setprio 0
	s_setprio 1
	v_mfma_f32_16x16x32_bf16 v[50:53], v[154:157], v[170:173], v[50:53]
	v_mfma_f32_16x16x32_bf16 v[50:53], v[158:161], v[174:177], v[50:53]
	v_mfma_f32_16x16x32_bf16 v[34:37], v[154:157], v[178:181], v[34:37]
	v_mfma_f32_16x16x32_bf16 v[34:37], v[158:161], v[182:185], v[34:37]
	v_mfma_f32_16x16x32_bf16 v[18:21], v[154:157], v[186:189], v[18:21]
	v_mfma_f32_16x16x32_bf16 v[18:21], v[158:161], v[190:193], v[18:21]
	v_mfma_f32_16x16x32_bf16 v[2:5], v[154:157], v[198:201], v[2:5]
	v_mfma_f32_16x16x32_bf16 v[2:5], v[158:161], v[202:205], v[2:5]
	v_mfma_f32_16x16x32_bf16 v[54:57], v[162:165], v[170:173], v[54:57]
	v_mfma_f32_16x16x32_bf16 v[54:57], v[166:169], v[174:177], v[54:57]
	v_mfma_f32_16x16x32_bf16 v[38:41], v[162:165], v[178:181], v[38:41]
	v_mfma_f32_16x16x32_bf16 v[38:41], v[166:169], v[182:185], v[38:41]
	v_mfma_f32_16x16x32_bf16 v[22:25], v[162:165], v[186:189], v[22:25]
	v_mfma_f32_16x16x32_bf16 v[22:25], v[166:169], v[190:193], v[22:25]
	s_setprio 2
	s_barrier
	v_mfma_f32_16x16x32_bf16 v[6:9], v[162:165], v[198:201], v[6:9]
	v_mfma_f32_16x16x32_bf16 v[6:9], v[166:169], v[202:205], v[6:9]
	s_setprio 0
	s_nop 0
	ds_read_b128 v[130:133], v144
	ds_read_b128 v[134:137], v144 offset:1024
	ds_read_b128 v[146:149], v144 offset:2048
	ds_read_b128 v[150:153], v144 offset:3072
	ds_read_b128 v[154:157], v145
	ds_read_b128 v[158:161], v145 offset:1024
	ds_read_b128 v[162:165], v145 offset:2048
	ds_read_b128 v[166:169], v145 offset:3072
	ds_read_b128 v[170:173], v143 offset:32768
	ds_read_b128 v[174:177], v143 offset:33792
	ds_read_b128 v[178:181], v143 offset:34816
	ds_read_b128 v[182:185], v143 offset:35840
	ds_read_b128 v[186:189], v143 offset:36864
	ds_read_b128 v[190:193], v143 offset:37888
	ds_read_b128 v[198:201], v143 offset:38912
	ds_read_b128 v[202:205], v143 offset:39936
	s_add_u32 s26, s48, 0x4000
	s_addc_u32 s27, s49, 0
	s_mov_b32 m0, s63
	s_nop 0
	global_load_lds_dwordx4 v195, s[26:27]
	s_add_u32 m0, s63, 0x2000
	s_nop 0
	global_load_lds_dwordx4 v212, s[26:27]
	s_waitcnt vmcnt(8)
	s_waitcnt lgkmcnt(0)
	s_setprio 1
	s_barrier
	v_mfma_f32_16x16x32_bf16 v[122:125], v[130:133], v[170:173], v[122:125]
	v_mfma_f32_16x16x32_bf16 v[122:125], v[134:137], v[174:177], v[122:125]
	s_waitcnt lgkmcnt(5)
	v_mfma_f32_16x16x32_bf16 v[110:113], v[130:133], v[178:181], v[110:113]
	v_mfma_f32_16x16x32_bf16 v[110:113], v[134:137], v[182:185], v[110:113]
	s_waitcnt lgkmcnt(3)
	v_mfma_f32_16x16x32_bf16 v[94:97], v[130:133], v[186:189], v[94:97]
	v_mfma_f32_16x16x32_bf16 v[94:97], v[134:137], v[190:193], v[94:97]
	s_waitcnt lgkmcnt(1)
	v_mfma_f32_16x16x32_bf16 v[78:81], v[130:133], v[198:201], v[78:81]
	v_mfma_f32_16x16x32_bf16 v[78:81], v[134:137], v[202:205], v[78:81]
	v_mfma_f32_16x16x32_bf16 v[126:129], v[146:149], v[170:173], v[126:129]
	v_mfma_f32_16x16x32_bf16 v[126:129], v[150:153], v[174:177], v[126:129]
	v_mfma_f32_16x16x32_bf16 v[106:109], v[146:149], v[178:181], v[106:109]
	v_mfma_f32_16x16x32_bf16 v[106:109], v[150:153], v[182:185], v[106:109]
	v_mfma_f32_16x16x32_bf16 v[90:93], v[146:149], v[186:189], v[90:93]
	v_mfma_f32_16x16x32_bf16 v[90:93], v[150:153], v[190:193], v[90:93]
	s_waitcnt lgkmcnt(0)
	v_mfma_f32_16x16x32_bf16 v[74:77], v[146:149], v[198:201], v[74:77]
	v_mfma_f32_16x16x32_bf16 v[74:77], v[150:153], v[202:205], v[74:77]
	s_setprio 0
	s_setprio 1
	v_mfma_f32_16x16x32_bf16 v[114:117], v[154:157], v[170:173], v[114:117]
	v_mfma_f32_16x16x32_bf16 v[114:117], v[158:161], v[174:177], v[114:117]
	v_mfma_f32_16x16x32_bf16 v[98:101], v[154:157], v[178:181], v[98:101]
	v_mfma_f32_16x16x32_bf16 v[98:101], v[158:161], v[182:185], v[98:101]
	v_mfma_f32_16x16x32_bf16 v[82:85], v[154:157], v[186:189], v[82:85]
	v_mfma_f32_16x16x32_bf16 v[82:85], v[158:161], v[190:193], v[82:85]
	v_mfma_f32_16x16x32_bf16 v[66:69], v[154:157], v[198:201], v[66:69]
	v_mfma_f32_16x16x32_bf16 v[66:69], v[158:161], v[202:205], v[66:69]
	v_mfma_f32_16x16x32_bf16 v[118:121], v[162:165], v[170:173], v[118:121]
	v_mfma_f32_16x16x32_bf16 v[118:121], v[166:169], v[174:177], v[118:121]
	v_mfma_f32_16x16x32_bf16 v[102:105], v[162:165], v[178:181], v[102:105]
	v_mfma_f32_16x16x32_bf16 v[102:105], v[166:169], v[182:185], v[102:105]
	v_mfma_f32_16x16x32_bf16 v[86:89], v[162:165], v[186:189], v[86:89]
	v_mfma_f32_16x16x32_bf16 v[86:89], v[166:169], v[190:193], v[86:89]
	s_setprio 2
	s_barrier
	v_mfma_f32_16x16x32_bf16 v[70:73], v[162:165], v[198:201], v[70:73]
	v_mfma_f32_16x16x32_bf16 v[70:73], v[166:169], v[202:205], v[70:73]
	s_setprio 0
	s_nop 0
	ds_read_b128 v[170:173], v143 offset:49152
	ds_read_b128 v[174:177], v143 offset:50176
	ds_read_b128 v[178:181], v143 offset:51200
	ds_read_b128 v[182:185], v143 offset:52224
	ds_read_b128 v[186:189], v143 offset:53248
	ds_read_b128 v[190:193], v143 offset:54272
	ds_read_b128 v[198:201], v143 offset:55296
	ds_read_b128 v[202:205], v143 offset:56320
	s_mov_b32 m0, s69
	s_nop 0
	global_load_lds_dwordx4 v195, s[38:39]
	s_add_u32 m0, s69, 0x2000
	s_nop 0
	global_load_lds_dwordx4 v212, s[38:39]
	s_add_u32 s26, s30, 0xc000
	s_addc_u32 s27, s31, 0
	s_mov_b32 m0, s71
	s_nop 0
	global_load_lds_dwordx4 v195, s[26:27]
	s_add_u32 m0, s71, 0x2000
	s_nop 0
	global_load_lds_dwordx4 v212, s[26:27]
	s_nop 0
	s_mov_b32 m0, s70
	s_nop 0
	global_load_lds_dwordx4 v195, s[28:29]
	s_add_u32 m0, s70, 0x2000
	s_nop 0
	global_load_lds_dwordx4 v212, s[28:29]
	s_waitcnt vmcnt(8)
	s_waitcnt lgkmcnt(0)
	s_setprio 1
	s_barrier
	v_mfma_f32_16x16x32_bf16 v[62:65], v[130:133], v[170:173], v[62:65]
	v_mfma_f32_16x16x32_bf16 v[62:65], v[134:137], v[174:177], v[62:65]
	s_waitcnt lgkmcnt(5)
	v_mfma_f32_16x16x32_bf16 v[46:49], v[130:133], v[178:181], v[46:49]
	v_mfma_f32_16x16x32_bf16 v[46:49], v[134:137], v[182:185], v[46:49]
	s_waitcnt lgkmcnt(3)
	v_mfma_f32_16x16x32_bf16 v[30:33], v[130:133], v[186:189], v[30:33]
	v_mfma_f32_16x16x32_bf16 v[30:33], v[134:137], v[190:193], v[30:33]
	s_waitcnt lgkmcnt(1)
	v_mfma_f32_16x16x32_bf16 v[14:17], v[130:133], v[198:201], v[14:17]
	v_mfma_f32_16x16x32_bf16 v[14:17], v[134:137], v[202:205], v[14:17]
	v_mfma_f32_16x16x32_bf16 v[58:61], v[146:149], v[170:173], v[58:61]
	v_mfma_f32_16x16x32_bf16 v[58:61], v[150:153], v[174:177], v[58:61]
	v_mfma_f32_16x16x32_bf16 v[42:45], v[146:149], v[178:181], v[42:45]
	v_mfma_f32_16x16x32_bf16 v[42:45], v[150:153], v[182:185], v[42:45]
	v_mfma_f32_16x16x32_bf16 v[26:29], v[146:149], v[186:189], v[26:29]
	v_mfma_f32_16x16x32_bf16 v[26:29], v[150:153], v[190:193], v[26:29]
	s_waitcnt lgkmcnt(0)
	v_mfma_f32_16x16x32_bf16 v[10:13], v[146:149], v[198:201], v[10:13]
	v_mfma_f32_16x16x32_bf16 v[10:13], v[150:153], v[202:205], v[10:13]
	s_setprio 0
	s_setprio 1
	v_mfma_f32_16x16x32_bf16 v[50:53], v[154:157], v[170:173], v[50:53]
	v_mfma_f32_16x16x32_bf16 v[50:53], v[158:161], v[174:177], v[50:53]
	v_mfma_f32_16x16x32_bf16 v[34:37], v[154:157], v[178:181], v[34:37]
	v_mfma_f32_16x16x32_bf16 v[34:37], v[158:161], v[182:185], v[34:37]
	v_mfma_f32_16x16x32_bf16 v[18:21], v[154:157], v[186:189], v[18:21]
	v_mfma_f32_16x16x32_bf16 v[18:21], v[158:161], v[190:193], v[18:21]
	v_mfma_f32_16x16x32_bf16 v[2:5], v[154:157], v[198:201], v[2:5]
	v_mfma_f32_16x16x32_bf16 v[2:5], v[158:161], v[202:205], v[2:5]
	v_mfma_f32_16x16x32_bf16 v[54:57], v[162:165], v[170:173], v[54:57]
	v_mfma_f32_16x16x32_bf16 v[54:57], v[166:169], v[174:177], v[54:57]
	v_mfma_f32_16x16x32_bf16 v[38:41], v[162:165], v[178:181], v[38:41]
	v_mfma_f32_16x16x32_bf16 v[38:41], v[166:169], v[182:185], v[38:41]
	v_mfma_f32_16x16x32_bf16 v[22:25], v[162:165], v[186:189], v[22:25]
	v_mfma_f32_16x16x32_bf16 v[22:25], v[166:169], v[190:193], v[22:25]
	s_setprio 2
	s_barrier
	v_mfma_f32_16x16x32_bf16 v[6:9], v[162:165], v[198:201], v[6:9]
	v_mfma_f32_16x16x32_bf16 v[6:9], v[166:169], v[202:205], v[6:9]
	s_setprio 0
	s_nop 0
	s_add_i32 s77, s77, 2
	s_add_u32 s75, s75, 0x10000
	s_addc_u32 s76, s76, 0
	s_cmp_gt_u32 s77, 13
	s_mov_b64 s[26:27], s[24:25]
	s_cbranch_scc0 .LBB0_519
	s_and_b64 vcc, exec, s[10:11]
	s_cbranch_vccz .LBB0_522
	s_barrier
	s_setprio 1

.LBB0_635:
	s_add_u32 s28, s24, 0x10000
	s_addc_u32 s29, s25, 0
	s_and_b64 s[24:25], s[22:23], exec
	s_cselect_b32 s25, s29, s15
	s_cselect_b32 s24, s28, s33
	s_add_u32 s3, s52, s3
	s_addc_u32 s28, s53, 0
	s_add_u32 s3, s3, 0x10000
	s_waitcnt vmcnt(8)
	s_addc_u32 s28, s28, 0
	s_waitcnt lgkmcnt(0)
	s_and_b64 s[22:23], s[22:23], exec
	s_cselect_b32 s23, s28, s13
	s_cselect_b32 s22, s3, s70
	s_setprio 1
	s_barrier
	v_mfma_f32_16x16x32_bf16 v[126:129], v[146:149], v[186:189], v[126:129]
	v_mfma_f32_16x16x32_bf16 v[126:129], v[150:153], v[190:193], v[126:129]
	s_waitcnt lgkmcnt(5)
	v_mfma_f32_16x16x32_bf16 v[118:121], v[146:149], v[178:181], v[118:121]
	v_mfma_f32_16x16x32_bf16 v[118:121], v[150:153], v[182:185], v[118:121]
	s_waitcnt lgkmcnt(3)
	v_mfma_f32_16x16x32_bf16 v[110:113], v[146:149], v[170:173], v[110:113]
	v_mfma_f32_16x16x32_bf16 v[110:113], v[150:153], v[174:177], v[110:113]
	s_waitcnt lgkmcnt(1)
	v_mfma_f32_16x16x32_bf16 v[102:105], v[146:149], v[162:165], v[102:105]
	v_mfma_f32_16x16x32_bf16 v[102:105], v[150:153], v[166:169], v[102:105]
	v_mfma_f32_16x16x32_bf16 v[122:125], v[154:157], v[186:189], v[122:125]
	v_mfma_f32_16x16x32_bf16 v[122:125], v[158:161], v[190:193], v[122:125]
	v_mfma_f32_16x16x32_bf16 v[114:117], v[154:157], v[178:181], v[114:117]
	v_mfma_f32_16x16x32_bf16 v[114:117], v[158:161], v[182:185], v[114:117]
	v_mfma_f32_16x16x32_bf16 v[106:109], v[154:157], v[170:173], v[106:109]
	v_mfma_f32_16x16x32_bf16 v[106:109], v[158:161], v[174:177], v[106:109]
	s_waitcnt lgkmcnt(0)
	v_mfma_f32_16x16x32_bf16 v[98:101], v[154:157], v[162:165], v[98:101]
	v_mfma_f32_16x16x32_bf16 v[98:101], v[158:161], v[166:169], v[98:101]
	s_setprio 0
	s_setprio 1
	v_mfma_f32_16x16x32_bf16 v[94:97], v[130:133], v[186:189], v[94:97]
	v_mfma_f32_16x16x32_bf16 v[94:97], v[134:137], v[190:193], v[94:97]
	v_mfma_f32_16x16x32_bf16 v[86:89], v[130:133], v[178:181], v[86:89]
	v_mfma_f32_16x16x32_bf16 v[86:89], v[134:137], v[182:185], v[86:89]
	v_mfma_f32_16x16x32_bf16 v[78:81], v[130:133], v[170:173], v[78:81]
	v_mfma_f32_16x16x32_bf16 v[78:81], v[134:137], v[174:177], v[78:81]
	v_mfma_f32_16x16x32_bf16 v[70:73], v[130:133], v[162:165], v[70:73]
	v_mfma_f32_16x16x32_bf16 v[70:73], v[134:137], v[166:169], v[70:73]
	v_mfma_f32_16x16x32_bf16 v[90:93], v[138:141], v[186:189], v[90:93]
	v_mfma_f32_16x16x32_bf16 v[90:93], v[142:145], v[190:193], v[90:93]
	v_mfma_f32_16x16x32_bf16 v[82:85], v[138:141], v[178:181], v[82:85]
	v_mfma_f32_16x16x32_bf16 v[82:85], v[142:145], v[182:185], v[82:85]
	v_mfma_f32_16x16x32_bf16 v[74:77], v[138:141], v[170:173], v[74:77]
	v_mfma_f32_16x16x32_bf16 v[74:77], v[142:145], v[174:177], v[74:77]
	s_setprio 2
	s_barrier
	v_mfma_f32_16x16x32_bf16 v[66:69], v[138:141], v[162:165], v[66:69]
	v_mfma_f32_16x16x32_bf16 v[66:69], v[142:145], v[166:169], v[66:69]
	s_setprio 0
	s_nop 0
	ds_read_b128 v[186:189], v219 offset:16384
	ds_read_b128 v[190:193], v219 offset:17408
	ds_read_b128 v[178:181], v219 offset:18432
	ds_read_b128 v[182:185], v219 offset:19456
	ds_read_b128 v[170:173], v219 offset:20480
	ds_read_b128 v[174:177], v219 offset:21504
	ds_read_b128 v[162:165], v219 offset:22528
	ds_read_b128 v[166:169], v219 offset:23552
	s_mov_b32 m0, s89
	s_nop 0
	global_load_lds_dwordx4 v195, s[22:23]
	s_add_u32 m0, s89, 0x2000
	s_nop 0
	global_load_lds_dwordx4 v213, s[22:23]
	s_add_u32 s28, s22, 0x4000
	s_addc_u32 s29, s23, 0
	s_mov_b32 m0, s54
	s_nop 0
	global_load_lds_dwordx4 v195, s[28:29]
	s_add_u32 m0, s54, 0x2000
	s_nop 0
	global_load_lds_dwordx4 v213, s[28:29]
	s_andn2_b64 vcc, exec, s[26:27]
	s_mov_b32 m0, s39
	s_nop 0
	global_load_lds_dwordx4 v195, s[24:25]
	s_add_u32 m0, s39, 0x2000
	s_nop 0
	global_load_lds_dwordx4 v213, s[24:25]
	s_cbranch_vccnz .LBB0_637
	v_mov_b32_e32 v2, 0
	v_mov_b32_e32 v3, v2
	v_mov_b32_e32 v4, v2
	v_mov_b32_e32 v5, v2
	v_mov_b32_e32 v6, v2
	v_mov_b32_e32 v7, v2
	v_mov_b32_e32 v8, v2
	v_mov_b32_e32 v9, v2
	v_mov_b32_e32 v10, v2
	v_mov_b32_e32 v11, v2
	v_mov_b32_e32 v12, v2
	v_mov_b32_e32 v13, v2
	v_mov_b32_e32 v14, v2
	v_mov_b32_e32 v15, v2
	v_mov_b32_e32 v16, v2
	v_mov_b32_e32 v17, v2
	v_mov_b32_e32 v18, v2
	v_mov_b32_e32 v19, v2
	v_mov_b32_e32 v20, v2
	v_mov_b32_e32 v21, v2
	v_mov_b32_e32 v22, v2
	v_mov_b32_e32 v23, v2
	v_mov_b32_e32 v24, v2
	v_mov_b32_e32 v25, v2
	v_mov_b32_e32 v26, v2
	v_mov_b32_e32 v27, v2
	v_mov_b32_e32 v28, v2
	v_mov_b32_e32 v29, v2
	v_mov_b32_e32 v30, v2
	v_mov_b32_e32 v31, v2
	v_mov_b32_e32 v32, v2
	v_mov_b32_e32 v33, v2
	v_mov_b32_e32 v34, v2
	v_mov_b32_e32 v35, v2
	v_mov_b32_e32 v36, v2
	v_mov_b32_e32 v37, v2
	v_mov_b32_e32 v38, v2
	v_mov_b32_e32 v39, v2
	v_mov_b32_e32 v40, v2
	v_mov_b32_e32 v41, v2
	v_mov_b32_e32 v42, v2
	v_mov_b32_e32 v43, v2
	v_mov_b32_e32 v44, v2
	v_mov_b32_e32 v45, v2
	v_mov_b32_e32 v46, v2
	v_mov_b32_e32 v47, v2
	v_mov_b32_e32 v48, v2
	v_mov_b32_e32 v49, v2
	v_mov_b32_e32 v50, v2
	v_mov_b32_e32 v51, v2
	v_mov_b32_e32 v52, v2
	v_mov_b32_e32 v53, v2
	v_mov_b32_e32 v54, v2
	v_mov_b32_e32 v55, v2
	v_mov_b32_e32 v56, v2
	v_mov_b32_e32 v57, v2
	v_mov_b32_e32 v58, v2
	v_mov_b32_e32 v59, v2
	v_mov_b32_e32 v60, v2
	v_mov_b32_e32 v61, v2
	v_mov_b32_e32 v62, v2
	v_mov_b32_e32 v63, v2
	v_mov_b32_e32 v64, v2
	v_mov_b32_e32 v65, v2
.LBB0_637:
	s_waitcnt vmcnt(8)
	s_add_u32 s26, s24, 0x8000
	s_waitcnt lgkmcnt(0)
	s_addc_u32 s27, s25, 0
	s_add_u32 s28, s22, 0x8000
	s_addc_u32 s29, s23, 0
	s_setprio 1
	s_barrier
	v_mfma_f32_16x16x32_bf16 v[62:65], v[146:149], v[186:189], v[62:65]
	v_mfma_f32_16x16x32_bf16 v[62:65], v[150:153], v[190:193], v[62:65]
	s_waitcnt lgkmcnt(5)
	v_mfma_f32_16x16x32_bf16 v[54:57], v[146:149], v[178:181], v[54:57]
	v_mfma_f32_16x16x32_bf16 v[54:57], v[150:153], v[182:185], v[54:57]
	s_waitcnt lgkmcnt(3)
	v_mfma_f32_16x16x32_bf16 v[46:49], v[146:149], v[170:173], v[46:49]
	v_mfma_f32_16x16x32_bf16 v[46:49], v[150:153], v[174:177], v[46:49]
	s_waitcnt lgkmcnt(1)
	v_mfma_f32_16x16x32_bf16 v[38:41], v[146:149], v[162:165], v[38:41]
	v_mfma_f32_16x16x32_bf16 v[38:41], v[150:153], v[166:169], v[38:41]
	v_mfma_f32_16x16x32_bf16 v[58:61], v[154:157], v[186:189], v[58:61]
	v_mfma_f32_16x16x32_bf16 v[58:61], v[158:161], v[190:193], v[58:61]
	v_mfma_f32_16x16x32_bf16 v[50:53], v[154:157], v[178:181], v[50:53]
	v_mfma_f32_16x16x32_bf16 v[50:53], v[158:161], v[182:185], v[50:53]
	v_mfma_f32_16x16x32_bf16 v[42:45], v[154:157], v[170:173], v[42:45]
	v_mfma_f32_16x16x32_bf16 v[42:45], v[158:161], v[174:177], v[42:45]
	s_waitcnt lgkmcnt(0)
	v_mfma_f32_16x16x32_bf16 v[34:37], v[154:157], v[162:165], v[34:37]
	v_mfma_f32_16x16x32_bf16 v[34:37], v[158:161], v[166:169], v[34:37]
	s_setprio 0
	s_setprio 1
	v_mfma_f32_16x16x32_bf16 v[30:33], v[130:133], v[186:189], v[30:33]
	v_mfma_f32_16x16x32_bf16 v[30:33], v[134:137], v[190:193], v[30:33]
	v_mfma_f32_16x16x32_bf16 v[22:25], v[130:133], v[178:181], v[22:25]
	v_mfma_f32_16x16x32_bf16 v[22:25], v[134:137], v[182:185], v[22:25]
	v_mfma_f32_16x16x32_bf16 v[14:17], v[130:133], v[170:173], v[14:17]
	v_mfma_f32_16x16x32_bf16 v[14:17], v[134:137], v[174:177], v[14:17]
	v_mfma_f32_16x16x32_bf16 v[6:9], v[130:133], v[162:165], v[6:9]
	v_mfma_f32_16x16x32_bf16 v[6:9], v[134:137], v[166:169], v[6:9]
	v_mfma_f32_16x16x32_bf16 v[26:29], v[138:141], v[186:189], v[26:29]
	v_mfma_f32_16x16x32_bf16 v[26:29], v[142:145], v[190:193], v[26:29]
	v_mfma_f32_16x16x32_bf16 v[18:21], v[138:141], v[178:181], v[18:21]
	v_mfma_f32_16x16x32_bf16 v[18:21], v[142:145], v[182:185], v[18:21]
	v_mfma_f32_16x16x32_bf16 v[10:13], v[138:141], v[170:173], v[10:13]
	v_mfma_f32_16x16x32_bf16 v[10:13], v[142:145], v[174:177], v[10:13]
	s_setprio 2
	s_barrier
	v_mfma_f32_16x16x32_bf16 v[2:5], v[138:141], v[162:165], v[2:5]
	v_mfma_f32_16x16x32_bf16 v[2:5], v[142:145], v[166:169], v[2:5]
	s_setprio 0
	s_nop 0
	v_add_u32_e32 v142, 0x18000, v218
	v_add_u32_e32 v158, 0x1c000, v218
	ds_read_b128 v[130:133], v142
	ds_read_b128 v[134:137], v142 offset:1024
	ds_read_b128 v[138:141], v142 offset:2048
	ds_read_b128 v[142:145], v142 offset:3072
	ds_read_b128 v[146:149], v158
	ds_read_b128 v[150:153], v158 offset:1024
	ds_read_b128 v[154:157], v158 offset:2048
	ds_read_b128 v[158:161], v158 offset:3072
	ds_read_b128 v[162:165], v219 offset:32768
	ds_read_b128 v[166:169], v219 offset:33792
	ds_read_b128 v[170:173], v219 offset:34816
	ds_read_b128 v[174:177], v219 offset:35840
	ds_read_b128 v[178:181], v219 offset:36864
	ds_read_b128 v[182:185], v219 offset:37888
	ds_read_b128 v[186:189], v219 offset:38912
	ds_read_b128 v[190:193], v219 offset:39936
	s_add_u32 s24, s24, 0x4000
	s_addc_u32 s25, s25, 0
	s_mov_b32 m0, s55
	s_nop 0
	global_load_lds_dwordx4 v195, s[24:25]
	s_add_u32 m0, s55, 0x2000
	s_nop 0
	global_load_lds_dwordx4 v213, s[24:25]
	s_waitcnt vmcnt(8)
	s_waitcnt lgkmcnt(0)
	s_setprio 1
	s_barrier
	v_mfma_f32_16x16x32_bf16 v[126:129], v[130:133], v[162:165], v[126:129]
	v_mfma_f32_16x16x32_bf16 v[126:129], v[134:137], v[166:169], v[126:129]
	s_waitcnt lgkmcnt(5)
	v_mfma_f32_16x16x32_bf16 v[118:121], v[130:133], v[170:173], v[118:121]
	v_mfma_f32_16x16x32_bf16 v[118:121], v[134:137], v[174:177], v[118:121]
	s_waitcnt lgkmcnt(3)
	v_mfma_f32_16x16x32_bf16 v[110:113], v[130:133], v[178:181], v[110:113]
	v_mfma_f32_16x16x32_bf16 v[110:113], v[134:137], v[182:185], v[110:113]
	s_waitcnt lgkmcnt(1)
	v_mfma_f32_16x16x32_bf16 v[102:105], v[130:133], v[186:189], v[102:105]
	v_mfma_f32_16x16x32_bf16 v[102:105], v[134:137], v[190:193], v[102:105]
	v_mfma_f32_16x16x32_bf16 v[122:125], v[138:141], v[162:165], v[122:125]
	v_mfma_f32_16x16x32_bf16 v[122:125], v[142:145], v[166:169], v[122:125]
	v_mfma_f32_16x16x32_bf16 v[114:117], v[138:141], v[170:173], v[114:117]
	v_mfma_f32_16x16x32_bf16 v[114:117], v[142:145], v[174:177], v[114:117]
	v_mfma_f32_16x16x32_bf16 v[106:109], v[138:141], v[178:181], v[106:109]
	v_mfma_f32_16x16x32_bf16 v[106:109], v[142:145], v[182:185], v[106:109]
	s_waitcnt lgkmcnt(0)
	v_mfma_f32_16x16x32_bf16 v[98:101], v[138:141], v[186:189], v[98:101]
	v_mfma_f32_16x16x32_bf16 v[98:101], v[142:145], v[190:193], v[98:101]
	s_setprio 0
	s_setprio 1
	v_mfma_f32_16x16x32_bf16 v[94:97], v[146:149], v[162:165], v[94:97]
	v_mfma_f32_16x16x32_bf16 v[94:97], v[150:153], v[166:169], v[94:97]
	v_mfma_f32_16x16x32_bf16 v[86:89], v[146:149], v[170:173], v[86:89]
	v_mfma_f32_16x16x32_bf16 v[86:89], v[150:153], v[174:177], v[86:89]
	v_mfma_f32_16x16x32_bf16 v[78:81], v[146:149], v[178:181], v[78:81]
	v_mfma_f32_16x16x32_bf16 v[78:81], v[150:153], v[182:185], v[78:81]
	v_mfma_f32_16x16x32_bf16 v[70:73], v[146:149], v[186:189], v[70:73]
	v_mfma_f32_16x16x32_bf16 v[70:73], v[150:153], v[190:193], v[70:73]
	v_mfma_f32_16x16x32_bf16 v[90:93], v[154:157], v[162:165], v[90:93]
	v_mfma_f32_16x16x32_bf16 v[90:93], v[158:161], v[166:169], v[90:93]
	v_mfma_f32_16x16x32_bf16 v[82:85], v[154:157], v[170:173], v[82:85]
	v_mfma_f32_16x16x32_bf16 v[82:85], v[158:161], v[174:177], v[82:85]
	v_mfma_f32_16x16x32_bf16 v[74:77], v[154:157], v[178:181], v[74:77]
	v_mfma_f32_16x16x32_bf16 v[74:77], v[158:161], v[182:185], v[74:77]
	s_setprio 2
	s_barrier
	v_mfma_f32_16x16x32_bf16 v[66:69], v[154:157], v[186:189], v[66:69]
	v_mfma_f32_16x16x32_bf16 v[66:69], v[158:161], v[190:193], v[66:69]
	s_setprio 0
	s_nop 0
	ds_read_b128 v[162:165], v219 offset:49152
	ds_read_b128 v[166:169], v219 offset:50176
	ds_read_b128 v[170:173], v219 offset:51200
	ds_read_b128 v[174:177], v219 offset:52224
	ds_read_b128 v[178:181], v219 offset:53248
	ds_read_b128 v[182:185], v219 offset:54272
	ds_read_b128 v[186:189], v219 offset:55296
	ds_read_b128 v[190:193], v219 offset:56320
	s_mov_b32 m0, s83
	s_nop 0
	global_load_lds_dwordx4 v195, s[28:29]
	s_add_u32 m0, s83, 0x2000
	s_nop 0
	global_load_lds_dwordx4 v213, s[28:29]
	s_add_u32 s22, s22, 0xc000
	s_addc_u32 s23, s23, 0
	s_mov_b32 m0, s91
	s_nop 0
	global_load_lds_dwordx4 v195, s[22:23]
	s_add_u32 m0, s91, 0x2000
	s_nop 0
	global_load_lds_dwordx4 v213, s[22:23]
	s_nop 0
	s_mov_b32 m0, s90
	s_nop 0
	global_load_lds_dwordx4 v195, s[26:27]
	s_add_u32 m0, s90, 0x2000
	s_nop 0
	global_load_lds_dwordx4 v213, s[26:27]
	s_waitcnt vmcnt(8)
	s_waitcnt lgkmcnt(0)
	s_setprio 1
	s_barrier
	v_mfma_f32_16x16x32_bf16 v[62:65], v[130:133], v[162:165], v[62:65]
	v_mfma_f32_16x16x32_bf16 v[62:65], v[134:137], v[166:169], v[62:65]
	s_waitcnt lgkmcnt(5)
	v_mfma_f32_16x16x32_bf16 v[54:57], v[130:133], v[170:173], v[54:57]
	v_mfma_f32_16x16x32_bf16 v[54:57], v[134:137], v[174:177], v[54:57]
	s_waitcnt lgkmcnt(3)
	v_mfma_f32_16x16x32_bf16 v[46:49], v[130:133], v[178:181], v[46:49]
	v_mfma_f32_16x16x32_bf16 v[46:49], v[134:137], v[182:185], v[46:49]
	s_waitcnt lgkmcnt(1)
	v_mfma_f32_16x16x32_bf16 v[38:41], v[130:133], v[186:189], v[38:41]
	v_mfma_f32_16x16x32_bf16 v[38:41], v[134:137], v[190:193], v[38:41]
	v_mfma_f32_16x16x32_bf16 v[58:61], v[138:141], v[162:165], v[58:61]
	v_mfma_f32_16x16x32_bf16 v[58:61], v[142:145], v[166:169], v[58:61]
	v_mfma_f32_16x16x32_bf16 v[50:53], v[138:141], v[170:173], v[50:53]
	v_mfma_f32_16x16x32_bf16 v[50:53], v[142:145], v[174:177], v[50:53]
	v_mfma_f32_16x16x32_bf16 v[42:45], v[138:141], v[178:181], v[42:45]
	v_mfma_f32_16x16x32_bf16 v[42:45], v[142:145], v[182:185], v[42:45]
	s_waitcnt lgkmcnt(0)
	v_mfma_f32_16x16x32_bf16 v[34:37], v[138:141], v[186:189], v[34:37]
	v_mfma_f32_16x16x32_bf16 v[34:37], v[142:145], v[190:193], v[34:37]
	s_setprio 0
	s_setprio 1
	v_mfma_f32_16x16x32_bf16 v[30:33], v[146:149], v[162:165], v[30:33]
	v_mfma_f32_16x16x32_bf16 v[30:33], v[150:153], v[166:169], v[30:33]
	v_mfma_f32_16x16x32_bf16 v[22:25], v[146:149], v[170:173], v[22:25]
	v_mfma_f32_16x16x32_bf16 v[22:25], v[150:153], v[174:177], v[22:25]
	v_mfma_f32_16x16x32_bf16 v[14:17], v[146:149], v[178:181], v[14:17]
	v_mfma_f32_16x16x32_bf16 v[14:17], v[150:153], v[182:185], v[14:17]
	v_mfma_f32_16x16x32_bf16 v[6:9], v[146:149], v[186:189], v[6:9]
	v_mfma_f32_16x16x32_bf16 v[6:9], v[150:153], v[190:193], v[6:9]
	v_mfma_f32_16x16x32_bf16 v[26:29], v[154:157], v[162:165], v[26:29]
	v_mfma_f32_16x16x32_bf16 v[26:29], v[158:161], v[166:169], v[26:29]
	v_mfma_f32_16x16x32_bf16 v[18:21], v[154:157], v[170:173], v[18:21]
	v_mfma_f32_16x16x32_bf16 v[18:21], v[158:161], v[174:177], v[18:21]
	v_mfma_f32_16x16x32_bf16 v[10:13], v[154:157], v[178:181], v[10:13]
	v_mfma_f32_16x16x32_bf16 v[10:13], v[158:161], v[182:185], v[10:13]
	s_setprio 2
	s_barrier
	v_mfma_f32_16x16x32_bf16 v[2:5], v[154:157], v[186:189], v[2:5]
	v_mfma_f32_16x16x32_bf16 v[2:5], v[158:161], v[190:193], v[2:5]
	s_setprio 0
	s_nop 0
	s_add_i32 s3, s71, 2
	s_cmp_gt_u32 s71, 13
	s_cbranch_scc1 .LBB0_639
	s_mov_b32 s71, s3
	s_branch .LBB0_616

.LBB0_1068:
	s_or_b64 exec, exec, s[62:63]
	s_add_u32 s88, s12, s0
	ds_read_b128 v[132:135], v214
	ds_read_b128 v[136:139], v214 offset:1024
	ds_read_b128 v[140:143], v214 offset:2048
	ds_read_b128 v[144:147], v214 offset:3072
	ds_read_b128 v[154:157], v215
	ds_read_b128 v[158:161], v215 offset:1024
	ds_read_b128 v[162:165], v215 offset:2048
	ds_read_b128 v[166:169], v215 offset:3072
	s_addc_u32 s89, s13, s1
	s_add_u32 s62, s88, 0x20000
	s_addc_u32 s63, s89, 0
	s_add_u32 s64, s94, s0
	s_addc_u32 s65, s96, s1
	s_cmp_eq_u32 s0, 0x60000
	s_cselect_b32 s68, s53, s62
	s_cselect_b32 s69, s33, s63
	s_cselect_b32 s63, s51, s65
	s_cselect_b32 s62, s95, s64
	s_add_u32 s64, s68, 0x8000
	s_addc_u32 s65, s69, 0
	s_add_u32 s66, s62, 0x8000
	s_addc_u32 s67, s63, 0
	ds_read_b128 v[170:173], v216
	ds_read_b128 v[174:177], v216 offset:1024
	ds_read_b128 v[178:181], v216 offset:2048
	ds_read_b128 v[182:185], v216 offset:3072
	ds_read_b128 v[186:189], v216 offset:4096
	ds_read_b128 v[190:193], v216 offset:5120
	ds_read_b128 v[198:201], v216 offset:6144
	ds_read_b128 v[202:205], v216 offset:7168
	s_add_u32 s88, s88, 0x1c000
	s_addc_u32 s89, s89, 0
	s_mov_b32 m0, s79
	s_nop 0
	global_load_lds_dwordx4 v195, s[88:89]
	s_add_u32 m0, s79, 0x2000
	s_nop 0
	global_load_lds_dwordx4 v212, s[88:89]
	s_waitcnt vmcnt(8)
	s_waitcnt lgkmcnt(0)
	s_setprio 1
	s_barrier
	v_mfma_f32_16x16x32_bf16 v[126:129], v[132:135], v[170:173], v[126:129]
	v_mfma_f32_16x16x32_bf16 v[126:129], v[136:139], v[174:177], v[126:129]
	s_waitcnt lgkmcnt(5)
	v_mfma_f32_16x16x32_bf16 v[110:113], v[132:135], v[178:181], v[110:113]
	v_mfma_f32_16x16x32_bf16 v[110:113], v[136:139], v[182:185], v[110:113]
	s_waitcnt lgkmcnt(3)
	v_mfma_f32_16x16x32_bf16 v[94:97], v[132:135], v[186:189], v[94:97]
	v_mfma_f32_16x16x32_bf16 v[94:97], v[136:139], v[190:193], v[94:97]
	s_waitcnt lgkmcnt(1)
	v_mfma_f32_16x16x32_bf16 v[78:81], v[132:135], v[198:201], v[78:81]
	v_mfma_f32_16x16x32_bf16 v[78:81], v[136:139], v[202:205], v[78:81]
	v_mfma_f32_16x16x32_bf16 v[122:125], v[140:143], v[170:173], v[122:125]
	v_mfma_f32_16x16x32_bf16 v[122:125], v[144:147], v[174:177], v[122:125]
	v_mfma_f32_16x16x32_bf16 v[106:109], v[140:143], v[178:181], v[106:109]
	v_mfma_f32_16x16x32_bf16 v[106:109], v[144:147], v[182:185], v[106:109]
	v_mfma_f32_16x16x32_bf16 v[90:93], v[140:143], v[186:189], v[90:93]
	v_mfma_f32_16x16x32_bf16 v[90:93], v[144:147], v[190:193], v[90:93]
	s_waitcnt lgkmcnt(0)
	v_mfma_f32_16x16x32_bf16 v[74:77], v[140:143], v[198:201], v[74:77]
	v_mfma_f32_16x16x32_bf16 v[74:77], v[144:147], v[202:205], v[74:77]
	s_setprio 0
	s_setprio 1
	v_mfma_f32_16x16x32_bf16 v[118:121], v[154:157], v[170:173], v[118:121]
	v_mfma_f32_16x16x32_bf16 v[118:121], v[158:161], v[174:177], v[118:121]
	v_mfma_f32_16x16x32_bf16 v[102:105], v[154:157], v[178:181], v[102:105]
	v_mfma_f32_16x16x32_bf16 v[102:105], v[158:161], v[182:185], v[102:105]
	v_mfma_f32_16x16x32_bf16 v[86:89], v[154:157], v[186:189], v[86:89]
	v_mfma_f32_16x16x32_bf16 v[86:89], v[158:161], v[190:193], v[86:89]
	v_mfma_f32_16x16x32_bf16 v[70:73], v[154:157], v[198:201], v[70:73]
	v_mfma_f32_16x16x32_bf16 v[70:73], v[158:161], v[202:205], v[70:73]
	v_mfma_f32_16x16x32_bf16 v[114:117], v[162:165], v[170:173], v[114:117]
	v_mfma_f32_16x16x32_bf16 v[114:117], v[166:169], v[174:177], v[114:117]
	v_mfma_f32_16x16x32_bf16 v[98:101], v[162:165], v[178:181], v[98:101]
	v_mfma_f32_16x16x32_bf16 v[98:101], v[166:169], v[182:185], v[98:101]
	v_mfma_f32_16x16x32_bf16 v[82:85], v[162:165], v[186:189], v[82:85]
	v_mfma_f32_16x16x32_bf16 v[82:85], v[166:169], v[190:193], v[82:85]
	s_setprio 2
	s_barrier
	v_mfma_f32_16x16x32_bf16 v[66:69], v[162:165], v[198:201], v[66:69]
	v_mfma_f32_16x16x32_bf16 v[66:69], v[166:169], v[202:205], v[66:69]
	s_setprio 0
	s_nop 0
	ds_read_b128 v[170:173], v216 offset:16384
	ds_read_b128 v[174:177], v216 offset:17408
	ds_read_b128 v[178:181], v216 offset:18432
	ds_read_b128 v[182:185], v216 offset:19456
	ds_read_b128 v[186:189], v216 offset:20480
	ds_read_b128 v[190:193], v216 offset:21504
	ds_read_b128 v[198:201], v216 offset:22528
	ds_read_b128 v[202:205], v216 offset:23552
	s_mov_b32 m0, s3
	s_nop 0
	global_load_lds_dwordx4 v195, s[62:63]
	s_add_u32 m0, s3, 0x2000
	s_nop 0
	global_load_lds_dwordx4 v212, s[62:63]
	s_add_u32 s88, s62, 0x4000
	s_addc_u32 s89, s63, 0
	s_mov_b32 m0, s71
	s_nop 0
	global_load_lds_dwordx4 v195, s[88:89]
	s_add_u32 m0, s71, 0x2000
	s_nop 0
	global_load_lds_dwordx4 v212, s[88:89]
	s_nop 0
	s_mov_b32 m0, s70
	s_nop 0
	global_load_lds_dwordx4 v195, s[68:69]
	s_add_u32 m0, s70, 0x2000
	s_nop 0
	global_load_lds_dwordx4 v212, s[68:69]
	s_waitcnt vmcnt(8)
	s_waitcnt lgkmcnt(0)
	s_setprio 1
	s_barrier
	v_mfma_f32_16x16x32_bf16 v[62:65], v[132:135], v[170:173], v[62:65]
	v_mfma_f32_16x16x32_bf16 v[62:65], v[136:139], v[174:177], v[62:65]
	s_waitcnt lgkmcnt(5)
	v_mfma_f32_16x16x32_bf16 v[46:49], v[132:135], v[178:181], v[46:49]
	v_mfma_f32_16x16x32_bf16 v[46:49], v[136:139], v[182:185], v[46:49]
	s_waitcnt lgkmcnt(3)
	v_mfma_f32_16x16x32_bf16 v[30:33], v[132:135], v[186:189], v[30:33]
	v_mfma_f32_16x16x32_bf16 v[30:33], v[136:139], v[190:193], v[30:33]
	s_waitcnt lgkmcnt(1)
	v_mfma_f32_16x16x32_bf16 v[14:17], v[132:135], v[198:201], v[14:17]
	v_mfma_f32_16x16x32_bf16 v[14:17], v[136:139], v[202:205], v[14:17]
	v_mfma_f32_16x16x32_bf16 v[58:61], v[140:143], v[170:173], v[58:61]
	v_mfma_f32_16x16x32_bf16 v[58:61], v[144:147], v[174:177], v[58:61]
	v_mfma_f32_16x16x32_bf16 v[42:45], v[140:143], v[178:181], v[42:45]
	v_mfma_f32_16x16x32_bf16 v[42:45], v[144:147], v[182:185], v[42:45]
	v_mfma_f32_16x16x32_bf16 v[26:29], v[140:143], v[186:189], v[26:29]
	v_mfma_f32_16x16x32_bf16 v[26:29], v[144:147], v[190:193], v[26:29]
	s_waitcnt lgkmcnt(0)
	v_mfma_f32_16x16x32_bf16 v[10:13], v[140:143], v[198:201], v[10:13]
	v_mfma_f32_16x16x32_bf16 v[10:13], v[144:147], v[202:205], v[10:13]
	s_setprio 0
	s_setprio 1
	v_mfma_f32_16x16x32_bf16 v[54:57], v[154:157], v[170:173], v[54:57]
	v_mfma_f32_16x16x32_bf16 v[54:57], v[158:161], v[174:177], v[54:57]
	v_mfma_f32_16x16x32_bf16 v[38:41], v[154:157], v[178:181], v[38:41]
	v_mfma_f32_16x16x32_bf16 v[38:41], v[158:161], v[182:185], v[38:41]
	v_mfma_f32_16x16x32_bf16 v[22:25], v[154:157], v[186:189], v[22:25]
	v_mfma_f32_16x16x32_bf16 v[22:25], v[158:161], v[190:193], v[22:25]
	v_mfma_f32_16x16x32_bf16 v[6:9], v[154:157], v[198:201], v[6:9]
	v_mfma_f32_16x16x32_bf16 v[6:9], v[158:161], v[202:205], v[6:9]
	v_mfma_f32_16x16x32_bf16 v[50:53], v[162:165], v[170:173], v[50:53]
	v_mfma_f32_16x16x32_bf16 v[50:53], v[166:169], v[174:177], v[50:53]
	v_mfma_f32_16x16x32_bf16 v[34:37], v[162:165], v[178:181], v[34:37]
	v_mfma_f32_16x16x32_bf16 v[34:37], v[166:169], v[182:185], v[34:37]
	v_mfma_f32_16x16x32_bf16 v[18:21], v[162:165], v[186:189], v[18:21]
	v_mfma_f32_16x16x32_bf16 v[18:21], v[166:169], v[190:193], v[18:21]
	s_setprio 2
	s_barrier
	v_mfma_f32_16x16x32_bf16 v[2:5], v[162:165], v[198:201], v[2:5]
	v_mfma_f32_16x16x32_bf16 v[2:5], v[166:169], v[202:205], v[2:5]
	s_setprio 0
	s_nop 0
	ds_read_b128 v[132:135], v217
	ds_read_b128 v[136:139], v217 offset:1024
	ds_read_b128 v[140:143], v217 offset:2048
	ds_read_b128 v[144:147], v217 offset:3072
	ds_read_b128 v[154:157], v218
	ds_read_b128 v[158:161], v218 offset:1024
	ds_read_b128 v[162:165], v218 offset:2048
	ds_read_b128 v[166:169], v218 offset:3072
	ds_read_b128 v[170:173], v216 offset:32768
	ds_read_b128 v[174:177], v216 offset:33792
	ds_read_b128 v[178:181], v216 offset:34816
	ds_read_b128 v[182:185], v216 offset:35840
	ds_read_b128 v[186:189], v216 offset:36864
	ds_read_b128 v[190:193], v216 offset:37888
	ds_read_b128 v[198:201], v216 offset:38912
	ds_read_b128 v[202:205], v216 offset:39936
	s_add_u32 s68, s68, 0x4000
	s_addc_u32 s69, s69, 0
	s_mov_b32 m0, s72
	s_nop 0
	global_load_lds_dwordx4 v195, s[68:69]
	s_add_u32 m0, s72, 0x2000
	s_nop 0
	global_load_lds_dwordx4 v212, s[68:69]
	s_waitcnt vmcnt(8)
	s_waitcnt lgkmcnt(0)
	s_setprio 1
	s_barrier
	v_mfma_f32_16x16x32_bf16 v[126:129], v[132:135], v[170:173], v[126:129]
	v_mfma_f32_16x16x32_bf16 v[126:129], v[136:139], v[174:177], v[126:129]
	s_waitcnt lgkmcnt(5)
	v_mfma_f32_16x16x32_bf16 v[110:113], v[132:135], v[178:181], v[110:113]
	v_mfma_f32_16x16x32_bf16 v[110:113], v[136:139], v[182:185], v[110:113]
	s_waitcnt lgkmcnt(3)
	v_mfma_f32_16x16x32_bf16 v[94:97], v[132:135], v[186:189], v[94:97]
	v_mfma_f32_16x16x32_bf16 v[94:97], v[136:139], v[190:193], v[94:97]
	s_waitcnt lgkmcnt(1)
	v_mfma_f32_16x16x32_bf16 v[78:81], v[132:135], v[198:201], v[78:81]
	v_mfma_f32_16x16x32_bf16 v[78:81], v[136:139], v[202:205], v[78:81]
	v_mfma_f32_16x16x32_bf16 v[122:125], v[140:143], v[170:173], v[122:125]
	v_mfma_f32_16x16x32_bf16 v[122:125], v[144:147], v[174:177], v[122:125]
	v_mfma_f32_16x16x32_bf16 v[106:109], v[140:143], v[178:181], v[106:109]
	v_mfma_f32_16x16x32_bf16 v[106:109], v[144:147], v[182:185], v[106:109]
	v_mfma_f32_16x16x32_bf16 v[90:93], v[140:143], v[186:189], v[90:93]
	v_mfma_f32_16x16x32_bf16 v[90:93], v[144:147], v[190:193], v[90:93]
	s_waitcnt lgkmcnt(0)
	v_mfma_f32_16x16x32_bf16 v[74:77], v[140:143], v[198:201], v[74:77]
	v_mfma_f32_16x16x32_bf16 v[74:77], v[144:147], v[202:205], v[74:77]
	s_setprio 0
	s_setprio 1
	v_mfma_f32_16x16x32_bf16 v[118:121], v[154:157], v[170:173], v[118:121]
	v_mfma_f32_16x16x32_bf16 v[118:121], v[158:161], v[174:177], v[118:121]
	v_mfma_f32_16x16x32_bf16 v[102:105], v[154:157], v[178:181], v[102:105]
	v_mfma_f32_16x16x32_bf16 v[102:105], v[158:161], v[182:185], v[102:105]
	v_mfma_f32_16x16x32_bf16 v[86:89], v[154:157], v[186:189], v[86:89]
	v_mfma_f32_16x16x32_bf16 v[86:89], v[158:161], v[190:193], v[86:89]
	v_mfma_f32_16x16x32_bf16 v[70:73], v[154:157], v[198:201], v[70:73]
	v_mfma_f32_16x16x32_bf16 v[70:73], v[158:161], v[202:205], v[70:73]
	v_mfma_f32_16x16x32_bf16 v[114:117], v[162:165], v[170:173], v[114:117]
	v_mfma_f32_16x16x32_bf16 v[114:117], v[166:169], v[174:177], v[114:117]
	v_mfma_f32_16x16x32_bf16 v[98:101], v[162:165], v[178:181], v[98:101]
	v_mfma_f32_16x16x32_bf16 v[98:101], v[166:169], v[182:185], v[98:101]
	v_mfma_f32_16x16x32_bf16 v[82:85], v[162:165], v[186:189], v[82:85]
	v_mfma_f32_16x16x32_bf16 v[82:85], v[166:169], v[190:193], v[82:85]
	s_setprio 2
	s_barrier
	v_mfma_f32_16x16x32_bf16 v[66:69], v[162:165], v[198:201], v[66:69]
	v_mfma_f32_16x16x32_bf16 v[66:69], v[166:169], v[202:205], v[66:69]
	s_setprio 0
	s_nop 0
	ds_read_b128 v[170:173], v216 offset:49152
	ds_read_b128 v[174:177], v216 offset:50176
	ds_read_b128 v[178:181], v216 offset:51200
	ds_read_b128 v[182:185], v216 offset:52224
	ds_read_b128 v[186:189], v216 offset:53248
	ds_read_b128 v[190:193], v216 offset:54272
	ds_read_b128 v[198:201], v216 offset:55296
	ds_read_b128 v[202:205], v216 offset:56320
	s_mov_b32 m0, s76
	s_nop 0
	global_load_lds_dwordx4 v195, s[66:67]
	s_add_u32 m0, s76, 0x2000
	s_nop 0
	global_load_lds_dwordx4 v212, s[66:67]
	s_add_u32 s62, s62, 0xc000
	s_addc_u32 s63, s63, 0
	s_mov_b32 m0, s78
	s_nop 0
	global_load_lds_dwordx4 v195, s[62:63]
	s_add_u32 m0, s78, 0x2000
	s_nop 0
	global_load_lds_dwordx4 v212, s[62:63]
	s_nop 0
	s_mov_b32 m0, s77
	s_nop 0
	global_load_lds_dwordx4 v195, s[64:65]
	s_add_u32 m0, s77, 0x2000
	s_nop 0
	global_load_lds_dwordx4 v212, s[64:65]
	s_waitcnt vmcnt(8)
	s_waitcnt lgkmcnt(0)
	s_setprio 1
	s_barrier
	v_mfma_f32_16x16x32_bf16 v[62:65], v[132:135], v[170:173], v[62:65]
	v_mfma_f32_16x16x32_bf16 v[62:65], v[136:139], v[174:177], v[62:65]
	s_waitcnt lgkmcnt(5)
	v_mfma_f32_16x16x32_bf16 v[46:49], v[132:135], v[178:181], v[46:49]
	v_mfma_f32_16x16x32_bf16 v[46:49], v[136:139], v[182:185], v[46:49]
	s_waitcnt lgkmcnt(3)
	v_mfma_f32_16x16x32_bf16 v[30:33], v[132:135], v[186:189], v[30:33]
	v_mfma_f32_16x16x32_bf16 v[30:33], v[136:139], v[190:193], v[30:33]
	s_waitcnt lgkmcnt(1)
	v_mfma_f32_16x16x32_bf16 v[14:17], v[132:135], v[198:201], v[14:17]
	v_mfma_f32_16x16x32_bf16 v[14:17], v[136:139], v[202:205], v[14:17]
	v_mfma_f32_16x16x32_bf16 v[58:61], v[140:143], v[170:173], v[58:61]
	v_mfma_f32_16x16x32_bf16 v[58:61], v[144:147], v[174:177], v[58:61]
	v_mfma_f32_16x16x32_bf16 v[42:45], v[140:143], v[178:181], v[42:45]
	v_mfma_f32_16x16x32_bf16 v[42:45], v[144:147], v[182:185], v[42:45]
	v_mfma_f32_16x16x32_bf16 v[26:29], v[140:143], v[186:189], v[26:29]
	v_mfma_f32_16x16x32_bf16 v[26:29], v[144:147], v[190:193], v[26:29]
	s_waitcnt lgkmcnt(0)
	v_mfma_f32_16x16x32_bf16 v[10:13], v[140:143], v[198:201], v[10:13]
	v_mfma_f32_16x16x32_bf16 v[10:13], v[144:147], v[202:205], v[10:13]
	s_setprio 0
	s_setprio 1
	v_mfma_f32_16x16x32_bf16 v[54:57], v[154:157], v[170:173], v[54:57]
	v_mfma_f32_16x16x32_bf16 v[54:57], v[158:161], v[174:177], v[54:57]
	v_mfma_f32_16x16x32_bf16 v[38:41], v[154:157], v[178:181], v[38:41]
	v_mfma_f32_16x16x32_bf16 v[38:41], v[158:161], v[182:185], v[38:41]
	v_mfma_f32_16x16x32_bf16 v[22:25], v[154:157], v[186:189], v[22:25]
	v_mfma_f32_16x16x32_bf16 v[22:25], v[158:161], v[190:193], v[22:25]
	v_mfma_f32_16x16x32_bf16 v[6:9], v[154:157], v[198:201], v[6:9]
	v_mfma_f32_16x16x32_bf16 v[6:9], v[158:161], v[202:205], v[6:9]
	v_mfma_f32_16x16x32_bf16 v[50:53], v[162:165], v[170:173], v[50:53]
	v_mfma_f32_16x16x32_bf16 v[50:53], v[166:169], v[174:177], v[50:53]
	v_mfma_f32_16x16x32_bf16 v[34:37], v[162:165], v[178:181], v[34:37]
	v_mfma_f32_16x16x32_bf16 v[34:37], v[166:169], v[182:185], v[34:37]
	v_mfma_f32_16x16x32_bf16 v[18:21], v[162:165], v[186:189], v[18:21]
	v_mfma_f32_16x16x32_bf16 v[18:21], v[166:169], v[190:193], v[18:21]
	s_setprio 2
	s_barrier
	v_mfma_f32_16x16x32_bf16 v[2:5], v[162:165], v[198:201], v[2:5]
	v_mfma_f32_16x16x32_bf16 v[2:5], v[166:169], v[202:205], v[2:5]
	s_setprio 0
	s_nop 0
	s_add_i32 s97, s97, 2
	s_add_u32 s0, s0, 0x10000
	s_addc_u32 s1, s1, 0
	s_cmp_gt_u32 s97, 13
	s_cbranch_scc1 .LBB0_1070
	v_mov_b32_e32 v131, v130
	s_branch .LBB0_1066

.LBB0_1336:
	s_add_u32 s50, s46, 0x10000
	s_addc_u32 s51, s47, 0
	s_and_b64 s[46:47], s[42:43], exec
	s_cselect_b32 s47, s51, s23
	s_cselect_b32 s46, s50, s75
	s_add_u32 s13, s16, s13
	s_addc_u32 s50, s17, 0
	s_add_u32 s13, s13, 0x10000
	s_waitcnt vmcnt(8)
	s_addc_u32 s50, s50, 0
	s_waitcnt lgkmcnt(0)
	s_and_b64 s[42:43], s[42:43], exec
	s_cselect_b32 s43, s50, s25
	s_cselect_b32 s42, s13, s76
	s_setprio 1
	s_barrier
	v_mfma_f32_16x16x32_bf16 v[126:129], v[146:149], v[186:189], v[126:129]
	v_mfma_f32_16x16x32_bf16 v[126:129], v[150:153], v[190:193], v[126:129]
	s_waitcnt lgkmcnt(5)
	v_mfma_f32_16x16x32_bf16 v[118:121], v[146:149], v[178:181], v[118:121]
	v_mfma_f32_16x16x32_bf16 v[118:121], v[150:153], v[182:185], v[118:121]
	s_waitcnt lgkmcnt(3)
	v_mfma_f32_16x16x32_bf16 v[110:113], v[146:149], v[170:173], v[110:113]
	v_mfma_f32_16x16x32_bf16 v[110:113], v[150:153], v[174:177], v[110:113]
	s_waitcnt lgkmcnt(1)
	v_mfma_f32_16x16x32_bf16 v[102:105], v[146:149], v[162:165], v[102:105]
	v_mfma_f32_16x16x32_bf16 v[102:105], v[150:153], v[166:169], v[102:105]
	v_mfma_f32_16x16x32_bf16 v[122:125], v[154:157], v[186:189], v[122:125]
	v_mfma_f32_16x16x32_bf16 v[122:125], v[158:161], v[190:193], v[122:125]
	v_mfma_f32_16x16x32_bf16 v[114:117], v[154:157], v[178:181], v[114:117]
	v_mfma_f32_16x16x32_bf16 v[114:117], v[158:161], v[182:185], v[114:117]
	v_mfma_f32_16x16x32_bf16 v[106:109], v[154:157], v[170:173], v[106:109]
	v_mfma_f32_16x16x32_bf16 v[106:109], v[158:161], v[174:177], v[106:109]
	s_waitcnt lgkmcnt(0)
	v_mfma_f32_16x16x32_bf16 v[98:101], v[154:157], v[162:165], v[98:101]
	v_mfma_f32_16x16x32_bf16 v[98:101], v[158:161], v[166:169], v[98:101]
	s_setprio 0
	s_setprio 1
	v_mfma_f32_16x16x32_bf16 v[94:97], v[130:133], v[186:189], v[94:97]
	v_mfma_f32_16x16x32_bf16 v[94:97], v[134:137], v[190:193], v[94:97]
	v_mfma_f32_16x16x32_bf16 v[86:89], v[130:133], v[178:181], v[86:89]
	v_mfma_f32_16x16x32_bf16 v[86:89], v[134:137], v[182:185], v[86:89]
	v_mfma_f32_16x16x32_bf16 v[78:81], v[130:133], v[170:173], v[78:81]
	v_mfma_f32_16x16x32_bf16 v[78:81], v[134:137], v[174:177], v[78:81]
	v_mfma_f32_16x16x32_bf16 v[70:73], v[130:133], v[162:165], v[70:73]
	v_mfma_f32_16x16x32_bf16 v[70:73], v[134:137], v[166:169], v[70:73]
	v_mfma_f32_16x16x32_bf16 v[90:93], v[138:141], v[186:189], v[90:93]
	v_mfma_f32_16x16x32_bf16 v[90:93], v[142:145], v[190:193], v[90:93]
	v_mfma_f32_16x16x32_bf16 v[82:85], v[138:141], v[178:181], v[82:85]
	v_mfma_f32_16x16x32_bf16 v[82:85], v[142:145], v[182:185], v[82:85]
	v_mfma_f32_16x16x32_bf16 v[74:77], v[138:141], v[170:173], v[74:77]
	v_mfma_f32_16x16x32_bf16 v[74:77], v[142:145], v[174:177], v[74:77]
	s_setprio 2
	s_barrier
	v_mfma_f32_16x16x32_bf16 v[66:69], v[138:141], v[162:165], v[66:69]
	v_mfma_f32_16x16x32_bf16 v[66:69], v[142:145], v[166:169], v[66:69]
	s_setprio 0
	s_nop 0
	ds_read_b128 v[186:189], v208 offset:16384
	ds_read_b128 v[190:193], v208 offset:17408
	ds_read_b128 v[178:181], v208 offset:18432
	ds_read_b128 v[182:185], v208 offset:19456
	ds_read_b128 v[170:173], v208 offset:20480
	ds_read_b128 v[174:177], v208 offset:21504
	ds_read_b128 v[162:165], v208 offset:22528
	ds_read_b128 v[166:169], v208 offset:23552
	s_mov_b32 m0, s58
	s_nop 0
	global_load_lds_dwordx4 v202, s[42:43]
	s_add_u32 m0, s58, 0x2000
	s_nop 0
	global_load_lds_dwordx4 v203, s[42:43]
	s_add_u32 s50, s42, 0x4000
	s_addc_u32 s51, s43, 0
	s_mov_b32 m0, s59
	s_nop 0
	global_load_lds_dwordx4 v202, s[50:51]
	s_add_u32 m0, s59, 0x2000
	s_nop 0
	global_load_lds_dwordx4 v203, s[50:51]
	s_andn2_b64 vcc, exec, s[48:49]
	s_mov_b32 m0, s7
	s_nop 0
	global_load_lds_dwordx4 v202, s[46:47]
	s_add_u32 m0, s7, 0x2000
	s_nop 0
	global_load_lds_dwordx4 v203, s[46:47]
	s_cbranch_vccnz .LBB0_1338
	v_mov_b32_e32 v2, 0
	v_mov_b32_e32 v3, v2
	v_mov_b32_e32 v4, v2
	v_mov_b32_e32 v5, v2
	v_mov_b32_e32 v6, v2
	v_mov_b32_e32 v7, v2
	v_mov_b32_e32 v8, v2
	v_mov_b32_e32 v9, v2
	v_mov_b32_e32 v10, v2
	v_mov_b32_e32 v11, v2
	v_mov_b32_e32 v12, v2
	v_mov_b32_e32 v13, v2
	v_mov_b32_e32 v14, v2
	v_mov_b32_e32 v15, v2
	v_mov_b32_e32 v16, v2
	v_mov_b32_e32 v17, v2
	v_mov_b32_e32 v18, v2
	v_mov_b32_e32 v19, v2
	v_mov_b32_e32 v20, v2
	v_mov_b32_e32 v21, v2
	v_mov_b32_e32 v22, v2
	v_mov_b32_e32 v23, v2
	v_mov_b32_e32 v24, v2
	v_mov_b32_e32 v25, v2
	v_mov_b32_e32 v26, v2
	v_mov_b32_e32 v27, v2
	v_mov_b32_e32 v28, v2
	v_mov_b32_e32 v29, v2
	v_mov_b32_e32 v30, v2
	v_mov_b32_e32 v31, v2
	v_mov_b32_e32 v32, v2
	v_mov_b32_e32 v33, v2
	v_mov_b32_e32 v34, v2
	v_mov_b32_e32 v35, v2
	v_mov_b32_e32 v36, v2
	v_mov_b32_e32 v37, v2
	v_mov_b32_e32 v38, v2
	v_mov_b32_e32 v39, v2
	v_mov_b32_e32 v40, v2
	v_mov_b32_e32 v41, v2
	v_mov_b32_e32 v42, v2
	v_mov_b32_e32 v43, v2
	v_mov_b32_e32 v44, v2
	v_mov_b32_e32 v45, v2
	v_mov_b32_e32 v46, v2
	v_mov_b32_e32 v47, v2
	v_mov_b32_e32 v48, v2
	v_mov_b32_e32 v49, v2
	v_mov_b32_e32 v50, v2
	v_mov_b32_e32 v51, v2
	v_mov_b32_e32 v52, v2
	v_mov_b32_e32 v53, v2
	v_mov_b32_e32 v54, v2
	v_mov_b32_e32 v55, v2
	v_mov_b32_e32 v56, v2
	v_mov_b32_e32 v57, v2
	v_mov_b32_e32 v58, v2
	v_mov_b32_e32 v59, v2
	v_mov_b32_e32 v60, v2
	v_mov_b32_e32 v61, v2
	v_mov_b32_e32 v62, v2
	v_mov_b32_e32 v63, v2
	v_mov_b32_e32 v64, v2
	v_mov_b32_e32 v65, v2
.LBB0_1338:
	s_waitcnt vmcnt(8)
	s_add_u32 s48, s46, 0x8000
	s_waitcnt lgkmcnt(0)
	s_addc_u32 s49, s47, 0
	s_add_u32 s50, s42, 0x8000
	s_addc_u32 s51, s43, 0
	s_setprio 1
	s_barrier
	v_mfma_f32_16x16x32_bf16 v[62:65], v[146:149], v[186:189], v[62:65]
	v_mfma_f32_16x16x32_bf16 v[62:65], v[150:153], v[190:193], v[62:65]
	s_waitcnt lgkmcnt(5)
	v_mfma_f32_16x16x32_bf16 v[54:57], v[146:149], v[178:181], v[54:57]
	v_mfma_f32_16x16x32_bf16 v[54:57], v[150:153], v[182:185], v[54:57]
	s_waitcnt lgkmcnt(3)
	v_mfma_f32_16x16x32_bf16 v[46:49], v[146:149], v[170:173], v[46:49]
	v_mfma_f32_16x16x32_bf16 v[46:49], v[150:153], v[174:177], v[46:49]
	s_waitcnt lgkmcnt(1)
	v_mfma_f32_16x16x32_bf16 v[38:41], v[146:149], v[162:165], v[38:41]
	v_mfma_f32_16x16x32_bf16 v[38:41], v[150:153], v[166:169], v[38:41]
	v_mfma_f32_16x16x32_bf16 v[58:61], v[154:157], v[186:189], v[58:61]
	v_mfma_f32_16x16x32_bf16 v[58:61], v[158:161], v[190:193], v[58:61]
	v_mfma_f32_16x16x32_bf16 v[50:53], v[154:157], v[178:181], v[50:53]
	v_mfma_f32_16x16x32_bf16 v[50:53], v[158:161], v[182:185], v[50:53]
	v_mfma_f32_16x16x32_bf16 v[42:45], v[154:157], v[170:173], v[42:45]
	v_mfma_f32_16x16x32_bf16 v[42:45], v[158:161], v[174:177], v[42:45]
	s_waitcnt lgkmcnt(0)
	v_mfma_f32_16x16x32_bf16 v[34:37], v[154:157], v[162:165], v[34:37]
	v_mfma_f32_16x16x32_bf16 v[34:37], v[158:161], v[166:169], v[34:37]
	s_setprio 0
	s_setprio 1
	v_mfma_f32_16x16x32_bf16 v[30:33], v[130:133], v[186:189], v[30:33]
	v_mfma_f32_16x16x32_bf16 v[30:33], v[134:137], v[190:193], v[30:33]
	v_mfma_f32_16x16x32_bf16 v[22:25], v[130:133], v[178:181], v[22:25]
	v_mfma_f32_16x16x32_bf16 v[22:25], v[134:137], v[182:185], v[22:25]
	v_mfma_f32_16x16x32_bf16 v[14:17], v[130:133], v[170:173], v[14:17]
	v_mfma_f32_16x16x32_bf16 v[14:17], v[134:137], v[174:177], v[14:17]
	v_mfma_f32_16x16x32_bf16 v[6:9], v[130:133], v[162:165], v[6:9]
	v_mfma_f32_16x16x32_bf16 v[6:9], v[134:137], v[166:169], v[6:9]
	v_mfma_f32_16x16x32_bf16 v[26:29], v[138:141], v[186:189], v[26:29]
	v_mfma_f32_16x16x32_bf16 v[26:29], v[142:145], v[190:193], v[26:29]
	v_mfma_f32_16x16x32_bf16 v[18:21], v[138:141], v[178:181], v[18:21]
	v_mfma_f32_16x16x32_bf16 v[18:21], v[142:145], v[182:185], v[18:21]
	v_mfma_f32_16x16x32_bf16 v[10:13], v[138:141], v[170:173], v[10:13]
	v_mfma_f32_16x16x32_bf16 v[10:13], v[142:145], v[174:177], v[10:13]
	s_setprio 2
	s_barrier
	v_mfma_f32_16x16x32_bf16 v[2:5], v[138:141], v[162:165], v[2:5]
	v_mfma_f32_16x16x32_bf16 v[2:5], v[142:145], v[166:169], v[2:5]
	s_setprio 0
	s_nop 0
	v_add_u32_e32 v142, 0x18000, v207
	v_add_u32_e32 v158, 0x1c000, v207
	ds_read_b128 v[130:133], v142
	ds_read_b128 v[134:137], v142 offset:1024
	ds_read_b128 v[138:141], v142 offset:2048
	ds_read_b128 v[142:145], v142 offset:3072
	ds_read_b128 v[146:149], v158
	ds_read_b128 v[150:153], v158 offset:1024
	ds_read_b128 v[154:157], v158 offset:2048
	ds_read_b128 v[158:161], v158 offset:3072
	ds_read_b128 v[162:165], v208 offset:32768
	ds_read_b128 v[166:169], v208 offset:33792
	ds_read_b128 v[170:173], v208 offset:34816
	ds_read_b128 v[174:177], v208 offset:35840
	ds_read_b128 v[178:181], v208 offset:36864
	ds_read_b128 v[182:185], v208 offset:37888
	ds_read_b128 v[186:189], v208 offset:38912
	ds_read_b128 v[190:193], v208 offset:39936
	s_add_u32 s46, s46, 0x4000
	s_addc_u32 s47, s47, 0
	s_mov_b32 m0, s60
	s_nop 0
	global_load_lds_dwordx4 v202, s[46:47]
	s_add_u32 m0, s60, 0x2000
	s_nop 0
	global_load_lds_dwordx4 v203, s[46:47]
	s_waitcnt vmcnt(8)
	s_waitcnt lgkmcnt(0)
	s_setprio 1
	s_barrier
	v_mfma_f32_16x16x32_bf16 v[126:129], v[130:133], v[162:165], v[126:129]
	v_mfma_f32_16x16x32_bf16 v[126:129], v[134:137], v[166:169], v[126:129]
	s_waitcnt lgkmcnt(5)
	v_mfma_f32_16x16x32_bf16 v[118:121], v[130:133], v[170:173], v[118:121]
	v_mfma_f32_16x16x32_bf16 v[118:121], v[134:137], v[174:177], v[118:121]
	s_waitcnt lgkmcnt(3)
	v_mfma_f32_16x16x32_bf16 v[110:113], v[130:133], v[178:181], v[110:113]
	v_mfma_f32_16x16x32_bf16 v[110:113], v[134:137], v[182:185], v[110:113]
	s_waitcnt lgkmcnt(1)
	v_mfma_f32_16x16x32_bf16 v[102:105], v[130:133], v[186:189], v[102:105]
	v_mfma_f32_16x16x32_bf16 v[102:105], v[134:137], v[190:193], v[102:105]
	v_mfma_f32_16x16x32_bf16 v[122:125], v[138:141], v[162:165], v[122:125]
	v_mfma_f32_16x16x32_bf16 v[122:125], v[142:145], v[166:169], v[122:125]
	v_mfma_f32_16x16x32_bf16 v[114:117], v[138:141], v[170:173], v[114:117]
	v_mfma_f32_16x16x32_bf16 v[114:117], v[142:145], v[174:177], v[114:117]
	v_mfma_f32_16x16x32_bf16 v[106:109], v[138:141], v[178:181], v[106:109]
	v_mfma_f32_16x16x32_bf16 v[106:109], v[142:145], v[182:185], v[106:109]
	s_waitcnt lgkmcnt(0)
	v_mfma_f32_16x16x32_bf16 v[98:101], v[138:141], v[186:189], v[98:101]
	v_mfma_f32_16x16x32_bf16 v[98:101], v[142:145], v[190:193], v[98:101]
	s_setprio 0
	s_setprio 1
	v_mfma_f32_16x16x32_bf16 v[94:97], v[146:149], v[162:165], v[94:97]
	v_mfma_f32_16x16x32_bf16 v[94:97], v[150:153], v[166:169], v[94:97]
	v_mfma_f32_16x16x32_bf16 v[86:89], v[146:149], v[170:173], v[86:89]
	v_mfma_f32_16x16x32_bf16 v[86:89], v[150:153], v[174:177], v[86:89]
	v_mfma_f32_16x16x32_bf16 v[78:81], v[146:149], v[178:181], v[78:81]
	v_mfma_f32_16x16x32_bf16 v[78:81], v[150:153], v[182:185], v[78:81]
	v_mfma_f32_16x16x32_bf16 v[70:73], v[146:149], v[186:189], v[70:73]
	v_mfma_f32_16x16x32_bf16 v[70:73], v[150:153], v[190:193], v[70:73]
	v_mfma_f32_16x16x32_bf16 v[90:93], v[154:157], v[162:165], v[90:93]
	v_mfma_f32_16x16x32_bf16 v[90:93], v[158:161], v[166:169], v[90:93]
	v_mfma_f32_16x16x32_bf16 v[82:85], v[154:157], v[170:173], v[82:85]
	v_mfma_f32_16x16x32_bf16 v[82:85], v[158:161], v[174:177], v[82:85]
	v_mfma_f32_16x16x32_bf16 v[74:77], v[154:157], v[178:181], v[74:77]
	v_mfma_f32_16x16x32_bf16 v[74:77], v[158:161], v[182:185], v[74:77]
	s_setprio 2
	s_barrier
	v_mfma_f32_16x16x32_bf16 v[66:69], v[154:157], v[186:189], v[66:69]
	v_mfma_f32_16x16x32_bf16 v[66:69], v[158:161], v[190:193], v[66:69]
	s_setprio 0
	s_nop 0
	ds_read_b128 v[162:165], v208 offset:49152
	ds_read_b128 v[166:169], v208 offset:50176
	ds_read_b128 v[170:173], v208 offset:51200
	ds_read_b128 v[174:177], v208 offset:52224
	ds_read_b128 v[178:181], v208 offset:53248
	ds_read_b128 v[182:185], v208 offset:54272
	ds_read_b128 v[186:189], v208 offset:55296
	ds_read_b128 v[190:193], v208 offset:56320
	s_mov_b32 m0, s64
	s_nop 0
	global_load_lds_dwordx4 v202, s[50:51]
	s_add_u32 m0, s64, 0x2000
	s_nop 0
	global_load_lds_dwordx4 v203, s[50:51]
	s_add_u32 s42, s42, 0xc000
	s_addc_u32 s43, s43, 0
	s_mov_b32 m0, s66
	s_nop 0
	global_load_lds_dwordx4 v202, s[42:43]
	s_add_u32 m0, s66, 0x2000
	s_nop 0
	global_load_lds_dwordx4 v203, s[42:43]
	s_nop 0
	s_mov_b32 m0, s65
	s_nop 0
	global_load_lds_dwordx4 v202, s[48:49]
	s_add_u32 m0, s65, 0x2000
	s_nop 0
	global_load_lds_dwordx4 v203, s[48:49]
	s_waitcnt vmcnt(8)
	s_waitcnt lgkmcnt(0)
	s_setprio 1
	s_barrier
	v_mfma_f32_16x16x32_bf16 v[62:65], v[130:133], v[162:165], v[62:65]
	v_mfma_f32_16x16x32_bf16 v[62:65], v[134:137], v[166:169], v[62:65]
	s_waitcnt lgkmcnt(5)
	v_mfma_f32_16x16x32_bf16 v[54:57], v[130:133], v[170:173], v[54:57]
	v_mfma_f32_16x16x32_bf16 v[54:57], v[134:137], v[174:177], v[54:57]
	s_waitcnt lgkmcnt(3)
	v_mfma_f32_16x16x32_bf16 v[46:49], v[130:133], v[178:181], v[46:49]
	v_mfma_f32_16x16x32_bf16 v[46:49], v[134:137], v[182:185], v[46:49]
	s_waitcnt lgkmcnt(1)
	v_mfma_f32_16x16x32_bf16 v[38:41], v[130:133], v[186:189], v[38:41]
	v_mfma_f32_16x16x32_bf16 v[38:41], v[134:137], v[190:193], v[38:41]
	v_mfma_f32_16x16x32_bf16 v[58:61], v[138:141], v[162:165], v[58:61]
	v_mfma_f32_16x16x32_bf16 v[58:61], v[142:145], v[166:169], v[58:61]
	v_mfma_f32_16x16x32_bf16 v[50:53], v[138:141], v[170:173], v[50:53]
	v_mfma_f32_16x16x32_bf16 v[50:53], v[142:145], v[174:177], v[50:53]
	v_mfma_f32_16x16x32_bf16 v[42:45], v[138:141], v[178:181], v[42:45]
	v_mfma_f32_16x16x32_bf16 v[42:45], v[142:145], v[182:185], v[42:45]
	s_waitcnt lgkmcnt(0)
	v_mfma_f32_16x16x32_bf16 v[34:37], v[138:141], v[186:189], v[34:37]
	v_mfma_f32_16x16x32_bf16 v[34:37], v[142:145], v[190:193], v[34:37]
	s_setprio 0
	s_setprio 1
	v_mfma_f32_16x16x32_bf16 v[30:33], v[146:149], v[162:165], v[30:33]
	v_mfma_f32_16x16x32_bf16 v[30:33], v[150:153], v[166:169], v[30:33]
	v_mfma_f32_16x16x32_bf16 v[22:25], v[146:149], v[170:173], v[22:25]
	v_mfma_f32_16x16x32_bf16 v[22:25], v[150:153], v[174:177], v[22:25]
	v_mfma_f32_16x16x32_bf16 v[14:17], v[146:149], v[178:181], v[14:17]
	v_mfma_f32_16x16x32_bf16 v[14:17], v[150:153], v[182:185], v[14:17]
	v_mfma_f32_16x16x32_bf16 v[6:9], v[146:149], v[186:189], v[6:9]
	v_mfma_f32_16x16x32_bf16 v[6:9], v[150:153], v[190:193], v[6:9]
	v_mfma_f32_16x16x32_bf16 v[26:29], v[154:157], v[162:165], v[26:29]
	v_mfma_f32_16x16x32_bf16 v[26:29], v[158:161], v[166:169], v[26:29]
	v_mfma_f32_16x16x32_bf16 v[18:21], v[154:157], v[170:173], v[18:21]
	v_mfma_f32_16x16x32_bf16 v[18:21], v[158:161], v[174:177], v[18:21]
	v_mfma_f32_16x16x32_bf16 v[10:13], v[154:157], v[178:181], v[10:13]
	v_mfma_f32_16x16x32_bf16 v[10:13], v[158:161], v[182:185], v[10:13]
	s_setprio 2
	s_barrier
	v_mfma_f32_16x16x32_bf16 v[2:5], v[154:157], v[186:189], v[2:5]
	v_mfma_f32_16x16x32_bf16 v[2:5], v[158:161], v[190:193], v[2:5]
	s_setprio 0
	s_nop 0
	s_add_i32 s13, s77, 2
	s_cmp_gt_u32 s77, 5
	s_cbranch_scc1 .LBB0_1340
	s_mov_b32 s77, s13
	s_branch .LBB0_1317

.LBB0_1374:
	s_or_b64 exec, exec, s[40:41]
	s_add_u32 s76, s16, s6
	ds_read_b128 v[132:135], v168
	ds_read_b128 v[136:139], v168 offset:1024
	ds_read_b128 v[140:143], v168 offset:2048
	ds_read_b128 v[144:147], v168 offset:3072
	ds_read_b128 v[148:151], v169
	ds_read_b128 v[158:161], v169 offset:1024
	ds_read_b128 v[162:165], v169 offset:2048
	ds_read_b128 v[174:177], v169 offset:3072
	s_addc_u32 s77, s17, s7
	s_add_u32 s40, s76, 0x20000
	s_addc_u32 s41, s77, 0
	s_add_u32 s42, s71, s6
	s_addc_u32 s43, s72, s7
	s_cmp_eq_u32 s6, 0x20000
	s_cselect_b32 s48, s73, s40
	s_cselect_b32 s49, s27, s41
	s_cselect_b32 s41, s25, s43
	s_cselect_b32 s40, s74, s42
	s_add_u32 s42, s48, 0x8000
	s_addc_u32 s43, s49, 0
	s_add_u32 s46, s40, 0x8000
	s_addc_u32 s47, s41, 0
	ds_read_b128 v[178:181], v170
	ds_read_b128 v[182:185], v170 offset:1024
	ds_read_b128 v[186:189], v170 offset:2048
	ds_read_b128 v[190:193], v170 offset:3072
	ds_read_b128 v[198:201], v170 offset:4096
	ds_read_b128 v[204:207], v170 offset:5120
	ds_read_b128 v[212:215], v170 offset:6144
	ds_read_b128 v[216:219], v170 offset:7168
	s_add_u32 s76, s76, 0x1c000
	s_addc_u32 s77, s77, 0
	s_mov_b32 m0, s63
	s_nop 0
	global_load_lds_dwordx4 v202, s[76:77]
	s_add_u32 m0, s63, 0x2000
	s_nop 0
	global_load_lds_dwordx4 v203, s[76:77]
	s_waitcnt vmcnt(8)
	s_waitcnt lgkmcnt(0)
	s_setprio 1
	s_barrier
	v_mfma_f32_16x16x32_bf16 v[126:129], v[132:135], v[178:181], v[126:129]
	v_mfma_f32_16x16x32_bf16 v[126:129], v[136:139], v[182:185], v[126:129]
	s_waitcnt lgkmcnt(5)
	v_mfma_f32_16x16x32_bf16 v[110:113], v[132:135], v[186:189], v[110:113]
	v_mfma_f32_16x16x32_bf16 v[110:113], v[136:139], v[190:193], v[110:113]
	s_waitcnt lgkmcnt(3)
	v_mfma_f32_16x16x32_bf16 v[94:97], v[132:135], v[198:201], v[94:97]
	v_mfma_f32_16x16x32_bf16 v[94:97], v[136:139], v[204:207], v[94:97]
	s_waitcnt lgkmcnt(1)
	v_mfma_f32_16x16x32_bf16 v[78:81], v[132:135], v[212:215], v[78:81]
	v_mfma_f32_16x16x32_bf16 v[78:81], v[136:139], v[216:219], v[78:81]
	v_mfma_f32_16x16x32_bf16 v[122:125], v[140:143], v[178:181], v[122:125]
	v_mfma_f32_16x16x32_bf16 v[122:125], v[144:147], v[182:185], v[122:125]
	v_mfma_f32_16x16x32_bf16 v[106:109], v[140:143], v[186:189], v[106:109]
	v_mfma_f32_16x16x32_bf16 v[106:109], v[144:147], v[190:193], v[106:109]
	v_mfma_f32_16x16x32_bf16 v[90:93], v[140:143], v[198:201], v[90:93]
	v_mfma_f32_16x16x32_bf16 v[90:93], v[144:147], v[204:207], v[90:93]
	s_waitcnt lgkmcnt(0)
	v_mfma_f32_16x16x32_bf16 v[74:77], v[140:143], v[212:215], v[74:77]
	v_mfma_f32_16x16x32_bf16 v[74:77], v[144:147], v[216:219], v[74:77]
	s_setprio 0
	s_setprio 1
	v_mfma_f32_16x16x32_bf16 v[118:121], v[148:151], v[178:181], v[118:121]
	v_mfma_f32_16x16x32_bf16 v[118:121], v[158:161], v[182:185], v[118:121]
	v_mfma_f32_16x16x32_bf16 v[102:105], v[148:151], v[186:189], v[102:105]
	v_mfma_f32_16x16x32_bf16 v[102:105], v[158:161], v[190:193], v[102:105]
	v_mfma_f32_16x16x32_bf16 v[86:89], v[148:151], v[198:201], v[86:89]
	v_mfma_f32_16x16x32_bf16 v[86:89], v[158:161], v[204:207], v[86:89]
	v_mfma_f32_16x16x32_bf16 v[70:73], v[148:151], v[212:215], v[70:73]
	v_mfma_f32_16x16x32_bf16 v[70:73], v[158:161], v[216:219], v[70:73]
	v_mfma_f32_16x16x32_bf16 v[114:117], v[162:165], v[178:181], v[114:117]
	v_mfma_f32_16x16x32_bf16 v[114:117], v[174:177], v[182:185], v[114:117]
	v_mfma_f32_16x16x32_bf16 v[98:101], v[162:165], v[186:189], v[98:101]
	v_mfma_f32_16x16x32_bf16 v[98:101], v[174:177], v[190:193], v[98:101]
	v_mfma_f32_16x16x32_bf16 v[82:85], v[162:165], v[198:201], v[82:85]
	v_mfma_f32_16x16x32_bf16 v[82:85], v[174:177], v[204:207], v[82:85]
	s_setprio 2
	s_barrier
	v_mfma_f32_16x16x32_bf16 v[66:69], v[162:165], v[212:215], v[66:69]
	v_mfma_f32_16x16x32_bf16 v[66:69], v[174:177], v[216:219], v[66:69]
	s_setprio 0
	s_nop 0
	ds_read_b128 v[178:181], v170 offset:16384
	ds_read_b128 v[182:185], v170 offset:17408
	ds_read_b128 v[186:189], v170 offset:18432
	ds_read_b128 v[190:193], v170 offset:19456
	ds_read_b128 v[198:201], v170 offset:20480
	ds_read_b128 v[204:207], v170 offset:21504
	ds_read_b128 v[212:215], v170 offset:22528
	ds_read_b128 v[216:219], v170 offset:23552
	s_mov_b32 m0, s13
	s_nop 0
	global_load_lds_dwordx4 v202, s[40:41]
	s_add_u32 m0, s13, 0x2000
	s_nop 0
	global_load_lds_dwordx4 v203, s[40:41]
	s_add_u32 s76, s40, 0x4000
	s_addc_u32 s77, s41, 0
	s_mov_b32 m0, s55
	s_nop 0
	global_load_lds_dwordx4 v202, s[76:77]
	s_add_u32 m0, s55, 0x2000
	s_nop 0
	global_load_lds_dwordx4 v203, s[76:77]
	s_nop 0
	s_mov_b32 m0, s54
	s_nop 0
	global_load_lds_dwordx4 v202, s[48:49]
	s_add_u32 m0, s54, 0x2000
	s_nop 0
	global_load_lds_dwordx4 v203, s[48:49]
	s_waitcnt vmcnt(8)
	s_waitcnt lgkmcnt(0)
	s_setprio 1
	s_barrier
	v_mfma_f32_16x16x32_bf16 v[62:65], v[132:135], v[178:181], v[62:65]
	v_mfma_f32_16x16x32_bf16 v[62:65], v[136:139], v[182:185], v[62:65]
	s_waitcnt lgkmcnt(5)
	v_mfma_f32_16x16x32_bf16 v[46:49], v[132:135], v[186:189], v[46:49]
	v_mfma_f32_16x16x32_bf16 v[46:49], v[136:139], v[190:193], v[46:49]
	s_waitcnt lgkmcnt(3)
	v_mfma_f32_16x16x32_bf16 v[30:33], v[132:135], v[198:201], v[30:33]
	v_mfma_f32_16x16x32_bf16 v[30:33], v[136:139], v[204:207], v[30:33]
	s_waitcnt lgkmcnt(1)
	v_mfma_f32_16x16x32_bf16 v[14:17], v[132:135], v[212:215], v[14:17]
	v_mfma_f32_16x16x32_bf16 v[14:17], v[136:139], v[216:219], v[14:17]
	v_mfma_f32_16x16x32_bf16 v[58:61], v[140:143], v[178:181], v[58:61]
	v_mfma_f32_16x16x32_bf16 v[58:61], v[144:147], v[182:185], v[58:61]
	v_mfma_f32_16x16x32_bf16 v[42:45], v[140:143], v[186:189], v[42:45]
	v_mfma_f32_16x16x32_bf16 v[42:45], v[144:147], v[190:193], v[42:45]
	v_mfma_f32_16x16x32_bf16 v[26:29], v[140:143], v[198:201], v[26:29]
	v_mfma_f32_16x16x32_bf16 v[26:29], v[144:147], v[204:207], v[26:29]
	s_waitcnt lgkmcnt(0)
	v_mfma_f32_16x16x32_bf16 v[10:13], v[140:143], v[212:215], v[10:13]
	v_mfma_f32_16x16x32_bf16 v[10:13], v[144:147], v[216:219], v[10:13]
	s_setprio 0
	s_setprio 1
	v_mfma_f32_16x16x32_bf16 v[54:57], v[148:151], v[178:181], v[54:57]
	v_mfma_f32_16x16x32_bf16 v[54:57], v[158:161], v[182:185], v[54:57]
	v_mfma_f32_16x16x32_bf16 v[38:41], v[148:151], v[186:189], v[38:41]
	v_mfma_f32_16x16x32_bf16 v[38:41], v[158:161], v[190:193], v[38:41]
	v_mfma_f32_16x16x32_bf16 v[22:25], v[148:151], v[198:201], v[22:25]
	v_mfma_f32_16x16x32_bf16 v[22:25], v[158:161], v[204:207], v[22:25]
	v_mfma_f32_16x16x32_bf16 v[6:9], v[148:151], v[212:215], v[6:9]
	v_mfma_f32_16x16x32_bf16 v[6:9], v[158:161], v[216:219], v[6:9]
	v_mfma_f32_16x16x32_bf16 v[50:53], v[162:165], v[178:181], v[50:53]
	v_mfma_f32_16x16x32_bf16 v[50:53], v[174:177], v[182:185], v[50:53]
	v_mfma_f32_16x16x32_bf16 v[34:37], v[162:165], v[186:189], v[34:37]
	v_mfma_f32_16x16x32_bf16 v[34:37], v[174:177], v[190:193], v[34:37]
	v_mfma_f32_16x16x32_bf16 v[18:21], v[162:165], v[198:201], v[18:21]
	v_mfma_f32_16x16x32_bf16 v[18:21], v[174:177], v[204:207], v[18:21]
	s_setprio 2
	s_barrier
	v_mfma_f32_16x16x32_bf16 v[2:5], v[162:165], v[212:215], v[2:5]
	v_mfma_f32_16x16x32_bf16 v[2:5], v[174:177], v[216:219], v[2:5]
	s_setprio 0
	s_nop 0
	ds_read_b128 v[132:135], v171
	ds_read_b128 v[136:139], v171 offset:1024
	ds_read_b128 v[140:143], v171 offset:2048
	ds_read_b128 v[144:147], v171 offset:3072
	ds_read_b128 v[148:151], v172
	ds_read_b128 v[158:161], v172 offset:1024
	ds_read_b128 v[162:165], v172 offset:2048
	ds_read_b128 v[174:177], v172 offset:3072
	ds_read_b128 v[178:181], v170 offset:32768
	ds_read_b128 v[182:185], v170 offset:33792
	ds_read_b128 v[186:189], v170 offset:34816
	ds_read_b128 v[190:193], v170 offset:35840
	ds_read_b128 v[198:201], v170 offset:36864
	ds_read_b128 v[204:207], v170 offset:37888
	ds_read_b128 v[212:215], v170 offset:38912
	ds_read_b128 v[216:219], v170 offset:39936
	s_add_u32 s48, s48, 0x4000
	s_addc_u32 s49, s49, 0
	s_mov_b32 m0, s56
	s_nop 0
	global_load_lds_dwordx4 v202, s[48:49]
	s_add_u32 m0, s56, 0x2000
	s_nop 0
	global_load_lds_dwordx4 v203, s[48:49]
	s_waitcnt vmcnt(8)
	s_waitcnt lgkmcnt(0)
	s_setprio 1
	s_barrier
	v_mfma_f32_16x16x32_bf16 v[126:129], v[132:135], v[178:181], v[126:129]
	v_mfma_f32_16x16x32_bf16 v[126:129], v[136:139], v[182:185], v[126:129]
	s_waitcnt lgkmcnt(5)
	v_mfma_f32_16x16x32_bf16 v[110:113], v[132:135], v[186:189], v[110:113]
	v_mfma_f32_16x16x32_bf16 v[110:113], v[136:139], v[190:193], v[110:113]
	s_waitcnt lgkmcnt(3)
	v_mfma_f32_16x16x32_bf16 v[94:97], v[132:135], v[198:201], v[94:97]
	v_mfma_f32_16x16x32_bf16 v[94:97], v[136:139], v[204:207], v[94:97]
	s_waitcnt lgkmcnt(1)
	v_mfma_f32_16x16x32_bf16 v[78:81], v[132:135], v[212:215], v[78:81]
	v_mfma_f32_16x16x32_bf16 v[78:81], v[136:139], v[216:219], v[78:81]
	v_mfma_f32_16x16x32_bf16 v[122:125], v[140:143], v[178:181], v[122:125]
	v_mfma_f32_16x16x32_bf16 v[122:125], v[144:147], v[182:185], v[122:125]
	v_mfma_f32_16x16x32_bf16 v[106:109], v[140:143], v[186:189], v[106:109]
	v_mfma_f32_16x16x32_bf16 v[106:109], v[144:147], v[190:193], v[106:109]
	v_mfma_f32_16x16x32_bf16 v[90:93], v[140:143], v[198:201], v[90:93]
	v_mfma_f32_16x16x32_bf16 v[90:93], v[144:147], v[204:207], v[90:93]
	s_waitcnt lgkmcnt(0)
	v_mfma_f32_16x16x32_bf16 v[74:77], v[140:143], v[212:215], v[74:77]
	v_mfma_f32_16x16x32_bf16 v[74:77], v[144:147], v[216:219], v[74:77]
	s_setprio 0
	s_setprio 1
	v_mfma_f32_16x16x32_bf16 v[118:121], v[148:151], v[178:181], v[118:121]
	v_mfma_f32_16x16x32_bf16 v[118:121], v[158:161], v[182:185], v[118:121]
	v_mfma_f32_16x16x32_bf16 v[102:105], v[148:151], v[186:189], v[102:105]
	v_mfma_f32_16x16x32_bf16 v[102:105], v[158:161], v[190:193], v[102:105]
	v_mfma_f32_16x16x32_bf16 v[86:89], v[148:151], v[198:201], v[86:89]
	v_mfma_f32_16x16x32_bf16 v[86:89], v[158:161], v[204:207], v[86:89]
	v_mfma_f32_16x16x32_bf16 v[70:73], v[148:151], v[212:215], v[70:73]
	v_mfma_f32_16x16x32_bf16 v[70:73], v[158:161], v[216:219], v[70:73]
	v_mfma_f32_16x16x32_bf16 v[114:117], v[162:165], v[178:181], v[114:117]
	v_mfma_f32_16x16x32_bf16 v[114:117], v[174:177], v[182:185], v[114:117]
	v_mfma_f32_16x16x32_bf16 v[98:101], v[162:165], v[186:189], v[98:101]
	v_mfma_f32_16x16x32_bf16 v[98:101], v[174:177], v[190:193], v[98:101]
	v_mfma_f32_16x16x32_bf16 v[82:85], v[162:165], v[198:201], v[82:85]
	v_mfma_f32_16x16x32_bf16 v[82:85], v[174:177], v[204:207], v[82:85]
	s_setprio 2
	s_barrier
	v_mfma_f32_16x16x32_bf16 v[66:69], v[162:165], v[212:215], v[66:69]
	v_mfma_f32_16x16x32_bf16 v[66:69], v[174:177], v[216:219], v[66:69]
	s_setprio 0
	s_nop 0
	ds_read_b128 v[178:181], v170 offset:49152
	ds_read_b128 v[182:185], v170 offset:50176
	ds_read_b128 v[186:189], v170 offset:51200
	ds_read_b128 v[190:193], v170 offset:52224
	ds_read_b128 v[198:201], v170 offset:53248
	ds_read_b128 v[204:207], v170 offset:54272
	ds_read_b128 v[212:215], v170 offset:55296
	ds_read_b128 v[216:219], v170 offset:56320
	s_mov_b32 m0, s59
	s_nop 0
	global_load_lds_dwordx4 v202, s[46:47]
	s_add_u32 m0, s59, 0x2000
	s_nop 0
	global_load_lds_dwordx4 v203, s[46:47]
	s_add_u32 s40, s40, 0xc000
	s_addc_u32 s41, s41, 0
	s_mov_b32 m0, s62
	s_nop 0
	global_load_lds_dwordx4 v202, s[40:41]
	s_add_u32 m0, s62, 0x2000
	s_nop 0
	global_load_lds_dwordx4 v203, s[40:41]
	s_nop 0
	s_mov_b32 m0, s61
	s_nop 0
	global_load_lds_dwordx4 v202, s[42:43]
	s_add_u32 m0, s61, 0x2000
	s_nop 0
	global_load_lds_dwordx4 v203, s[42:43]
	s_waitcnt vmcnt(8)
	s_waitcnt lgkmcnt(0)
	s_setprio 1
	s_barrier
	v_mfma_f32_16x16x32_bf16 v[62:65], v[132:135], v[178:181], v[62:65]
	v_mfma_f32_16x16x32_bf16 v[62:65], v[136:139], v[182:185], v[62:65]
	s_waitcnt lgkmcnt(5)
	v_mfma_f32_16x16x32_bf16 v[46:49], v[132:135], v[186:189], v[46:49]
	v_mfma_f32_16x16x32_bf16 v[46:49], v[136:139], v[190:193], v[46:49]
	s_waitcnt lgkmcnt(3)
	v_mfma_f32_16x16x32_bf16 v[30:33], v[132:135], v[198:201], v[30:33]
	v_mfma_f32_16x16x32_bf16 v[30:33], v[136:139], v[204:207], v[30:33]
	s_waitcnt lgkmcnt(1)
	v_mfma_f32_16x16x32_bf16 v[14:17], v[132:135], v[212:215], v[14:17]
	v_mfma_f32_16x16x32_bf16 v[14:17], v[136:139], v[216:219], v[14:17]
	v_mfma_f32_16x16x32_bf16 v[58:61], v[140:143], v[178:181], v[58:61]
	v_mfma_f32_16x16x32_bf16 v[58:61], v[144:147], v[182:185], v[58:61]
	v_mfma_f32_16x16x32_bf16 v[42:45], v[140:143], v[186:189], v[42:45]
	v_mfma_f32_16x16x32_bf16 v[42:45], v[144:147], v[190:193], v[42:45]
	v_mfma_f32_16x16x32_bf16 v[26:29], v[140:143], v[198:201], v[26:29]
	v_mfma_f32_16x16x32_bf16 v[26:29], v[144:147], v[204:207], v[26:29]
	s_waitcnt lgkmcnt(0)
	v_mfma_f32_16x16x32_bf16 v[10:13], v[140:143], v[212:215], v[10:13]
	v_mfma_f32_16x16x32_bf16 v[10:13], v[144:147], v[216:219], v[10:13]
	s_setprio 0
	s_setprio 1
	v_mfma_f32_16x16x32_bf16 v[54:57], v[148:151], v[178:181], v[54:57]
	v_mfma_f32_16x16x32_bf16 v[54:57], v[158:161], v[182:185], v[54:57]
	v_mfma_f32_16x16x32_bf16 v[38:41], v[148:151], v[186:189], v[38:41]
	v_mfma_f32_16x16x32_bf16 v[38:41], v[158:161], v[190:193], v[38:41]
	v_mfma_f32_16x16x32_bf16 v[22:25], v[148:151], v[198:201], v[22:25]
	v_mfma_f32_16x16x32_bf16 v[22:25], v[158:161], v[204:207], v[22:25]
	v_mfma_f32_16x16x32_bf16 v[6:9], v[148:151], v[212:215], v[6:9]
	v_mfma_f32_16x16x32_bf16 v[6:9], v[158:161], v[216:219], v[6:9]
	v_mfma_f32_16x16x32_bf16 v[50:53], v[162:165], v[178:181], v[50:53]
	v_mfma_f32_16x16x32_bf16 v[50:53], v[174:177], v[182:185], v[50:53]
	v_mfma_f32_16x16x32_bf16 v[34:37], v[162:165], v[186:189], v[34:37]
	v_mfma_f32_16x16x32_bf16 v[34:37], v[174:177], v[190:193], v[34:37]
	v_mfma_f32_16x16x32_bf16 v[18:21], v[162:165], v[198:201], v[18:21]
	v_mfma_f32_16x16x32_bf16 v[18:21], v[174:177], v[204:207], v[18:21]
	s_setprio 2
	s_barrier
	v_mfma_f32_16x16x32_bf16 v[2:5], v[162:165], v[212:215], v[2:5]
	v_mfma_f32_16x16x32_bf16 v[2:5], v[174:177], v[216:219], v[2:5]
	s_setprio 0
	s_nop 0
	s_add_i32 s75, s75, 2
	s_add_u32 s6, s6, 0x10000
	s_addc_u32 s7, s7, 0
	s_cmp_gt_u32 s75, 5
	s_cbranch_scc1 .LBB0_1376
	v_mov_b32_e32 v131, v130
	s_branch .LBB0_1372

.LBB0_1519:
	s_add_i32 s26, s58, 2
	s_lshl_b64 s[54:55], s[26:27], 15
	s_add_u32 s17, s18, s54
	s_addc_u32 s59, s19, s55
	s_and_b64 s[50:51], s[12:13], exec
	s_cselect_b32 s51, s59, s41
	s_cselect_b32 s50, s17, s56
	s_add_u32 s17, s20, s54
	s_waitcnt vmcnt(8)
	s_addc_u32 s54, s21, s55
	s_waitcnt lgkmcnt(0)
	s_and_b64 s[12:13], s[12:13], exec
	s_cselect_b32 s13, s54, s39
	s_cselect_b32 s12, s17, s57
	s_setprio 1
	s_barrier
	v_mfma_f32_16x16x32_bf16 v[126:129], v[146:149], v[186:189], v[126:129]
	v_mfma_f32_16x16x32_bf16 v[126:129], v[150:153], v[190:193], v[126:129]
	s_waitcnt lgkmcnt(5)
	v_mfma_f32_16x16x32_bf16 v[118:121], v[146:149], v[178:181], v[118:121]
	v_mfma_f32_16x16x32_bf16 v[118:121], v[150:153], v[182:185], v[118:121]
	s_waitcnt lgkmcnt(3)
	v_mfma_f32_16x16x32_bf16 v[110:113], v[146:149], v[170:173], v[110:113]
	v_mfma_f32_16x16x32_bf16 v[110:113], v[150:153], v[174:177], v[110:113]
	s_waitcnt lgkmcnt(1)
	v_mfma_f32_16x16x32_bf16 v[102:105], v[146:149], v[162:165], v[102:105]
	v_mfma_f32_16x16x32_bf16 v[102:105], v[150:153], v[166:169], v[102:105]
	v_mfma_f32_16x16x32_bf16 v[122:125], v[154:157], v[186:189], v[122:125]
	v_mfma_f32_16x16x32_bf16 v[122:125], v[158:161], v[190:193], v[122:125]
	v_mfma_f32_16x16x32_bf16 v[114:117], v[154:157], v[178:181], v[114:117]
	v_mfma_f32_16x16x32_bf16 v[114:117], v[158:161], v[182:185], v[114:117]
	v_mfma_f32_16x16x32_bf16 v[106:109], v[154:157], v[170:173], v[106:109]
	v_mfma_f32_16x16x32_bf16 v[106:109], v[158:161], v[174:177], v[106:109]
	s_waitcnt lgkmcnt(0)
	v_mfma_f32_16x16x32_bf16 v[98:101], v[154:157], v[162:165], v[98:101]
	v_mfma_f32_16x16x32_bf16 v[98:101], v[158:161], v[166:169], v[98:101]
	s_setprio 0
	s_setprio 1
	v_mfma_f32_16x16x32_bf16 v[94:97], v[130:133], v[186:189], v[94:97]
	v_mfma_f32_16x16x32_bf16 v[94:97], v[134:137], v[190:193], v[94:97]
	v_mfma_f32_16x16x32_bf16 v[86:89], v[130:133], v[178:181], v[86:89]
	v_mfma_f32_16x16x32_bf16 v[86:89], v[134:137], v[182:185], v[86:89]
	v_mfma_f32_16x16x32_bf16 v[78:81], v[130:133], v[170:173], v[78:81]
	v_mfma_f32_16x16x32_bf16 v[78:81], v[134:137], v[174:177], v[78:81]
	v_mfma_f32_16x16x32_bf16 v[70:73], v[130:133], v[162:165], v[70:73]
	v_mfma_f32_16x16x32_bf16 v[70:73], v[134:137], v[166:169], v[70:73]
	v_mfma_f32_16x16x32_bf16 v[90:93], v[138:141], v[186:189], v[90:93]
	v_mfma_f32_16x16x32_bf16 v[90:93], v[142:145], v[190:193], v[90:93]
	v_mfma_f32_16x16x32_bf16 v[82:85], v[138:141], v[178:181], v[82:85]
	v_mfma_f32_16x16x32_bf16 v[82:85], v[142:145], v[182:185], v[82:85]
	v_mfma_f32_16x16x32_bf16 v[74:77], v[138:141], v[170:173], v[74:77]
	v_mfma_f32_16x16x32_bf16 v[74:77], v[142:145], v[174:177], v[74:77]
	s_setprio 2
	s_barrier
	v_mfma_f32_16x16x32_bf16 v[66:69], v[138:141], v[162:165], v[66:69]
	v_mfma_f32_16x16x32_bf16 v[66:69], v[142:145], v[166:169], v[66:69]
	s_setprio 0
	s_nop 0
	ds_read_b128 v[186:189], v217 offset:16384
	ds_read_b128 v[190:193], v217 offset:17408
	ds_read_b128 v[178:181], v217 offset:18432
	ds_read_b128 v[182:185], v217 offset:19456
	ds_read_b128 v[170:173], v217 offset:20480
	ds_read_b128 v[174:177], v217 offset:21504
	ds_read_b128 v[162:165], v217 offset:22528
	ds_read_b128 v[166:169], v217 offset:23552
	s_mov_b32 m0, s66
	s_nop 0
	global_load_lds_dwordx4 v195, s[12:13]
	s_add_u32 m0, s66, 0x2000
	s_nop 0
	global_load_lds_dwordx4 v212, s[12:13]
	s_add_u32 s54, s12, 0x4000
	s_addc_u32 s55, s13, 0
	s_mov_b32 m0, s67
	s_nop 0
	global_load_lds_dwordx4 v195, s[54:55]
	s_add_u32 m0, s67, 0x2000
	s_nop 0
	global_load_lds_dwordx4 v212, s[54:55]
	s_andn2_b64 vcc, exec, s[52:53]
	s_mov_b32 m0, s15
	s_nop 0
	global_load_lds_dwordx4 v195, s[50:51]
	s_add_u32 m0, s15, 0x2000
	s_nop 0
	global_load_lds_dwordx4 v212, s[50:51]
	s_cbranch_vccnz .LBB0_1521
	v_mov_b32_e32 v2, 0
	v_mov_b32_e32 v3, v2
	v_mov_b32_e32 v4, v2
	v_mov_b32_e32 v5, v2
	v_mov_b32_e32 v6, v2
	v_mov_b32_e32 v7, v2
	v_mov_b32_e32 v8, v2
	v_mov_b32_e32 v9, v2
	v_mov_b32_e32 v10, v2
	v_mov_b32_e32 v11, v2
	v_mov_b32_e32 v12, v2
	v_mov_b32_e32 v13, v2
	v_mov_b32_e32 v14, v2
	v_mov_b32_e32 v15, v2
	v_mov_b32_e32 v16, v2
	v_mov_b32_e32 v17, v2
	v_mov_b32_e32 v18, v2
	v_mov_b32_e32 v19, v2
	v_mov_b32_e32 v20, v2
	v_mov_b32_e32 v21, v2
	v_mov_b32_e32 v22, v2
	v_mov_b32_e32 v23, v2
	v_mov_b32_e32 v24, v2
	v_mov_b32_e32 v25, v2
	v_mov_b32_e32 v26, v2
	v_mov_b32_e32 v27, v2
	v_mov_b32_e32 v28, v2
	v_mov_b32_e32 v29, v2
	v_mov_b32_e32 v30, v2
	v_mov_b32_e32 v31, v2
	v_mov_b32_e32 v32, v2
	v_mov_b32_e32 v33, v2
	v_mov_b32_e32 v34, v2
	v_mov_b32_e32 v35, v2
	v_mov_b32_e32 v36, v2
	v_mov_b32_e32 v37, v2
	v_mov_b32_e32 v38, v2
	v_mov_b32_e32 v39, v2
	v_mov_b32_e32 v40, v2
	v_mov_b32_e32 v41, v2
	v_mov_b32_e32 v42, v2
	v_mov_b32_e32 v43, v2
	v_mov_b32_e32 v44, v2
	v_mov_b32_e32 v45, v2
	v_mov_b32_e32 v46, v2
	v_mov_b32_e32 v47, v2
	v_mov_b32_e32 v48, v2
	v_mov_b32_e32 v49, v2
	v_mov_b32_e32 v50, v2
	v_mov_b32_e32 v51, v2
	v_mov_b32_e32 v52, v2
	v_mov_b32_e32 v53, v2
	v_mov_b32_e32 v54, v2
	v_mov_b32_e32 v55, v2
	v_mov_b32_e32 v56, v2
	v_mov_b32_e32 v57, v2
	v_mov_b32_e32 v58, v2
	v_mov_b32_e32 v59, v2
	v_mov_b32_e32 v60, v2
	v_mov_b32_e32 v61, v2
	v_mov_b32_e32 v62, v2
	v_mov_b32_e32 v63, v2
	v_mov_b32_e32 v64, v2
	v_mov_b32_e32 v65, v2
.LBB0_1521:
	s_waitcnt vmcnt(8)
	s_add_u32 s52, s50, 0x8000
	s_waitcnt lgkmcnt(0)
	s_addc_u32 s53, s51, 0
	s_add_u32 s54, s12, 0x8000
	s_addc_u32 s55, s13, 0
	s_setprio 1
	s_barrier
	v_mfma_f32_16x16x32_bf16 v[62:65], v[146:149], v[186:189], v[62:65]
	v_mfma_f32_16x16x32_bf16 v[62:65], v[150:153], v[190:193], v[62:65]
	s_waitcnt lgkmcnt(5)
	v_mfma_f32_16x16x32_bf16 v[54:57], v[146:149], v[178:181], v[54:57]
	v_mfma_f32_16x16x32_bf16 v[54:57], v[150:153], v[182:185], v[54:57]
	s_waitcnt lgkmcnt(3)
	v_mfma_f32_16x16x32_bf16 v[46:49], v[146:149], v[170:173], v[46:49]
	v_mfma_f32_16x16x32_bf16 v[46:49], v[150:153], v[174:177], v[46:49]
	s_waitcnt lgkmcnt(1)
	v_mfma_f32_16x16x32_bf16 v[38:41], v[146:149], v[162:165], v[38:41]
	v_mfma_f32_16x16x32_bf16 v[38:41], v[150:153], v[166:169], v[38:41]
	v_mfma_f32_16x16x32_bf16 v[58:61], v[154:157], v[186:189], v[58:61]
	v_mfma_f32_16x16x32_bf16 v[58:61], v[158:161], v[190:193], v[58:61]
	v_mfma_f32_16x16x32_bf16 v[50:53], v[154:157], v[178:181], v[50:53]
	v_mfma_f32_16x16x32_bf16 v[50:53], v[158:161], v[182:185], v[50:53]
	v_mfma_f32_16x16x32_bf16 v[42:45], v[154:157], v[170:173], v[42:45]
	v_mfma_f32_16x16x32_bf16 v[42:45], v[158:161], v[174:177], v[42:45]
	s_waitcnt lgkmcnt(0)
	v_mfma_f32_16x16x32_bf16 v[34:37], v[154:157], v[162:165], v[34:37]
	v_mfma_f32_16x16x32_bf16 v[34:37], v[158:161], v[166:169], v[34:37]
	s_setprio 0
	s_setprio 1
	v_mfma_f32_16x16x32_bf16 v[30:33], v[130:133], v[186:189], v[30:33]
	v_mfma_f32_16x16x32_bf16 v[30:33], v[134:137], v[190:193], v[30:33]
	v_mfma_f32_16x16x32_bf16 v[22:25], v[130:133], v[178:181], v[22:25]
	v_mfma_f32_16x16x32_bf16 v[22:25], v[134:137], v[182:185], v[22:25]
	v_mfma_f32_16x16x32_bf16 v[14:17], v[130:133], v[170:173], v[14:17]
	v_mfma_f32_16x16x32_bf16 v[14:17], v[134:137], v[174:177], v[14:17]
	v_mfma_f32_16x16x32_bf16 v[6:9], v[130:133], v[162:165], v[6:9]
	v_mfma_f32_16x16x32_bf16 v[6:9], v[134:137], v[166:169], v[6:9]
	v_mfma_f32_16x16x32_bf16 v[26:29], v[138:141], v[186:189], v[26:29]
	v_mfma_f32_16x16x32_bf16 v[26:29], v[142:145], v[190:193], v[26:29]
	v_mfma_f32_16x16x32_bf16 v[18:21], v[138:141], v[178:181], v[18:21]
	v_mfma_f32_16x16x32_bf16 v[18:21], v[142:145], v[182:185], v[18:21]
	v_mfma_f32_16x16x32_bf16 v[10:13], v[138:141], v[170:173], v[10:13]
	v_mfma_f32_16x16x32_bf16 v[10:13], v[142:145], v[174:177], v[10:13]
	s_setprio 2
	s_barrier
	v_mfma_f32_16x16x32_bf16 v[2:5], v[138:141], v[162:165], v[2:5]
	v_mfma_f32_16x16x32_bf16 v[2:5], v[142:145], v[166:169], v[2:5]
	s_setprio 0
	s_nop 0
	v_add_u32_e32 v142, 0x18000, v216
	v_add_u32_e32 v158, 0x1c000, v216
	ds_read_b128 v[130:133], v142
	ds_read_b128 v[134:137], v142 offset:1024
	ds_read_b128 v[138:141], v142 offset:2048
	ds_read_b128 v[142:145], v142 offset:3072
	ds_read_b128 v[146:149], v158
	ds_read_b128 v[150:153], v158 offset:1024
	ds_read_b128 v[154:157], v158 offset:2048
	ds_read_b128 v[158:161], v158 offset:3072
	ds_read_b128 v[162:165], v217 offset:32768
	ds_read_b128 v[166:169], v217 offset:33792
	ds_read_b128 v[170:173], v217 offset:34816
	ds_read_b128 v[174:177], v217 offset:35840
	ds_read_b128 v[178:181], v217 offset:36864
	ds_read_b128 v[182:185], v217 offset:37888
	ds_read_b128 v[186:189], v217 offset:38912
	ds_read_b128 v[190:193], v217 offset:39936
	s_add_u32 s50, s50, 0x4000
	s_addc_u32 s51, s51, 0
	s_mov_b32 m0, s68
	s_nop 0
	global_load_lds_dwordx4 v195, s[50:51]
	s_add_u32 m0, s68, 0x2000
	s_nop 0
	global_load_lds_dwordx4 v212, s[50:51]
	s_waitcnt vmcnt(8)
	s_waitcnt lgkmcnt(0)
	s_setprio 1
	s_barrier
	v_mfma_f32_16x16x32_bf16 v[126:129], v[130:133], v[162:165], v[126:129]
	v_mfma_f32_16x16x32_bf16 v[126:129], v[134:137], v[166:169], v[126:129]
	s_waitcnt lgkmcnt(5)
	v_mfma_f32_16x16x32_bf16 v[118:121], v[130:133], v[170:173], v[118:121]
	v_mfma_f32_16x16x32_bf16 v[118:121], v[134:137], v[174:177], v[118:121]
	s_waitcnt lgkmcnt(3)
	v_mfma_f32_16x16x32_bf16 v[110:113], v[130:133], v[178:181], v[110:113]
	v_mfma_f32_16x16x32_bf16 v[110:113], v[134:137], v[182:185], v[110:113]
	s_waitcnt lgkmcnt(1)
	v_mfma_f32_16x16x32_bf16 v[102:105], v[130:133], v[186:189], v[102:105]
	v_mfma_f32_16x16x32_bf16 v[102:105], v[134:137], v[190:193], v[102:105]
	v_mfma_f32_16x16x32_bf16 v[122:125], v[138:141], v[162:165], v[122:125]
	v_mfma_f32_16x16x32_bf16 v[122:125], v[142:145], v[166:169], v[122:125]
	v_mfma_f32_16x16x32_bf16 v[114:117], v[138:141], v[170:173], v[114:117]
	v_mfma_f32_16x16x32_bf16 v[114:117], v[142:145], v[174:177], v[114:117]
	v_mfma_f32_16x16x32_bf16 v[106:109], v[138:141], v[178:181], v[106:109]
	v_mfma_f32_16x16x32_bf16 v[106:109], v[142:145], v[182:185], v[106:109]
	s_waitcnt lgkmcnt(0)
	v_mfma_f32_16x16x32_bf16 v[98:101], v[138:141], v[186:189], v[98:101]
	v_mfma_f32_16x16x32_bf16 v[98:101], v[142:145], v[190:193], v[98:101]
	s_setprio 0
	s_setprio 1
	v_mfma_f32_16x16x32_bf16 v[94:97], v[146:149], v[162:165], v[94:97]
	v_mfma_f32_16x16x32_bf16 v[94:97], v[150:153], v[166:169], v[94:97]
	v_mfma_f32_16x16x32_bf16 v[86:89], v[146:149], v[170:173], v[86:89]
	v_mfma_f32_16x16x32_bf16 v[86:89], v[150:153], v[174:177], v[86:89]
	v_mfma_f32_16x16x32_bf16 v[78:81], v[146:149], v[178:181], v[78:81]
	v_mfma_f32_16x16x32_bf16 v[78:81], v[150:153], v[182:185], v[78:81]
	v_mfma_f32_16x16x32_bf16 v[70:73], v[146:149], v[186:189], v[70:73]
	v_mfma_f32_16x16x32_bf16 v[70:73], v[150:153], v[190:193], v[70:73]
	v_mfma_f32_16x16x32_bf16 v[90:93], v[154:157], v[162:165], v[90:93]
	v_mfma_f32_16x16x32_bf16 v[90:93], v[158:161], v[166:169], v[90:93]
	v_mfma_f32_16x16x32_bf16 v[82:85], v[154:157], v[170:173], v[82:85]
	v_mfma_f32_16x16x32_bf16 v[82:85], v[158:161], v[174:177], v[82:85]
	v_mfma_f32_16x16x32_bf16 v[74:77], v[154:157], v[178:181], v[74:77]
	v_mfma_f32_16x16x32_bf16 v[74:77], v[158:161], v[182:185], v[74:77]
	s_setprio 2
	s_barrier
	v_mfma_f32_16x16x32_bf16 v[66:69], v[154:157], v[186:189], v[66:69]
	v_mfma_f32_16x16x32_bf16 v[66:69], v[158:161], v[190:193], v[66:69]
	s_setprio 0
	s_nop 0
	ds_read_b128 v[162:165], v217 offset:49152
	ds_read_b128 v[166:169], v217 offset:50176
	ds_read_b128 v[170:173], v217 offset:51200
	ds_read_b128 v[174:177], v217 offset:52224
	ds_read_b128 v[178:181], v217 offset:53248
	ds_read_b128 v[182:185], v217 offset:54272
	ds_read_b128 v[186:189], v217 offset:55296
	ds_read_b128 v[190:193], v217 offset:56320
	s_mov_b32 m0, s72
	s_nop 0
	global_load_lds_dwordx4 v195, s[54:55]
	s_add_u32 m0, s72, 0x2000
	s_nop 0
	global_load_lds_dwordx4 v212, s[54:55]
	s_add_u32 s12, s12, 0xc000
	s_addc_u32 s13, s13, 0
	s_mov_b32 m0, s74
	s_nop 0
	global_load_lds_dwordx4 v195, s[12:13]
	s_add_u32 m0, s74, 0x2000
	s_nop 0
	global_load_lds_dwordx4 v212, s[12:13]
	s_nop 0
	s_mov_b32 m0, s73
	s_nop 0
	global_load_lds_dwordx4 v195, s[52:53]
	s_add_u32 m0, s73, 0x2000
	s_nop 0
	global_load_lds_dwordx4 v212, s[52:53]
	s_waitcnt vmcnt(8)
	s_waitcnt lgkmcnt(0)
	s_setprio 1
	s_barrier
	v_mfma_f32_16x16x32_bf16 v[62:65], v[130:133], v[162:165], v[62:65]
	v_mfma_f32_16x16x32_bf16 v[62:65], v[134:137], v[166:169], v[62:65]
	s_waitcnt lgkmcnt(5)
	v_mfma_f32_16x16x32_bf16 v[54:57], v[130:133], v[170:173], v[54:57]
	v_mfma_f32_16x16x32_bf16 v[54:57], v[134:137], v[174:177], v[54:57]
	s_waitcnt lgkmcnt(3)
	v_mfma_f32_16x16x32_bf16 v[46:49], v[130:133], v[178:181], v[46:49]
	v_mfma_f32_16x16x32_bf16 v[46:49], v[134:137], v[182:185], v[46:49]
	s_waitcnt lgkmcnt(1)
	v_mfma_f32_16x16x32_bf16 v[38:41], v[130:133], v[186:189], v[38:41]
	v_mfma_f32_16x16x32_bf16 v[38:41], v[134:137], v[190:193], v[38:41]
	v_mfma_f32_16x16x32_bf16 v[58:61], v[138:141], v[162:165], v[58:61]
	v_mfma_f32_16x16x32_bf16 v[58:61], v[142:145], v[166:169], v[58:61]
	v_mfma_f32_16x16x32_bf16 v[50:53], v[138:141], v[170:173], v[50:53]
	v_mfma_f32_16x16x32_bf16 v[50:53], v[142:145], v[174:177], v[50:53]
	v_mfma_f32_16x16x32_bf16 v[42:45], v[138:141], v[178:181], v[42:45]
	v_mfma_f32_16x16x32_bf16 v[42:45], v[142:145], v[182:185], v[42:45]
	s_waitcnt lgkmcnt(0)
	v_mfma_f32_16x16x32_bf16 v[34:37], v[138:141], v[186:189], v[34:37]
	v_mfma_f32_16x16x32_bf16 v[34:37], v[142:145], v[190:193], v[34:37]
	s_setprio 0
	s_setprio 1
	v_mfma_f32_16x16x32_bf16 v[30:33], v[146:149], v[162:165], v[30:33]
	v_mfma_f32_16x16x32_bf16 v[30:33], v[150:153], v[166:169], v[30:33]
	v_mfma_f32_16x16x32_bf16 v[22:25], v[146:149], v[170:173], v[22:25]
	v_mfma_f32_16x16x32_bf16 v[22:25], v[150:153], v[174:177], v[22:25]
	v_mfma_f32_16x16x32_bf16 v[14:17], v[146:149], v[178:181], v[14:17]
	v_mfma_f32_16x16x32_bf16 v[14:17], v[150:153], v[182:185], v[14:17]
	v_mfma_f32_16x16x32_bf16 v[6:9], v[146:149], v[186:189], v[6:9]
	v_mfma_f32_16x16x32_bf16 v[6:9], v[150:153], v[190:193], v[6:9]
	v_mfma_f32_16x16x32_bf16 v[26:29], v[154:157], v[162:165], v[26:29]
	v_mfma_f32_16x16x32_bf16 v[26:29], v[158:161], v[166:169], v[26:29]
	v_mfma_f32_16x16x32_bf16 v[18:21], v[154:157], v[170:173], v[18:21]
	v_mfma_f32_16x16x32_bf16 v[18:21], v[158:161], v[174:177], v[18:21]
	v_mfma_f32_16x16x32_bf16 v[10:13], v[154:157], v[178:181], v[10:13]
	v_mfma_f32_16x16x32_bf16 v[10:13], v[158:161], v[182:185], v[10:13]
	s_setprio 2
	s_barrier
	v_mfma_f32_16x16x32_bf16 v[2:5], v[154:157], v[186:189], v[2:5]
	v_mfma_f32_16x16x32_bf16 v[2:5], v[158:161], v[190:193], v[2:5]
	s_setprio 0
	s_nop 0
	s_cmp_gt_u32 s58, 13
	s_cbranch_scc1 .LBB0_1523
	v_mov_b32_e32 v130, v198
	s_mov_b32 s58, s26
	s_branch .LBB0_1498

.LBB0_1712:
	s_add_u32 s52, s48, 0x10000
	s_addc_u32 s53, s49, 0
	s_and_b64 s[48:49], s[46:47], exec
	s_cselect_b32 s49, s53, s25
	s_cselect_b32 s48, s52, s75
	s_add_u32 s13, s16, s13
	s_addc_u32 s52, s17, 0
	s_add_u32 s13, s13, 0x10000
	s_waitcnt vmcnt(8)
	s_addc_u32 s52, s52, 0
	s_waitcnt lgkmcnt(0)
	s_and_b64 s[46:47], s[46:47], exec
	s_cselect_b32 s47, s52, s27
	s_cselect_b32 s46, s13, s76
	s_setprio 1
	s_barrier
	v_mfma_f32_16x16x32_bf16 v[126:129], v[146:149], v[186:189], v[126:129]
	v_mfma_f32_16x16x32_bf16 v[126:129], v[150:153], v[190:193], v[126:129]
	s_waitcnt lgkmcnt(5)
	v_mfma_f32_16x16x32_bf16 v[118:121], v[146:149], v[178:181], v[118:121]
	v_mfma_f32_16x16x32_bf16 v[118:121], v[150:153], v[182:185], v[118:121]
	s_waitcnt lgkmcnt(3)
	v_mfma_f32_16x16x32_bf16 v[110:113], v[146:149], v[170:173], v[110:113]
	v_mfma_f32_16x16x32_bf16 v[110:113], v[150:153], v[174:177], v[110:113]
	s_waitcnt lgkmcnt(1)
	v_mfma_f32_16x16x32_bf16 v[102:105], v[146:149], v[162:165], v[102:105]
	v_mfma_f32_16x16x32_bf16 v[102:105], v[150:153], v[166:169], v[102:105]
	v_mfma_f32_16x16x32_bf16 v[122:125], v[154:157], v[186:189], v[122:125]
	v_mfma_f32_16x16x32_bf16 v[122:125], v[158:161], v[190:193], v[122:125]
	v_mfma_f32_16x16x32_bf16 v[114:117], v[154:157], v[178:181], v[114:117]
	v_mfma_f32_16x16x32_bf16 v[114:117], v[158:161], v[182:185], v[114:117]
	v_mfma_f32_16x16x32_bf16 v[106:109], v[154:157], v[170:173], v[106:109]
	v_mfma_f32_16x16x32_bf16 v[106:109], v[158:161], v[174:177], v[106:109]
	s_waitcnt lgkmcnt(0)
	v_mfma_f32_16x16x32_bf16 v[98:101], v[154:157], v[162:165], v[98:101]
	v_mfma_f32_16x16x32_bf16 v[98:101], v[158:161], v[166:169], v[98:101]
	s_setprio 0
	s_setprio 1
	v_mfma_f32_16x16x32_bf16 v[94:97], v[130:133], v[186:189], v[94:97]
	v_mfma_f32_16x16x32_bf16 v[94:97], v[134:137], v[190:193], v[94:97]
	v_mfma_f32_16x16x32_bf16 v[86:89], v[130:133], v[178:181], v[86:89]
	v_mfma_f32_16x16x32_bf16 v[86:89], v[134:137], v[182:185], v[86:89]
	v_mfma_f32_16x16x32_bf16 v[78:81], v[130:133], v[170:173], v[78:81]
	v_mfma_f32_16x16x32_bf16 v[78:81], v[134:137], v[174:177], v[78:81]
	v_mfma_f32_16x16x32_bf16 v[70:73], v[130:133], v[162:165], v[70:73]
	v_mfma_f32_16x16x32_bf16 v[70:73], v[134:137], v[166:169], v[70:73]
	v_mfma_f32_16x16x32_bf16 v[90:93], v[138:141], v[186:189], v[90:93]
	v_mfma_f32_16x16x32_bf16 v[90:93], v[142:145], v[190:193], v[90:93]
	v_mfma_f32_16x16x32_bf16 v[82:85], v[138:141], v[178:181], v[82:85]
	v_mfma_f32_16x16x32_bf16 v[82:85], v[142:145], v[182:185], v[82:85]
	v_mfma_f32_16x16x32_bf16 v[74:77], v[138:141], v[170:173], v[74:77]
	v_mfma_f32_16x16x32_bf16 v[74:77], v[142:145], v[174:177], v[74:77]
	s_setprio 2
	s_barrier
	v_mfma_f32_16x16x32_bf16 v[66:69], v[138:141], v[162:165], v[66:69]
	v_mfma_f32_16x16x32_bf16 v[66:69], v[142:145], v[166:169], v[66:69]
	s_setprio 0
	s_nop 0
	ds_read_b128 v[186:189], v209 offset:16384
	ds_read_b128 v[190:193], v209 offset:17408
	ds_read_b128 v[178:181], v209 offset:18432
	ds_read_b128 v[182:185], v209 offset:19456
	ds_read_b128 v[170:173], v209 offset:20480
	ds_read_b128 v[174:177], v209 offset:21504
	ds_read_b128 v[162:165], v209 offset:22528
	ds_read_b128 v[166:169], v209 offset:23552
	s_mov_b32 m0, s58
	s_nop 0
	global_load_lds_dwordx4 v195, s[46:47]
	s_add_u32 m0, s58, 0x2000
	s_nop 0
	global_load_lds_dwordx4 v203, s[46:47]
	s_add_u32 s52, s46, 0x4000
	s_addc_u32 s53, s47, 0
	s_mov_b32 m0, s59
	s_nop 0
	global_load_lds_dwordx4 v195, s[52:53]
	s_add_u32 m0, s59, 0x2000
	s_nop 0
	global_load_lds_dwordx4 v203, s[52:53]
	s_andn2_b64 vcc, exec, s[50:51]
	s_mov_b32 m0, s11
	s_nop 0
	global_load_lds_dwordx4 v195, s[48:49]
	s_add_u32 m0, s11, 0x2000
	s_nop 0
	global_load_lds_dwordx4 v203, s[48:49]
	s_cbranch_vccnz .LBB0_1714
	v_mov_b32_e32 v2, 0
	v_mov_b32_e32 v3, v2
	v_mov_b32_e32 v4, v2
	v_mov_b32_e32 v5, v2
	v_mov_b32_e32 v6, v2
	v_mov_b32_e32 v7, v2
	v_mov_b32_e32 v8, v2
	v_mov_b32_e32 v9, v2
	v_mov_b32_e32 v10, v2
	v_mov_b32_e32 v11, v2
	v_mov_b32_e32 v12, v2
	v_mov_b32_e32 v13, v2
	v_mov_b32_e32 v14, v2
	v_mov_b32_e32 v15, v2
	v_mov_b32_e32 v16, v2
	v_mov_b32_e32 v17, v2
	v_mov_b32_e32 v18, v2
	v_mov_b32_e32 v19, v2
	v_mov_b32_e32 v20, v2
	v_mov_b32_e32 v21, v2
	v_mov_b32_e32 v22, v2
	v_mov_b32_e32 v23, v2
	v_mov_b32_e32 v24, v2
	v_mov_b32_e32 v25, v2
	v_mov_b32_e32 v26, v2
	v_mov_b32_e32 v27, v2
	v_mov_b32_e32 v28, v2
	v_mov_b32_e32 v29, v2
	v_mov_b32_e32 v30, v2
	v_mov_b32_e32 v31, v2
	v_mov_b32_e32 v32, v2
	v_mov_b32_e32 v33, v2
	v_mov_b32_e32 v34, v2
	v_mov_b32_e32 v35, v2
	v_mov_b32_e32 v36, v2
	v_mov_b32_e32 v37, v2
	v_mov_b32_e32 v38, v2
	v_mov_b32_e32 v39, v2
	v_mov_b32_e32 v40, v2
	v_mov_b32_e32 v41, v2
	v_mov_b32_e32 v42, v2
	v_mov_b32_e32 v43, v2
	v_mov_b32_e32 v44, v2
	v_mov_b32_e32 v45, v2
	v_mov_b32_e32 v46, v2
	v_mov_b32_e32 v47, v2
	v_mov_b32_e32 v48, v2
	v_mov_b32_e32 v49, v2
	v_mov_b32_e32 v50, v2
	v_mov_b32_e32 v51, v2
	v_mov_b32_e32 v52, v2
	v_mov_b32_e32 v53, v2
	v_mov_b32_e32 v54, v2
	v_mov_b32_e32 v55, v2
	v_mov_b32_e32 v56, v2
	v_mov_b32_e32 v57, v2
	v_mov_b32_e32 v58, v2
	v_mov_b32_e32 v59, v2
	v_mov_b32_e32 v60, v2
	v_mov_b32_e32 v61, v2
	v_mov_b32_e32 v62, v2
	v_mov_b32_e32 v63, v2
	v_mov_b32_e32 v64, v2
	v_mov_b32_e32 v65, v2
.LBB0_1714:
	s_waitcnt vmcnt(8)
	s_add_u32 s50, s48, 0x8000
	s_waitcnt lgkmcnt(0)
	s_addc_u32 s51, s49, 0
	s_add_u32 s52, s46, 0x8000
	s_addc_u32 s53, s47, 0
	s_setprio 1
	s_barrier
	v_mfma_f32_16x16x32_bf16 v[62:65], v[146:149], v[186:189], v[62:65]
	v_mfma_f32_16x16x32_bf16 v[62:65], v[150:153], v[190:193], v[62:65]
	s_waitcnt lgkmcnt(5)
	v_mfma_f32_16x16x32_bf16 v[54:57], v[146:149], v[178:181], v[54:57]
	v_mfma_f32_16x16x32_bf16 v[54:57], v[150:153], v[182:185], v[54:57]
	s_waitcnt lgkmcnt(3)
	v_mfma_f32_16x16x32_bf16 v[46:49], v[146:149], v[170:173], v[46:49]
	v_mfma_f32_16x16x32_bf16 v[46:49], v[150:153], v[174:177], v[46:49]
	s_waitcnt lgkmcnt(1)
	v_mfma_f32_16x16x32_bf16 v[38:41], v[146:149], v[162:165], v[38:41]
	v_mfma_f32_16x16x32_bf16 v[38:41], v[150:153], v[166:169], v[38:41]
	v_mfma_f32_16x16x32_bf16 v[58:61], v[154:157], v[186:189], v[58:61]
	v_mfma_f32_16x16x32_bf16 v[58:61], v[158:161], v[190:193], v[58:61]
	v_mfma_f32_16x16x32_bf16 v[50:53], v[154:157], v[178:181], v[50:53]
	v_mfma_f32_16x16x32_bf16 v[50:53], v[158:161], v[182:185], v[50:53]
	v_mfma_f32_16x16x32_bf16 v[42:45], v[154:157], v[170:173], v[42:45]
	v_mfma_f32_16x16x32_bf16 v[42:45], v[158:161], v[174:177], v[42:45]
	s_waitcnt lgkmcnt(0)
	v_mfma_f32_16x16x32_bf16 v[34:37], v[154:157], v[162:165], v[34:37]
	v_mfma_f32_16x16x32_bf16 v[34:37], v[158:161], v[166:169], v[34:37]
	s_setprio 0
	s_setprio 1
	v_mfma_f32_16x16x32_bf16 v[30:33], v[130:133], v[186:189], v[30:33]
	v_mfma_f32_16x16x32_bf16 v[30:33], v[134:137], v[190:193], v[30:33]
	v_mfma_f32_16x16x32_bf16 v[22:25], v[130:133], v[178:181], v[22:25]
	v_mfma_f32_16x16x32_bf16 v[22:25], v[134:137], v[182:185], v[22:25]
	v_mfma_f32_16x16x32_bf16 v[14:17], v[130:133], v[170:173], v[14:17]
	v_mfma_f32_16x16x32_bf16 v[14:17], v[134:137], v[174:177], v[14:17]
	v_mfma_f32_16x16x32_bf16 v[6:9], v[130:133], v[162:165], v[6:9]
	v_mfma_f32_16x16x32_bf16 v[6:9], v[134:137], v[166:169], v[6:9]
	v_mfma_f32_16x16x32_bf16 v[26:29], v[138:141], v[186:189], v[26:29]
	v_mfma_f32_16x16x32_bf16 v[26:29], v[142:145], v[190:193], v[26:29]
	v_mfma_f32_16x16x32_bf16 v[18:21], v[138:141], v[178:181], v[18:21]
	v_mfma_f32_16x16x32_bf16 v[18:21], v[142:145], v[182:185], v[18:21]
	v_mfma_f32_16x16x32_bf16 v[10:13], v[138:141], v[170:173], v[10:13]
	v_mfma_f32_16x16x32_bf16 v[10:13], v[142:145], v[174:177], v[10:13]
	s_setprio 2
	s_barrier
	v_mfma_f32_16x16x32_bf16 v[2:5], v[138:141], v[162:165], v[2:5]
	v_mfma_f32_16x16x32_bf16 v[2:5], v[142:145], v[166:169], v[2:5]
	s_setprio 0
	s_nop 0
	v_add_u32_e32 v142, 0x18000, v208
	v_add_u32_e32 v158, 0x1c000, v208
	ds_read_b128 v[130:133], v142
	ds_read_b128 v[134:137], v142 offset:1024
	ds_read_b128 v[138:141], v142 offset:2048
	ds_read_b128 v[142:145], v142 offset:3072
	ds_read_b128 v[146:149], v158
	ds_read_b128 v[150:153], v158 offset:1024
	ds_read_b128 v[154:157], v158 offset:2048
	ds_read_b128 v[158:161], v158 offset:3072
	ds_read_b128 v[162:165], v209 offset:32768
	ds_read_b128 v[166:169], v209 offset:33792
	ds_read_b128 v[170:173], v209 offset:34816
	ds_read_b128 v[174:177], v209 offset:35840
	ds_read_b128 v[178:181], v209 offset:36864
	ds_read_b128 v[182:185], v209 offset:37888
	ds_read_b128 v[186:189], v209 offset:38912
	ds_read_b128 v[190:193], v209 offset:39936
	s_add_u32 s48, s48, 0x4000
	s_addc_u32 s49, s49, 0
	s_mov_b32 m0, s60
	s_nop 0
	global_load_lds_dwordx4 v195, s[48:49]
	s_add_u32 m0, s60, 0x2000
	s_nop 0
	global_load_lds_dwordx4 v203, s[48:49]
	s_waitcnt vmcnt(8)
	s_waitcnt lgkmcnt(0)
	s_setprio 1
	s_barrier
	v_mfma_f32_16x16x32_bf16 v[126:129], v[130:133], v[162:165], v[126:129]
	v_mfma_f32_16x16x32_bf16 v[126:129], v[134:137], v[166:169], v[126:129]
	s_waitcnt lgkmcnt(5)
	v_mfma_f32_16x16x32_bf16 v[118:121], v[130:133], v[170:173], v[118:121]
	v_mfma_f32_16x16x32_bf16 v[118:121], v[134:137], v[174:177], v[118:121]
	s_waitcnt lgkmcnt(3)
	v_mfma_f32_16x16x32_bf16 v[110:113], v[130:133], v[178:181], v[110:113]
	v_mfma_f32_16x16x32_bf16 v[110:113], v[134:137], v[182:185], v[110:113]
	s_waitcnt lgkmcnt(1)
	v_mfma_f32_16x16x32_bf16 v[102:105], v[130:133], v[186:189], v[102:105]
	v_mfma_f32_16x16x32_bf16 v[102:105], v[134:137], v[190:193], v[102:105]
	v_mfma_f32_16x16x32_bf16 v[122:125], v[138:141], v[162:165], v[122:125]
	v_mfma_f32_16x16x32_bf16 v[122:125], v[142:145], v[166:169], v[122:125]
	v_mfma_f32_16x16x32_bf16 v[114:117], v[138:141], v[170:173], v[114:117]
	v_mfma_f32_16x16x32_bf16 v[114:117], v[142:145], v[174:177], v[114:117]
	v_mfma_f32_16x16x32_bf16 v[106:109], v[138:141], v[178:181], v[106:109]
	v_mfma_f32_16x16x32_bf16 v[106:109], v[142:145], v[182:185], v[106:109]
	s_waitcnt lgkmcnt(0)
	v_mfma_f32_16x16x32_bf16 v[98:101], v[138:141], v[186:189], v[98:101]
	v_mfma_f32_16x16x32_bf16 v[98:101], v[142:145], v[190:193], v[98:101]
	s_setprio 0
	s_setprio 1
	v_mfma_f32_16x16x32_bf16 v[94:97], v[146:149], v[162:165], v[94:97]
	v_mfma_f32_16x16x32_bf16 v[94:97], v[150:153], v[166:169], v[94:97]
	v_mfma_f32_16x16x32_bf16 v[86:89], v[146:149], v[170:173], v[86:89]
	v_mfma_f32_16x16x32_bf16 v[86:89], v[150:153], v[174:177], v[86:89]
	v_mfma_f32_16x16x32_bf16 v[78:81], v[146:149], v[178:181], v[78:81]
	v_mfma_f32_16x16x32_bf16 v[78:81], v[150:153], v[182:185], v[78:81]
	v_mfma_f32_16x16x32_bf16 v[70:73], v[146:149], v[186:189], v[70:73]
	v_mfma_f32_16x16x32_bf16 v[70:73], v[150:153], v[190:193], v[70:73]
	v_mfma_f32_16x16x32_bf16 v[90:93], v[154:157], v[162:165], v[90:93]
	v_mfma_f32_16x16x32_bf16 v[90:93], v[158:161], v[166:169], v[90:93]
	v_mfma_f32_16x16x32_bf16 v[82:85], v[154:157], v[170:173], v[82:85]
	v_mfma_f32_16x16x32_bf16 v[82:85], v[158:161], v[174:177], v[82:85]
	v_mfma_f32_16x16x32_bf16 v[74:77], v[154:157], v[178:181], v[74:77]
	v_mfma_f32_16x16x32_bf16 v[74:77], v[158:161], v[182:185], v[74:77]
	s_setprio 2
	s_barrier
	v_mfma_f32_16x16x32_bf16 v[66:69], v[154:157], v[186:189], v[66:69]
	v_mfma_f32_16x16x32_bf16 v[66:69], v[158:161], v[190:193], v[66:69]
	s_setprio 0
	s_nop 0
	ds_read_b128 v[162:165], v209 offset:49152
	ds_read_b128 v[166:169], v209 offset:50176
	ds_read_b128 v[170:173], v209 offset:51200
	ds_read_b128 v[174:177], v209 offset:52224
	ds_read_b128 v[178:181], v209 offset:53248
	ds_read_b128 v[182:185], v209 offset:54272
	ds_read_b128 v[186:189], v209 offset:55296
	ds_read_b128 v[190:193], v209 offset:56320
	s_mov_b32 m0, s64
	s_nop 0
	global_load_lds_dwordx4 v195, s[52:53]
	s_add_u32 m0, s64, 0x2000
	s_nop 0
	global_load_lds_dwordx4 v203, s[52:53]
	s_add_u32 s46, s46, 0xc000
	s_addc_u32 s47, s47, 0
	s_mov_b32 m0, s66
	s_nop 0
	global_load_lds_dwordx4 v195, s[46:47]
	s_add_u32 m0, s66, 0x2000
	s_nop 0
	global_load_lds_dwordx4 v203, s[46:47]
	s_nop 0
	s_mov_b32 m0, s65
	s_nop 0
	global_load_lds_dwordx4 v195, s[50:51]
	s_add_u32 m0, s65, 0x2000
	s_nop 0
	global_load_lds_dwordx4 v203, s[50:51]
	s_waitcnt vmcnt(8)
	s_waitcnt lgkmcnt(0)
	s_setprio 1
	s_barrier
	v_mfma_f32_16x16x32_bf16 v[62:65], v[130:133], v[162:165], v[62:65]
	v_mfma_f32_16x16x32_bf16 v[62:65], v[134:137], v[166:169], v[62:65]
	s_waitcnt lgkmcnt(5)
	v_mfma_f32_16x16x32_bf16 v[54:57], v[130:133], v[170:173], v[54:57]
	v_mfma_f32_16x16x32_bf16 v[54:57], v[134:137], v[174:177], v[54:57]
	s_waitcnt lgkmcnt(3)
	v_mfma_f32_16x16x32_bf16 v[46:49], v[130:133], v[178:181], v[46:49]
	v_mfma_f32_16x16x32_bf16 v[46:49], v[134:137], v[182:185], v[46:49]
	s_waitcnt lgkmcnt(1)
	v_mfma_f32_16x16x32_bf16 v[38:41], v[130:133], v[186:189], v[38:41]
	v_mfma_f32_16x16x32_bf16 v[38:41], v[134:137], v[190:193], v[38:41]
	v_mfma_f32_16x16x32_bf16 v[58:61], v[138:141], v[162:165], v[58:61]
	v_mfma_f32_16x16x32_bf16 v[58:61], v[142:145], v[166:169], v[58:61]
	v_mfma_f32_16x16x32_bf16 v[50:53], v[138:141], v[170:173], v[50:53]
	v_mfma_f32_16x16x32_bf16 v[50:53], v[142:145], v[174:177], v[50:53]
	v_mfma_f32_16x16x32_bf16 v[42:45], v[138:141], v[178:181], v[42:45]
	v_mfma_f32_16x16x32_bf16 v[42:45], v[142:145], v[182:185], v[42:45]
	s_waitcnt lgkmcnt(0)
	v_mfma_f32_16x16x32_bf16 v[34:37], v[138:141], v[186:189], v[34:37]
	v_mfma_f32_16x16x32_bf16 v[34:37], v[142:145], v[190:193], v[34:37]
	s_setprio 0
	s_setprio 1
	v_mfma_f32_16x16x32_bf16 v[30:33], v[146:149], v[162:165], v[30:33]
	v_mfma_f32_16x16x32_bf16 v[30:33], v[150:153], v[166:169], v[30:33]
	v_mfma_f32_16x16x32_bf16 v[22:25], v[146:149], v[170:173], v[22:25]
	v_mfma_f32_16x16x32_bf16 v[22:25], v[150:153], v[174:177], v[22:25]
	v_mfma_f32_16x16x32_bf16 v[14:17], v[146:149], v[178:181], v[14:17]
	v_mfma_f32_16x16x32_bf16 v[14:17], v[150:153], v[182:185], v[14:17]
	v_mfma_f32_16x16x32_bf16 v[6:9], v[146:149], v[186:189], v[6:9]
	v_mfma_f32_16x16x32_bf16 v[6:9], v[150:153], v[190:193], v[6:9]
	v_mfma_f32_16x16x32_bf16 v[26:29], v[154:157], v[162:165], v[26:29]
	v_mfma_f32_16x16x32_bf16 v[26:29], v[158:161], v[166:169], v[26:29]
	v_mfma_f32_16x16x32_bf16 v[18:21], v[154:157], v[170:173], v[18:21]
	v_mfma_f32_16x16x32_bf16 v[18:21], v[158:161], v[174:177], v[18:21]
	v_mfma_f32_16x16x32_bf16 v[10:13], v[154:157], v[178:181], v[10:13]
	v_mfma_f32_16x16x32_bf16 v[10:13], v[158:161], v[182:185], v[10:13]
	s_setprio 2
	s_barrier
	v_mfma_f32_16x16x32_bf16 v[2:5], v[154:157], v[186:189], v[2:5]
	v_mfma_f32_16x16x32_bf16 v[2:5], v[158:161], v[190:193], v[2:5]
	s_setprio 0
	s_nop 0
	s_add_i32 s13, s77, 2
	s_cmp_gt_u32 s77, 13
	s_cbranch_scc1 .LBB0_1716
	s_mov_b32 s77, s13
	s_branch .LBB0_1693

.LBB0_1919:
	s_or_b64 exec, exec, s[10:11]
	s_add_u32 s50, s16, s6
	ds_read_b128 v[134:137], v201
	ds_read_b128 v[138:141], v201 offset:1024
	ds_read_b128 v[142:145], v201 offset:2048
	ds_read_b128 v[146:149], v201 offset:3072
	ds_read_b128 v[150:153], v202
	ds_read_b128 v[154:157], v202 offset:1024
	ds_read_b128 v[162:165], v202 offset:2048
	ds_read_b128 v[166:169], v202 offset:3072
	s_addc_u32 s51, s17, s7
	s_add_u32 s10, s50, 0x20000
	s_addc_u32 s11, s51, 0
	s_add_u32 s42, s75, s6
	s_addc_u32 s43, s76, s7
	s_cmp_eq_u32 s6, 0x60000
	s_cselect_b32 s46, s29, s10
	s_cselect_b32 s47, s20, s11
	s_cselect_b32 s11, s27, s43
	s_cselect_b32 s10, s48, s42
	s_add_u32 s42, s46, 0x8000
	s_addc_u32 s43, s47, 0
	s_add_u32 s44, s10, 0x8000
	s_addc_u32 s45, s11, 0
	ds_read_b128 v[170:173], v203
	ds_read_b128 v[174:177], v203 offset:1024
	ds_read_b128 v[178:181], v203 offset:2048
	ds_read_b128 v[182:185], v203 offset:3072
	ds_read_b128 v[186:189], v203 offset:4096
	ds_read_b128 v[190:193], v203 offset:5120
	ds_read_b128 v[212:215], v203 offset:6144
	ds_read_b128 v[216:219], v203 offset:7168
	s_add_u32 s50, s50, 0x1c000
	s_addc_u32 s51, s51, 0
	s_mov_b32 m0, s65
	s_nop 0
	global_load_lds_dwordx4 v195, s[50:51]
	s_add_u32 m0, s65, 0x2000
	s_nop 0
	global_load_lds_dwordx4 v197, s[50:51]
	s_waitcnt vmcnt(8)
	s_waitcnt lgkmcnt(0)
	s_setprio 1
	s_barrier
	v_mfma_f32_16x16x32_bf16 v[130:133], v[134:137], v[170:173], v[130:133]
	v_mfma_f32_16x16x32_bf16 v[126:129], v[142:145], v[170:173], v[126:129]
	s_waitcnt lgkmcnt(5)
	v_mfma_f32_16x16x32_bf16 v[110:113], v[134:137], v[178:181], v[110:113]
	v_mfma_f32_16x16x32_bf16 v[106:109], v[142:145], v[178:181], v[106:109]
	s_waitcnt lgkmcnt(3)
	v_mfma_f32_16x16x32_bf16 v[94:97], v[134:137], v[186:189], v[94:97]
	v_mfma_f32_16x16x32_bf16 v[90:93], v[142:145], v[186:189], v[90:93]
	s_waitcnt lgkmcnt(1)
	v_mfma_f32_16x16x32_bf16 v[78:81], v[134:137], v[212:215], v[78:81]
	v_mfma_f32_16x16x32_bf16 v[74:77], v[142:145], v[212:215], v[74:77]
	v_mfma_f32_16x16x32_bf16 v[130:133], v[138:141], v[174:177], v[130:133]
	v_mfma_f32_16x16x32_bf16 v[126:129], v[146:149], v[174:177], v[126:129]
	v_mfma_f32_16x16x32_bf16 v[110:113], v[138:141], v[182:185], v[110:113]
	v_mfma_f32_16x16x32_bf16 v[106:109], v[146:149], v[182:185], v[106:109]
	v_mfma_f32_16x16x32_bf16 v[94:97], v[138:141], v[190:193], v[94:97]
	v_mfma_f32_16x16x32_bf16 v[90:93], v[146:149], v[190:193], v[90:93]
	s_waitcnt lgkmcnt(0)
	v_mfma_f32_16x16x32_bf16 v[78:81], v[138:141], v[216:219], v[78:81]
	v_mfma_f32_16x16x32_bf16 v[74:77], v[146:149], v[216:219], v[74:77]
	s_setprio 0
	s_setprio 1
	v_mfma_f32_16x16x32_bf16 v[122:125], v[150:153], v[170:173], v[122:125]
	v_mfma_f32_16x16x32_bf16 v[116:119], v[162:165], v[170:173], v[118:121]
	v_mfma_f32_16x16x32_bf16 v[102:105], v[150:153], v[178:181], v[102:105]
	v_mfma_f32_16x16x32_bf16 v[98:101], v[162:165], v[178:181], v[98:101]
	v_mfma_f32_16x16x32_bf16 v[86:89], v[150:153], v[186:189], v[86:89]
	v_mfma_f32_16x16x32_bf16 v[82:85], v[162:165], v[186:189], v[82:85]
	v_mfma_f32_16x16x32_bf16 v[70:73], v[150:153], v[212:215], v[70:73]
	v_mfma_f32_16x16x32_bf16 v[66:69], v[162:165], v[212:215], v[66:69]
	v_mfma_f32_16x16x32_bf16 v[122:125], v[154:157], v[174:177], v[122:125]
	v_mfma_f32_16x16x32_bf16 v[116:119], v[166:169], v[174:177], v[116:119]
	v_mfma_f32_16x16x32_bf16 v[102:105], v[154:157], v[182:185], v[102:105]
	v_mfma_f32_16x16x32_bf16 v[98:101], v[166:169], v[182:185], v[98:101]
	v_mfma_f32_16x16x32_bf16 v[86:89], v[154:157], v[190:193], v[86:89]
	v_mfma_f32_16x16x32_bf16 v[82:85], v[166:169], v[190:193], v[82:85]
	s_setprio 2
	s_barrier
	v_mfma_f32_16x16x32_bf16 v[70:73], v[154:157], v[216:219], v[70:73]
	v_mfma_f32_16x16x32_bf16 v[66:69], v[166:169], v[216:219], v[66:69]
	s_setprio 0
	s_nop 0
	ds_read_b128 v[170:173], v203 offset:16384
	ds_read_b128 v[174:177], v203 offset:17408
	ds_read_b128 v[178:181], v203 offset:18432
	ds_read_b128 v[182:185], v203 offset:19456
	ds_read_b128 v[186:189], v203 offset:20480
	ds_read_b128 v[190:193], v203 offset:21504
	ds_read_b128 v[212:215], v203 offset:22528
	ds_read_b128 v[216:219], v203 offset:23552
	s_mov_b32 m0, s13
	s_nop 0
	global_load_lds_dwordx4 v195, s[10:11]
	s_add_u32 m0, s13, 0x2000
	s_nop 0
	global_load_lds_dwordx4 v197, s[10:11]
	s_add_u32 s50, s10, 0x4000
	s_addc_u32 s51, s11, 0
	s_mov_b32 m0, s57
	s_nop 0
	global_load_lds_dwordx4 v195, s[50:51]
	s_add_u32 m0, s57, 0x2000
	s_nop 0
	global_load_lds_dwordx4 v197, s[50:51]
	s_nop 0
	s_mov_b32 m0, s56
	s_nop 0
	global_load_lds_dwordx4 v195, s[46:47]
	s_add_u32 m0, s56, 0x2000
	s_nop 0
	global_load_lds_dwordx4 v197, s[46:47]
	s_waitcnt vmcnt(8)
	s_waitcnt lgkmcnt(0)
	s_setprio 1
	s_barrier
	v_mfma_f32_16x16x32_bf16 v[62:65], v[134:137], v[170:173], v[62:65]
	v_mfma_f32_16x16x32_bf16 v[62:65], v[138:141], v[174:177], v[62:65]
	s_waitcnt lgkmcnt(5)
	v_mfma_f32_16x16x32_bf16 v[46:49], v[134:137], v[178:181], v[46:49]
	v_mfma_f32_16x16x32_bf16 v[46:49], v[138:141], v[182:185], v[46:49]
	s_waitcnt lgkmcnt(3)
	v_mfma_f32_16x16x32_bf16 v[30:33], v[134:137], v[186:189], v[30:33]
	v_mfma_f32_16x16x32_bf16 v[30:33], v[138:141], v[190:193], v[30:33]
	s_waitcnt lgkmcnt(1)
	v_mfma_f32_16x16x32_bf16 v[14:17], v[134:137], v[212:215], v[14:17]
	v_mfma_f32_16x16x32_bf16 v[14:17], v[138:141], v[216:219], v[14:17]
	v_mfma_f32_16x16x32_bf16 v[58:61], v[142:145], v[170:173], v[58:61]
	v_mfma_f32_16x16x32_bf16 v[58:61], v[146:149], v[174:177], v[58:61]
	v_mfma_f32_16x16x32_bf16 v[42:45], v[142:145], v[178:181], v[42:45]
	v_mfma_f32_16x16x32_bf16 v[42:45], v[146:149], v[182:185], v[42:45]
	v_mfma_f32_16x16x32_bf16 v[26:29], v[142:145], v[186:189], v[26:29]
	v_mfma_f32_16x16x32_bf16 v[26:29], v[146:149], v[190:193], v[26:29]
	s_waitcnt lgkmcnt(0)
	v_mfma_f32_16x16x32_bf16 v[10:13], v[142:145], v[212:215], v[10:13]
	v_mfma_f32_16x16x32_bf16 v[10:13], v[146:149], v[216:219], v[10:13]
	s_setprio 0
	s_setprio 1
	v_mfma_f32_16x16x32_bf16 v[54:57], v[150:153], v[170:173], v[54:57]
	v_mfma_f32_16x16x32_bf16 v[54:57], v[154:157], v[174:177], v[54:57]
	v_mfma_f32_16x16x32_bf16 v[38:41], v[150:153], v[178:181], v[38:41]
	v_mfma_f32_16x16x32_bf16 v[38:41], v[154:157], v[182:185], v[38:41]
	v_mfma_f32_16x16x32_bf16 v[22:25], v[150:153], v[186:189], v[22:25]
	v_mfma_f32_16x16x32_bf16 v[22:25], v[154:157], v[190:193], v[22:25]
	v_mfma_f32_16x16x32_bf16 v[6:9], v[150:153], v[212:215], v[6:9]
	v_mfma_f32_16x16x32_bf16 v[6:9], v[154:157], v[216:219], v[6:9]
	v_mfma_f32_16x16x32_bf16 v[50:53], v[162:165], v[170:173], v[50:53]
	v_mfma_f32_16x16x32_bf16 v[50:53], v[166:169], v[174:177], v[50:53]
	v_mfma_f32_16x16x32_bf16 v[34:37], v[162:165], v[178:181], v[34:37]
	v_mfma_f32_16x16x32_bf16 v[34:37], v[166:169], v[182:185], v[34:37]
	v_mfma_f32_16x16x32_bf16 v[18:21], v[162:165], v[186:189], v[18:21]
	v_mfma_f32_16x16x32_bf16 v[18:21], v[166:169], v[190:193], v[18:21]
	s_setprio 2
	s_barrier
	v_mfma_f32_16x16x32_bf16 v[2:5], v[162:165], v[212:215], v[2:5]
	v_mfma_f32_16x16x32_bf16 v[2:5], v[166:169], v[216:219], v[2:5]
	s_setprio 0
	s_nop 0
	ds_read_b128 v[134:137], v204
	ds_read_b128 v[138:141], v204 offset:1024
	ds_read_b128 v[142:145], v204 offset:2048
	ds_read_b128 v[146:149], v204 offset:3072
	ds_read_b128 v[150:153], v205
	ds_read_b128 v[154:157], v205 offset:1024
	ds_read_b128 v[162:165], v205 offset:2048
	ds_read_b128 v[166:169], v205 offset:3072
	ds_read_b128 v[170:173], v203 offset:32768
	ds_read_b128 v[174:177], v203 offset:33792
	ds_read_b128 v[178:181], v203 offset:34816
	ds_read_b128 v[182:185], v203 offset:35840
	ds_read_b128 v[186:189], v203 offset:36864
	ds_read_b128 v[190:193], v203 offset:37888
	ds_read_b128 v[212:215], v203 offset:38912
	ds_read_b128 v[216:219], v203 offset:39936
	s_add_u32 s46, s46, 0x4000
	s_addc_u32 s47, s47, 0
	s_mov_b32 m0, s58
	s_nop 0
	global_load_lds_dwordx4 v195, s[46:47]
	s_add_u32 m0, s58, 0x2000
	s_nop 0
	global_load_lds_dwordx4 v197, s[46:47]
	s_waitcnt vmcnt(8)
	s_waitcnt lgkmcnt(0)
	s_setprio 1
	s_barrier
	v_mfma_f32_16x16x32_bf16 v[130:133], v[134:137], v[170:173], v[130:133]
	v_mfma_f32_16x16x32_bf16 v[126:129], v[142:145], v[170:173], v[126:129]
	s_waitcnt lgkmcnt(5)
	v_mfma_f32_16x16x32_bf16 v[110:113], v[134:137], v[178:181], v[110:113]
	v_mfma_f32_16x16x32_bf16 v[106:109], v[142:145], v[178:181], v[106:109]
	s_waitcnt lgkmcnt(3)
	v_mfma_f32_16x16x32_bf16 v[94:97], v[134:137], v[186:189], v[94:97]
	v_mfma_f32_16x16x32_bf16 v[90:93], v[142:145], v[186:189], v[90:93]
	s_waitcnt lgkmcnt(1)
	v_mfma_f32_16x16x32_bf16 v[78:81], v[134:137], v[212:215], v[78:81]
	v_mfma_f32_16x16x32_bf16 v[74:77], v[142:145], v[212:215], v[74:77]
	v_mfma_f32_16x16x32_bf16 v[130:133], v[138:141], v[174:177], v[130:133]
	v_mfma_f32_16x16x32_bf16 v[126:129], v[146:149], v[174:177], v[126:129]
	v_mfma_f32_16x16x32_bf16 v[110:113], v[138:141], v[182:185], v[110:113]
	v_mfma_f32_16x16x32_bf16 v[106:109], v[146:149], v[182:185], v[106:109]
	v_mfma_f32_16x16x32_bf16 v[94:97], v[138:141], v[190:193], v[94:97]
	v_mfma_f32_16x16x32_bf16 v[90:93], v[146:149], v[190:193], v[90:93]
	s_waitcnt lgkmcnt(0)
	v_mfma_f32_16x16x32_bf16 v[78:81], v[138:141], v[216:219], v[78:81]
	v_mfma_f32_16x16x32_bf16 v[74:77], v[146:149], v[216:219], v[74:77]
	s_setprio 0
	s_setprio 1
	v_mfma_f32_16x16x32_bf16 v[120:123], v[150:153], v[170:173], v[122:125]
	v_mfma_f32_16x16x32_bf16 v[116:119], v[162:165], v[170:173], v[116:119]
	v_mfma_f32_16x16x32_bf16 v[102:105], v[150:153], v[178:181], v[102:105]
	v_mfma_f32_16x16x32_bf16 v[98:101], v[162:165], v[178:181], v[98:101]
	v_mfma_f32_16x16x32_bf16 v[86:89], v[150:153], v[186:189], v[86:89]
	v_mfma_f32_16x16x32_bf16 v[82:85], v[162:165], v[186:189], v[82:85]
	v_mfma_f32_16x16x32_bf16 v[70:73], v[150:153], v[212:215], v[70:73]
	v_mfma_f32_16x16x32_bf16 v[66:69], v[162:165], v[212:215], v[66:69]
	v_mfma_f32_16x16x32_bf16 v[122:125], v[154:157], v[174:177], v[120:123]
	v_mfma_f32_16x16x32_bf16 v[118:121], v[166:169], v[174:177], v[116:119]
	v_mfma_f32_16x16x32_bf16 v[102:105], v[154:157], v[182:185], v[102:105]
	v_mfma_f32_16x16x32_bf16 v[98:101], v[166:169], v[182:185], v[98:101]
	v_mfma_f32_16x16x32_bf16 v[86:89], v[154:157], v[190:193], v[86:89]
	v_mfma_f32_16x16x32_bf16 v[82:85], v[166:169], v[190:193], v[82:85]
	s_setprio 2
	s_barrier
	v_mfma_f32_16x16x32_bf16 v[70:73], v[154:157], v[216:219], v[70:73]
	v_mfma_f32_16x16x32_bf16 v[66:69], v[166:169], v[216:219], v[66:69]
	s_setprio 0
	s_nop 0
	ds_read_b128 v[170:173], v203 offset:49152
	ds_read_b128 v[174:177], v203 offset:50176
	ds_read_b128 v[178:181], v203 offset:51200
	ds_read_b128 v[182:185], v203 offset:52224
	ds_read_b128 v[186:189], v203 offset:53248
	ds_read_b128 v[190:193], v203 offset:54272
	ds_read_b128 v[212:215], v203 offset:55296
	ds_read_b128 v[216:219], v203 offset:56320
	s_mov_b32 m0, s62
	s_nop 0
	global_load_lds_dwordx4 v195, s[44:45]
	s_add_u32 m0, s62, 0x2000
	s_nop 0
	global_load_lds_dwordx4 v197, s[44:45]
	s_add_u32 s10, s10, 0xc000
	s_addc_u32 s11, s11, 0
	s_mov_b32 m0, s64
	s_nop 0
	global_load_lds_dwordx4 v195, s[10:11]
	s_add_u32 m0, s64, 0x2000
	s_nop 0
	global_load_lds_dwordx4 v197, s[10:11]
	s_nop 0
	s_mov_b32 m0, s63
	s_nop 0
	global_load_lds_dwordx4 v195, s[42:43]
	s_add_u32 m0, s63, 0x2000
	s_nop 0
	global_load_lds_dwordx4 v197, s[42:43]
	s_waitcnt vmcnt(8)
	s_waitcnt lgkmcnt(0)
	s_setprio 1
	s_barrier
	v_mfma_f32_16x16x32_bf16 v[62:65], v[134:137], v[170:173], v[62:65]
	v_mfma_f32_16x16x32_bf16 v[62:65], v[138:141], v[174:177], v[62:65]
	s_waitcnt lgkmcnt(5)
	v_mfma_f32_16x16x32_bf16 v[46:49], v[134:137], v[178:181], v[46:49]
	v_mfma_f32_16x16x32_bf16 v[46:49], v[138:141], v[182:185], v[46:49]
	s_waitcnt lgkmcnt(3)
	v_mfma_f32_16x16x32_bf16 v[30:33], v[134:137], v[186:189], v[30:33]
	v_mfma_f32_16x16x32_bf16 v[30:33], v[138:141], v[190:193], v[30:33]
	s_waitcnt lgkmcnt(1)
	v_mfma_f32_16x16x32_bf16 v[14:17], v[134:137], v[212:215], v[14:17]
	v_mfma_f32_16x16x32_bf16 v[14:17], v[138:141], v[216:219], v[14:17]
	v_mfma_f32_16x16x32_bf16 v[58:61], v[142:145], v[170:173], v[58:61]
	v_mfma_f32_16x16x32_bf16 v[58:61], v[146:149], v[174:177], v[58:61]
	v_mfma_f32_16x16x32_bf16 v[42:45], v[142:145], v[178:181], v[42:45]
	v_mfma_f32_16x16x32_bf16 v[42:45], v[146:149], v[182:185], v[42:45]
	v_mfma_f32_16x16x32_bf16 v[26:29], v[142:145], v[186:189], v[26:29]
	v_mfma_f32_16x16x32_bf16 v[26:29], v[146:149], v[190:193], v[26:29]
	s_waitcnt lgkmcnt(0)
	v_mfma_f32_16x16x32_bf16 v[10:13], v[142:145], v[212:215], v[10:13]
	v_mfma_f32_16x16x32_bf16 v[10:13], v[146:149], v[216:219], v[10:13]
	s_setprio 0
	s_setprio 1
	v_mfma_f32_16x16x32_bf16 v[54:57], v[150:153], v[170:173], v[54:57]
	v_mfma_f32_16x16x32_bf16 v[54:57], v[154:157], v[174:177], v[54:57]
	v_mfma_f32_16x16x32_bf16 v[38:41], v[150:153], v[178:181], v[38:41]
	v_mfma_f32_16x16x32_bf16 v[38:41], v[154:157], v[182:185], v[38:41]
	v_mfma_f32_16x16x32_bf16 v[22:25], v[150:153], v[186:189], v[22:25]
	v_mfma_f32_16x16x32_bf16 v[22:25], v[154:157], v[190:193], v[22:25]
	v_mfma_f32_16x16x32_bf16 v[6:9], v[150:153], v[212:215], v[6:9]
	v_mfma_f32_16x16x32_bf16 v[6:9], v[154:157], v[216:219], v[6:9]
	v_mfma_f32_16x16x32_bf16 v[50:53], v[162:165], v[170:173], v[50:53]
	v_mfma_f32_16x16x32_bf16 v[50:53], v[166:169], v[174:177], v[50:53]
	v_mfma_f32_16x16x32_bf16 v[34:37], v[162:165], v[178:181], v[34:37]
	v_mfma_f32_16x16x32_bf16 v[34:37], v[166:169], v[182:185], v[34:37]
	v_mfma_f32_16x16x32_bf16 v[18:21], v[162:165], v[186:189], v[18:21]
	v_mfma_f32_16x16x32_bf16 v[18:21], v[166:169], v[190:193], v[18:21]
	s_setprio 2
	s_barrier
	v_mfma_f32_16x16x32_bf16 v[2:5], v[162:165], v[212:215], v[2:5]
	v_mfma_f32_16x16x32_bf16 v[2:5], v[166:169], v[216:219], v[2:5]
	s_setprio 0
	s_nop 0
	s_add_i32 s49, s49, 2
	s_add_u32 s6, s6, 0x10000
	s_addc_u32 s7, s7, 0
	s_cmp_gt_u32 s49, 13
	v_mov_b32_e32 v115, v114
	s_cbranch_scc1 .LBB0_1922

.LBB0_2120:
	s_add_u32 s56, s52, 0x10000
	s_addc_u32 s57, s53, 0
	s_and_b64 s[52:53], s[50:51], exec
	s_cselect_b32 s53, s57, s43
	s_cselect_b32 s52, s56, s88
	s_add_u32 s15, s18, s15
	s_addc_u32 s56, s19, 0
	s_add_u32 s15, s15, 0x10000
	s_waitcnt vmcnt(8)
	s_addc_u32 s56, s56, 0
	s_waitcnt lgkmcnt(0)
	s_and_b64 s[50:51], s[50:51], exec
	s_cselect_b32 s51, s56, s41
	s_cselect_b32 s50, s15, s89
	s_setprio 1
	s_barrier
	v_mfma_f32_16x16x32_bf16 v[126:129], v[146:149], v[186:189], v[126:129]
	v_mfma_f32_16x16x32_bf16 v[126:129], v[150:153], v[190:193], v[126:129]
	s_waitcnt lgkmcnt(5)
	v_mfma_f32_16x16x32_bf16 v[118:121], v[146:149], v[178:181], v[118:121]
	v_mfma_f32_16x16x32_bf16 v[118:121], v[150:153], v[182:185], v[118:121]
	s_waitcnt lgkmcnt(3)
	v_mfma_f32_16x16x32_bf16 v[110:113], v[146:149], v[170:173], v[110:113]
	v_mfma_f32_16x16x32_bf16 v[110:113], v[150:153], v[174:177], v[110:113]
	s_waitcnt lgkmcnt(1)
	v_mfma_f32_16x16x32_bf16 v[102:105], v[146:149], v[162:165], v[102:105]
	v_mfma_f32_16x16x32_bf16 v[102:105], v[150:153], v[166:169], v[102:105]
	v_mfma_f32_16x16x32_bf16 v[122:125], v[154:157], v[186:189], v[122:125]
	v_mfma_f32_16x16x32_bf16 v[122:125], v[158:161], v[190:193], v[122:125]
	v_mfma_f32_16x16x32_bf16 v[114:117], v[154:157], v[178:181], v[114:117]
	v_mfma_f32_16x16x32_bf16 v[114:117], v[158:161], v[182:185], v[114:117]
	v_mfma_f32_16x16x32_bf16 v[106:109], v[154:157], v[170:173], v[106:109]
	v_mfma_f32_16x16x32_bf16 v[106:109], v[158:161], v[174:177], v[106:109]
	s_waitcnt lgkmcnt(0)
	v_mfma_f32_16x16x32_bf16 v[98:101], v[154:157], v[162:165], v[98:101]
	v_mfma_f32_16x16x32_bf16 v[98:101], v[158:161], v[166:169], v[98:101]
	s_setprio 0
	s_setprio 1
	v_mfma_f32_16x16x32_bf16 v[94:97], v[130:133], v[186:189], v[94:97]
	v_mfma_f32_16x16x32_bf16 v[94:97], v[134:137], v[190:193], v[94:97]
	v_mfma_f32_16x16x32_bf16 v[86:89], v[130:133], v[178:181], v[86:89]
	v_mfma_f32_16x16x32_bf16 v[86:89], v[134:137], v[182:185], v[86:89]
	v_mfma_f32_16x16x32_bf16 v[78:81], v[130:133], v[170:173], v[78:81]
	v_mfma_f32_16x16x32_bf16 v[78:81], v[134:137], v[174:177], v[78:81]
	v_mfma_f32_16x16x32_bf16 v[70:73], v[130:133], v[162:165], v[70:73]
	v_mfma_f32_16x16x32_bf16 v[70:73], v[134:137], v[166:169], v[70:73]
	v_mfma_f32_16x16x32_bf16 v[90:93], v[138:141], v[186:189], v[90:93]
	v_mfma_f32_16x16x32_bf16 v[90:93], v[142:145], v[190:193], v[90:93]
	v_mfma_f32_16x16x32_bf16 v[82:85], v[138:141], v[178:181], v[82:85]
	v_mfma_f32_16x16x32_bf16 v[82:85], v[142:145], v[182:185], v[82:85]
	v_mfma_f32_16x16x32_bf16 v[74:77], v[138:141], v[170:173], v[74:77]
	v_mfma_f32_16x16x32_bf16 v[74:77], v[142:145], v[174:177], v[74:77]
	s_setprio 2
	s_barrier
	v_mfma_f32_16x16x32_bf16 v[66:69], v[138:141], v[162:165], v[66:69]
	v_mfma_f32_16x16x32_bf16 v[66:69], v[142:145], v[166:169], v[66:69]
	s_setprio 0
	s_nop 0
	ds_read_b128 v[186:189], v207 offset:16384
	ds_read_b128 v[190:193], v207 offset:17408
	ds_read_b128 v[178:181], v207 offset:18432
	ds_read_b128 v[182:185], v207 offset:19456
	ds_read_b128 v[170:173], v207 offset:20480
	ds_read_b128 v[174:177], v207 offset:21504
	ds_read_b128 v[162:165], v207 offset:22528
	ds_read_b128 v[166:169], v207 offset:23552
	s_mov_b32 m0, s62
	s_nop 0
	global_load_lds_dwordx4 v195, s[50:51]
	s_add_u32 m0, s62, 0x2000
	s_nop 0
	global_load_lds_dwordx4 v197, s[50:51]
	s_add_u32 s56, s50, 0x4000
	s_addc_u32 s57, s51, 0
	s_mov_b32 m0, s63
	s_nop 0
	global_load_lds_dwordx4 v195, s[56:57]
	s_add_u32 m0, s63, 0x2000
	s_nop 0
	global_load_lds_dwordx4 v197, s[56:57]
	s_andn2_b64 vcc, exec, s[54:55]
	s_mov_b32 m0, s61
	s_nop 0
	global_load_lds_dwordx4 v195, s[52:53]
	s_add_u32 m0, s61, 0x2000
	s_nop 0
	global_load_lds_dwordx4 v197, s[52:53]
	s_cbranch_vccnz .LBB0_2122
	v_mov_b32_e32 v2, 0
	v_mov_b32_e32 v3, v2
	v_mov_b32_e32 v4, v2
	v_mov_b32_e32 v5, v2
	v_mov_b32_e32 v6, v2
	v_mov_b32_e32 v7, v2
	v_mov_b32_e32 v8, v2
	v_mov_b32_e32 v9, v2
	v_mov_b32_e32 v10, v2
	v_mov_b32_e32 v11, v2
	v_mov_b32_e32 v12, v2
	v_mov_b32_e32 v13, v2
	v_mov_b32_e32 v14, v2
	v_mov_b32_e32 v15, v2
	v_mov_b32_e32 v16, v2
	v_mov_b32_e32 v17, v2
	v_mov_b32_e32 v18, v2
	v_mov_b32_e32 v19, v2
	v_mov_b32_e32 v20, v2
	v_mov_b32_e32 v21, v2
	v_mov_b32_e32 v22, v2
	v_mov_b32_e32 v23, v2
	v_mov_b32_e32 v24, v2
	v_mov_b32_e32 v25, v2
	v_mov_b32_e32 v26, v2
	v_mov_b32_e32 v27, v2
	v_mov_b32_e32 v28, v2
	v_mov_b32_e32 v29, v2
	v_mov_b32_e32 v30, v2
	v_mov_b32_e32 v31, v2
	v_mov_b32_e32 v32, v2
	v_mov_b32_e32 v33, v2
	v_mov_b32_e32 v34, v2
	v_mov_b32_e32 v35, v2
	v_mov_b32_e32 v36, v2
	v_mov_b32_e32 v37, v2
	v_mov_b32_e32 v38, v2
	v_mov_b32_e32 v39, v2
	v_mov_b32_e32 v40, v2
	v_mov_b32_e32 v41, v2
	v_mov_b32_e32 v42, v2
	v_mov_b32_e32 v43, v2
	v_mov_b32_e32 v44, v2
	v_mov_b32_e32 v45, v2
	v_mov_b32_e32 v46, v2
	v_mov_b32_e32 v47, v2
	v_mov_b32_e32 v48, v2
	v_mov_b32_e32 v49, v2
	v_mov_b32_e32 v50, v2
	v_mov_b32_e32 v51, v2
	v_mov_b32_e32 v52, v2
	v_mov_b32_e32 v53, v2
	v_mov_b32_e32 v54, v2
	v_mov_b32_e32 v55, v2
	v_mov_b32_e32 v56, v2
	v_mov_b32_e32 v57, v2
	v_mov_b32_e32 v58, v2
	v_mov_b32_e32 v59, v2
	v_mov_b32_e32 v60, v2
	v_mov_b32_e32 v61, v2
	v_mov_b32_e32 v62, v2
	v_mov_b32_e32 v63, v2
	v_mov_b32_e32 v64, v2
	v_mov_b32_e32 v65, v2
.LBB0_2122:
	s_waitcnt vmcnt(8)
	s_add_u32 s54, s52, 0x8000
	s_waitcnt lgkmcnt(0)
	s_addc_u32 s55, s53, 0
	s_add_u32 s56, s50, 0x8000
	s_addc_u32 s57, s51, 0
	s_setprio 1
	s_barrier
	v_mfma_f32_16x16x32_bf16 v[62:65], v[146:149], v[186:189], v[62:65]
	v_mfma_f32_16x16x32_bf16 v[62:65], v[150:153], v[190:193], v[62:65]
	s_waitcnt lgkmcnt(5)
	v_mfma_f32_16x16x32_bf16 v[54:57], v[146:149], v[178:181], v[54:57]
	v_mfma_f32_16x16x32_bf16 v[54:57], v[150:153], v[182:185], v[54:57]
	s_waitcnt lgkmcnt(3)
	v_mfma_f32_16x16x32_bf16 v[46:49], v[146:149], v[170:173], v[46:49]
	v_mfma_f32_16x16x32_bf16 v[46:49], v[150:153], v[174:177], v[46:49]
	s_waitcnt lgkmcnt(1)
	v_mfma_f32_16x16x32_bf16 v[38:41], v[146:149], v[162:165], v[38:41]
	v_mfma_f32_16x16x32_bf16 v[38:41], v[150:153], v[166:169], v[38:41]
	v_mfma_f32_16x16x32_bf16 v[58:61], v[154:157], v[186:189], v[58:61]
	v_mfma_f32_16x16x32_bf16 v[58:61], v[158:161], v[190:193], v[58:61]
	v_mfma_f32_16x16x32_bf16 v[50:53], v[154:157], v[178:181], v[50:53]
	v_mfma_f32_16x16x32_bf16 v[50:53], v[158:161], v[182:185], v[50:53]
	v_mfma_f32_16x16x32_bf16 v[42:45], v[154:157], v[170:173], v[42:45]
	v_mfma_f32_16x16x32_bf16 v[42:45], v[158:161], v[174:177], v[42:45]
	s_waitcnt lgkmcnt(0)
	v_mfma_f32_16x16x32_bf16 v[34:37], v[154:157], v[162:165], v[34:37]
	v_mfma_f32_16x16x32_bf16 v[34:37], v[158:161], v[166:169], v[34:37]
	s_setprio 0
	s_setprio 1
	v_mfma_f32_16x16x32_bf16 v[30:33], v[130:133], v[186:189], v[30:33]
	v_mfma_f32_16x16x32_bf16 v[30:33], v[134:137], v[190:193], v[30:33]
	v_mfma_f32_16x16x32_bf16 v[22:25], v[130:133], v[178:181], v[22:25]
	v_mfma_f32_16x16x32_bf16 v[22:25], v[134:137], v[182:185], v[22:25]
	v_mfma_f32_16x16x32_bf16 v[14:17], v[130:133], v[170:173], v[14:17]
	v_mfma_f32_16x16x32_bf16 v[14:17], v[134:137], v[174:177], v[14:17]
	v_mfma_f32_16x16x32_bf16 v[6:9], v[130:133], v[162:165], v[6:9]
	v_mfma_f32_16x16x32_bf16 v[6:9], v[134:137], v[166:169], v[6:9]
	v_mfma_f32_16x16x32_bf16 v[26:29], v[138:141], v[186:189], v[26:29]
	v_mfma_f32_16x16x32_bf16 v[26:29], v[142:145], v[190:193], v[26:29]
	v_mfma_f32_16x16x32_bf16 v[18:21], v[138:141], v[178:181], v[18:21]
	v_mfma_f32_16x16x32_bf16 v[18:21], v[142:145], v[182:185], v[18:21]
	v_mfma_f32_16x16x32_bf16 v[10:13], v[138:141], v[170:173], v[10:13]
	v_mfma_f32_16x16x32_bf16 v[10:13], v[142:145], v[174:177], v[10:13]
	s_setprio 2
	s_barrier
	v_mfma_f32_16x16x32_bf16 v[2:5], v[138:141], v[162:165], v[2:5]
	v_mfma_f32_16x16x32_bf16 v[2:5], v[142:145], v[166:169], v[2:5]
	s_setprio 0
	s_nop 0
	v_add_u32_e32 v142, 0x18000, v206
	v_add_u32_e32 v158, 0x1c000, v206
	ds_read_b128 v[130:133], v142
	ds_read_b128 v[134:137], v142 offset:1024
	ds_read_b128 v[138:141], v142 offset:2048
	ds_read_b128 v[142:145], v142 offset:3072
	ds_read_b128 v[146:149], v158
	ds_read_b128 v[150:153], v158 offset:1024
	ds_read_b128 v[154:157], v158 offset:2048
	ds_read_b128 v[158:161], v158 offset:3072
	ds_read_b128 v[162:165], v207 offset:32768
	ds_read_b128 v[166:169], v207 offset:33792
	ds_read_b128 v[170:173], v207 offset:34816
	ds_read_b128 v[174:177], v207 offset:35840
	ds_read_b128 v[178:181], v207 offset:36864
	ds_read_b128 v[182:185], v207 offset:37888
	ds_read_b128 v[186:189], v207 offset:38912
	ds_read_b128 v[190:193], v207 offset:39936
	s_add_u32 s52, s52, 0x4000
	s_addc_u32 s53, s53, 0
	s_mov_b32 m0, s64
	s_nop 0
	global_load_lds_dwordx4 v195, s[52:53]
	s_add_u32 m0, s64, 0x2000
	s_nop 0
	global_load_lds_dwordx4 v197, s[52:53]
	s_waitcnt vmcnt(8)
	s_waitcnt lgkmcnt(0)
	s_setprio 1
	s_barrier
	v_mfma_f32_16x16x32_bf16 v[126:129], v[130:133], v[162:165], v[126:129]
	v_mfma_f32_16x16x32_bf16 v[126:129], v[134:137], v[166:169], v[126:129]
	s_waitcnt lgkmcnt(5)
	v_mfma_f32_16x16x32_bf16 v[118:121], v[130:133], v[170:173], v[118:121]
	v_mfma_f32_16x16x32_bf16 v[118:121], v[134:137], v[174:177], v[118:121]
	s_waitcnt lgkmcnt(3)
	v_mfma_f32_16x16x32_bf16 v[110:113], v[130:133], v[178:181], v[110:113]
	v_mfma_f32_16x16x32_bf16 v[110:113], v[134:137], v[182:185], v[110:113]
	s_waitcnt lgkmcnt(1)
	v_mfma_f32_16x16x32_bf16 v[102:105], v[130:133], v[186:189], v[102:105]
	v_mfma_f32_16x16x32_bf16 v[102:105], v[134:137], v[190:193], v[102:105]
	v_mfma_f32_16x16x32_bf16 v[122:125], v[138:141], v[162:165], v[122:125]
	v_mfma_f32_16x16x32_bf16 v[122:125], v[142:145], v[166:169], v[122:125]
	v_mfma_f32_16x16x32_bf16 v[114:117], v[138:141], v[170:173], v[114:117]
	v_mfma_f32_16x16x32_bf16 v[114:117], v[142:145], v[174:177], v[114:117]
	v_mfma_f32_16x16x32_bf16 v[106:109], v[138:141], v[178:181], v[106:109]
	v_mfma_f32_16x16x32_bf16 v[106:109], v[142:145], v[182:185], v[106:109]
	s_waitcnt lgkmcnt(0)
	v_mfma_f32_16x16x32_bf16 v[98:101], v[138:141], v[186:189], v[98:101]
	v_mfma_f32_16x16x32_bf16 v[98:101], v[142:145], v[190:193], v[98:101]
	s_setprio 0
	s_setprio 1
	v_mfma_f32_16x16x32_bf16 v[94:97], v[146:149], v[162:165], v[94:97]
	v_mfma_f32_16x16x32_bf16 v[94:97], v[150:153], v[166:169], v[94:97]
	v_mfma_f32_16x16x32_bf16 v[86:89], v[146:149], v[170:173], v[86:89]
	v_mfma_f32_16x16x32_bf16 v[86:89], v[150:153], v[174:177], v[86:89]
	v_mfma_f32_16x16x32_bf16 v[78:81], v[146:149], v[178:181], v[78:81]
	v_mfma_f32_16x16x32_bf16 v[78:81], v[150:153], v[182:185], v[78:81]
	v_mfma_f32_16x16x32_bf16 v[70:73], v[146:149], v[186:189], v[70:73]
	v_mfma_f32_16x16x32_bf16 v[70:73], v[150:153], v[190:193], v[70:73]
	v_mfma_f32_16x16x32_bf16 v[90:93], v[154:157], v[162:165], v[90:93]
	v_mfma_f32_16x16x32_bf16 v[90:93], v[158:161], v[166:169], v[90:93]
	v_mfma_f32_16x16x32_bf16 v[82:85], v[154:157], v[170:173], v[82:85]
	v_mfma_f32_16x16x32_bf16 v[82:85], v[158:161], v[174:177], v[82:85]
	v_mfma_f32_16x16x32_bf16 v[74:77], v[154:157], v[178:181], v[74:77]
	v_mfma_f32_16x16x32_bf16 v[74:77], v[158:161], v[182:185], v[74:77]
	s_setprio 2
	s_barrier
	v_mfma_f32_16x16x32_bf16 v[66:69], v[154:157], v[186:189], v[66:69]
	v_mfma_f32_16x16x32_bf16 v[66:69], v[158:161], v[190:193], v[66:69]
	s_setprio 0
	s_nop 0
	ds_read_b128 v[162:165], v207 offset:49152
	ds_read_b128 v[166:169], v207 offset:50176
	ds_read_b128 v[170:173], v207 offset:51200
	ds_read_b128 v[174:177], v207 offset:52224
	ds_read_b128 v[178:181], v207 offset:53248
	ds_read_b128 v[182:185], v207 offset:54272
	ds_read_b128 v[186:189], v207 offset:55296
	ds_read_b128 v[190:193], v207 offset:56320
	s_mov_b32 m0, s70
	s_nop 0
	global_load_lds_dwordx4 v195, s[56:57]
	s_add_u32 m0, s70, 0x2000
	s_nop 0
	global_load_lds_dwordx4 v197, s[56:57]
	s_add_u32 s50, s50, 0xc000
	s_addc_u32 s51, s51, 0
	s_mov_b32 m0, s72
	s_nop 0
	global_load_lds_dwordx4 v195, s[50:51]
	s_add_u32 m0, s72, 0x2000
	s_nop 0
	global_load_lds_dwordx4 v197, s[50:51]
	s_nop 0
	s_mov_b32 m0, s71
	s_nop 0
	global_load_lds_dwordx4 v195, s[54:55]
	s_add_u32 m0, s71, 0x2000
	s_nop 0
	global_load_lds_dwordx4 v197, s[54:55]
	s_waitcnt vmcnt(8)
	s_waitcnt lgkmcnt(0)
	s_setprio 1
	s_barrier
	v_mfma_f32_16x16x32_bf16 v[62:65], v[130:133], v[162:165], v[62:65]
	v_mfma_f32_16x16x32_bf16 v[62:65], v[134:137], v[166:169], v[62:65]
	s_waitcnt lgkmcnt(5)
	v_mfma_f32_16x16x32_bf16 v[54:57], v[130:133], v[170:173], v[54:57]
	v_mfma_f32_16x16x32_bf16 v[54:57], v[134:137], v[174:177], v[54:57]
	s_waitcnt lgkmcnt(3)
	v_mfma_f32_16x16x32_bf16 v[46:49], v[130:133], v[178:181], v[46:49]
	v_mfma_f32_16x16x32_bf16 v[46:49], v[134:137], v[182:185], v[46:49]
	s_waitcnt lgkmcnt(1)
	v_mfma_f32_16x16x32_bf16 v[38:41], v[130:133], v[186:189], v[38:41]
	v_mfma_f32_16x16x32_bf16 v[38:41], v[134:137], v[190:193], v[38:41]
	v_mfma_f32_16x16x32_bf16 v[58:61], v[138:141], v[162:165], v[58:61]
	v_mfma_f32_16x16x32_bf16 v[58:61], v[142:145], v[166:169], v[58:61]
	v_mfma_f32_16x16x32_bf16 v[50:53], v[138:141], v[170:173], v[50:53]
	v_mfma_f32_16x16x32_bf16 v[50:53], v[142:145], v[174:177], v[50:53]
	v_mfma_f32_16x16x32_bf16 v[42:45], v[138:141], v[178:181], v[42:45]
	v_mfma_f32_16x16x32_bf16 v[42:45], v[142:145], v[182:185], v[42:45]
	s_waitcnt lgkmcnt(0)
	v_mfma_f32_16x16x32_bf16 v[34:37], v[138:141], v[186:189], v[34:37]
	v_mfma_f32_16x16x32_bf16 v[34:37], v[142:145], v[190:193], v[34:37]
	s_setprio 0
	s_setprio 1
	v_mfma_f32_16x16x32_bf16 v[30:33], v[146:149], v[162:165], v[30:33]
	v_mfma_f32_16x16x32_bf16 v[30:33], v[150:153], v[166:169], v[30:33]
	v_mfma_f32_16x16x32_bf16 v[22:25], v[146:149], v[170:173], v[22:25]
	v_mfma_f32_16x16x32_bf16 v[22:25], v[150:153], v[174:177], v[22:25]
	v_mfma_f32_16x16x32_bf16 v[14:17], v[146:149], v[178:181], v[14:17]
	v_mfma_f32_16x16x32_bf16 v[14:17], v[150:153], v[182:185], v[14:17]
	v_mfma_f32_16x16x32_bf16 v[6:9], v[146:149], v[186:189], v[6:9]
	v_mfma_f32_16x16x32_bf16 v[6:9], v[150:153], v[190:193], v[6:9]
	v_mfma_f32_16x16x32_bf16 v[26:29], v[154:157], v[162:165], v[26:29]
	v_mfma_f32_16x16x32_bf16 v[26:29], v[158:161], v[166:169], v[26:29]
	v_mfma_f32_16x16x32_bf16 v[18:21], v[154:157], v[170:173], v[18:21]
	v_mfma_f32_16x16x32_bf16 v[18:21], v[158:161], v[174:177], v[18:21]
	v_mfma_f32_16x16x32_bf16 v[10:13], v[154:157], v[178:181], v[10:13]
	v_mfma_f32_16x16x32_bf16 v[10:13], v[158:161], v[182:185], v[10:13]
	s_setprio 2
	s_barrier
	v_mfma_f32_16x16x32_bf16 v[2:5], v[154:157], v[186:189], v[2:5]
	v_mfma_f32_16x16x32_bf16 v[2:5], v[158:161], v[190:193], v[2:5]
	s_setprio 0
	s_nop 0
	s_add_i32 s15, s90, 2
	s_cmp_gt_u32 s90, 13
	s_cbranch_scc1 .LBB0_2124
	v_mov_b32_e32 v130, v198
	s_mov_b32 s90, s15
	s_branch .LBB0_2099

.LBB0_2229:
	s_add_i32 s22, s46, 2
	s_lshl_b64 s[42:43], s[22:23], 15
	s_add_u32 s44, s2, s42
	s_addc_u32 s45, s3, s43
	s_and_b64 s[38:39], s[14:15], exec
	s_cselect_b32 s39, s45, s29
	s_cselect_b32 s38, s44, s28
	s_add_u32 s42, s16, s42
	s_waitcnt vmcnt(8)
	s_addc_u32 s43, s17, s43
	s_waitcnt lgkmcnt(0)
	s_and_b64 s[14:15], s[14:15], exec
	s_cselect_b32 s15, s43, s31
	s_cselect_b32 s14, s42, s30
	s_setprio 1
	s_barrier
	v_mfma_f32_16x16x32_bf16 v[126:129], v[146:149], v[186:189], v[126:129]
	v_mfma_f32_16x16x32_bf16 v[126:129], v[150:153], v[190:193], v[126:129]
	s_waitcnt lgkmcnt(5)
	v_mfma_f32_16x16x32_bf16 v[118:121], v[146:149], v[178:181], v[118:121]
	v_mfma_f32_16x16x32_bf16 v[118:121], v[150:153], v[182:185], v[118:121]
	s_waitcnt lgkmcnt(3)
	v_mfma_f32_16x16x32_bf16 v[110:113], v[146:149], v[170:173], v[110:113]
	v_mfma_f32_16x16x32_bf16 v[110:113], v[150:153], v[174:177], v[110:113]
	s_waitcnt lgkmcnt(1)
	v_mfma_f32_16x16x32_bf16 v[102:105], v[146:149], v[162:165], v[102:105]
	v_mfma_f32_16x16x32_bf16 v[102:105], v[150:153], v[166:169], v[102:105]
	v_mfma_f32_16x16x32_bf16 v[122:125], v[154:157], v[186:189], v[122:125]
	v_mfma_f32_16x16x32_bf16 v[122:125], v[158:161], v[190:193], v[122:125]
	v_mfma_f32_16x16x32_bf16 v[114:117], v[154:157], v[178:181], v[114:117]
	v_mfma_f32_16x16x32_bf16 v[114:117], v[158:161], v[182:185], v[114:117]
	v_mfma_f32_16x16x32_bf16 v[106:109], v[154:157], v[170:173], v[106:109]
	v_mfma_f32_16x16x32_bf16 v[106:109], v[158:161], v[174:177], v[106:109]
	s_waitcnt lgkmcnt(0)
	v_mfma_f32_16x16x32_bf16 v[98:101], v[154:157], v[162:165], v[98:101]
	v_mfma_f32_16x16x32_bf16 v[98:101], v[158:161], v[166:169], v[98:101]
	s_setprio 0
	s_setprio 1
	v_mfma_f32_16x16x32_bf16 v[94:97], v[130:133], v[186:189], v[94:97]
	v_mfma_f32_16x16x32_bf16 v[94:97], v[134:137], v[190:193], v[94:97]
	v_mfma_f32_16x16x32_bf16 v[86:89], v[130:133], v[178:181], v[86:89]
	v_mfma_f32_16x16x32_bf16 v[86:89], v[134:137], v[182:185], v[86:89]
	v_mfma_f32_16x16x32_bf16 v[78:81], v[130:133], v[170:173], v[78:81]
	v_mfma_f32_16x16x32_bf16 v[78:81], v[134:137], v[174:177], v[78:81]
	v_mfma_f32_16x16x32_bf16 v[70:73], v[130:133], v[162:165], v[70:73]
	v_mfma_f32_16x16x32_bf16 v[70:73], v[134:137], v[166:169], v[70:73]
	v_mfma_f32_16x16x32_bf16 v[90:93], v[138:141], v[186:189], v[90:93]
	v_mfma_f32_16x16x32_bf16 v[90:93], v[142:145], v[190:193], v[90:93]
	v_mfma_f32_16x16x32_bf16 v[82:85], v[138:141], v[178:181], v[82:85]
	v_mfma_f32_16x16x32_bf16 v[82:85], v[142:145], v[182:185], v[82:85]
	v_mfma_f32_16x16x32_bf16 v[74:77], v[138:141], v[170:173], v[74:77]
	v_mfma_f32_16x16x32_bf16 v[74:77], v[142:145], v[174:177], v[74:77]
	s_setprio 2
	s_barrier
	v_mfma_f32_16x16x32_bf16 v[66:69], v[138:141], v[162:165], v[66:69]
	v_mfma_f32_16x16x32_bf16 v[66:69], v[142:145], v[166:169], v[66:69]
	s_setprio 0
	s_nop 0
	ds_read_b128 v[186:189], v215 offset:16384
	ds_read_b128 v[190:193], v215 offset:17408
	ds_read_b128 v[178:181], v215 offset:18432
	ds_read_b128 v[182:185], v215 offset:19456
	ds_read_b128 v[170:173], v215 offset:20480
	ds_read_b128 v[174:177], v215 offset:21504
	ds_read_b128 v[162:165], v215 offset:22528
	ds_read_b128 v[166:169], v215 offset:23552
	s_mov_b32 m0, s57
	s_nop 0
	global_load_lds_dwordx4 v195, s[14:15]
	s_add_u32 m0, s57, 0x2000
	s_nop 0
	global_load_lds_dwordx4 v208, s[14:15]
	s_add_u32 s42, s14, 0x4000
	s_addc_u32 s43, s15, 0
	s_mov_b32 m0, s58
	s_nop 0
	global_load_lds_dwordx4 v195, s[42:43]
	s_add_u32 m0, s58, 0x2000
	s_nop 0
	global_load_lds_dwordx4 v208, s[42:43]
	s_andn2_b64 vcc, exec, s[40:41]
	s_mov_b32 m0, s56
	s_nop 0
	global_load_lds_dwordx4 v195, s[38:39]
	s_add_u32 m0, s56, 0x2000
	s_nop 0
	global_load_lds_dwordx4 v208, s[38:39]
	s_cbranch_vccnz .LBB0_2231
	v_mov_b32_e32 v2, 0
	v_mov_b32_e32 v3, v2
	v_mov_b32_e32 v4, v2
	v_mov_b32_e32 v5, v2
	v_mov_b32_e32 v6, v2
	v_mov_b32_e32 v7, v2
	v_mov_b32_e32 v8, v2
	v_mov_b32_e32 v9, v2
	v_mov_b32_e32 v10, v2
	v_mov_b32_e32 v11, v2
	v_mov_b32_e32 v12, v2
	v_mov_b32_e32 v13, v2
	v_mov_b32_e32 v14, v2
	v_mov_b32_e32 v15, v2
	v_mov_b32_e32 v16, v2
	v_mov_b32_e32 v17, v2
	v_mov_b32_e32 v18, v2
	v_mov_b32_e32 v19, v2
	v_mov_b32_e32 v20, v2
	v_mov_b32_e32 v21, v2
	v_mov_b32_e32 v22, v2
	v_mov_b32_e32 v23, v2
	v_mov_b32_e32 v24, v2
	v_mov_b32_e32 v25, v2
	v_mov_b32_e32 v26, v2
	v_mov_b32_e32 v27, v2
	v_mov_b32_e32 v28, v2
	v_mov_b32_e32 v29, v2
	v_mov_b32_e32 v30, v2
	v_mov_b32_e32 v31, v2
	v_mov_b32_e32 v32, v2
	v_mov_b32_e32 v33, v2
	v_mov_b32_e32 v34, v2
	v_mov_b32_e32 v35, v2
	v_mov_b32_e32 v36, v2
	v_mov_b32_e32 v37, v2
	v_mov_b32_e32 v38, v2
	v_mov_b32_e32 v39, v2
	v_mov_b32_e32 v40, v2
	v_mov_b32_e32 v41, v2
	v_mov_b32_e32 v42, v2
	v_mov_b32_e32 v43, v2
	v_mov_b32_e32 v44, v2
	v_mov_b32_e32 v45, v2
	v_mov_b32_e32 v46, v2
	v_mov_b32_e32 v47, v2
	v_mov_b32_e32 v48, v2
	v_mov_b32_e32 v49, v2
	v_mov_b32_e32 v50, v2
	v_mov_b32_e32 v51, v2
	v_mov_b32_e32 v52, v2
	v_mov_b32_e32 v53, v2
	v_mov_b32_e32 v54, v2
	v_mov_b32_e32 v55, v2
	v_mov_b32_e32 v56, v2
	v_mov_b32_e32 v57, v2
	v_mov_b32_e32 v58, v2
	v_mov_b32_e32 v59, v2
	v_mov_b32_e32 v60, v2
	v_mov_b32_e32 v61, v2
	v_mov_b32_e32 v62, v2
	v_mov_b32_e32 v63, v2
	v_mov_b32_e32 v64, v2
	v_mov_b32_e32 v65, v2
.LBB0_2231:
	s_waitcnt vmcnt(8)
	s_add_u32 s40, s38, 0x8000
	s_waitcnt lgkmcnt(0)
	s_addc_u32 s41, s39, 0
	s_add_u32 s42, s14, 0x8000
	s_addc_u32 s43, s15, 0
	s_setprio 1
	s_barrier
	v_mfma_f32_16x16x32_bf16 v[62:65], v[146:149], v[186:189], v[62:65]
	v_mfma_f32_16x16x32_bf16 v[62:65], v[150:153], v[190:193], v[62:65]
	s_waitcnt lgkmcnt(5)
	v_mfma_f32_16x16x32_bf16 v[54:57], v[146:149], v[178:181], v[54:57]
	v_mfma_f32_16x16x32_bf16 v[54:57], v[150:153], v[182:185], v[54:57]
	s_waitcnt lgkmcnt(3)
	v_mfma_f32_16x16x32_bf16 v[46:49], v[146:149], v[170:173], v[46:49]
	v_mfma_f32_16x16x32_bf16 v[46:49], v[150:153], v[174:177], v[46:49]
	s_waitcnt lgkmcnt(1)
	v_mfma_f32_16x16x32_bf16 v[38:41], v[146:149], v[162:165], v[38:41]
	v_mfma_f32_16x16x32_bf16 v[38:41], v[150:153], v[166:169], v[38:41]
	v_mfma_f32_16x16x32_bf16 v[58:61], v[154:157], v[186:189], v[58:61]
	v_mfma_f32_16x16x32_bf16 v[58:61], v[158:161], v[190:193], v[58:61]
	v_mfma_f32_16x16x32_bf16 v[50:53], v[154:157], v[178:181], v[50:53]
	v_mfma_f32_16x16x32_bf16 v[50:53], v[158:161], v[182:185], v[50:53]
	v_mfma_f32_16x16x32_bf16 v[42:45], v[154:157], v[170:173], v[42:45]
	v_mfma_f32_16x16x32_bf16 v[42:45], v[158:161], v[174:177], v[42:45]
	s_waitcnt lgkmcnt(0)
	v_mfma_f32_16x16x32_bf16 v[34:37], v[154:157], v[162:165], v[34:37]
	v_mfma_f32_16x16x32_bf16 v[34:37], v[158:161], v[166:169], v[34:37]
	s_setprio 0
	s_setprio 1
	v_mfma_f32_16x16x32_bf16 v[30:33], v[130:133], v[186:189], v[30:33]
	v_mfma_f32_16x16x32_bf16 v[30:33], v[134:137], v[190:193], v[30:33]
	v_mfma_f32_16x16x32_bf16 v[22:25], v[130:133], v[178:181], v[22:25]
	v_mfma_f32_16x16x32_bf16 v[22:25], v[134:137], v[182:185], v[22:25]
	v_mfma_f32_16x16x32_bf16 v[14:17], v[130:133], v[170:173], v[14:17]
	v_mfma_f32_16x16x32_bf16 v[14:17], v[134:137], v[174:177], v[14:17]
	v_mfma_f32_16x16x32_bf16 v[6:9], v[130:133], v[162:165], v[6:9]
	v_mfma_f32_16x16x32_bf16 v[6:9], v[134:137], v[166:169], v[6:9]
	v_mfma_f32_16x16x32_bf16 v[26:29], v[138:141], v[186:189], v[26:29]
	v_mfma_f32_16x16x32_bf16 v[26:29], v[142:145], v[190:193], v[26:29]
	v_mfma_f32_16x16x32_bf16 v[18:21], v[138:141], v[178:181], v[18:21]
	v_mfma_f32_16x16x32_bf16 v[18:21], v[142:145], v[182:185], v[18:21]
	v_mfma_f32_16x16x32_bf16 v[10:13], v[138:141], v[170:173], v[10:13]
	v_mfma_f32_16x16x32_bf16 v[10:13], v[142:145], v[174:177], v[10:13]
	s_setprio 2
	s_barrier
	v_mfma_f32_16x16x32_bf16 v[2:5], v[138:141], v[162:165], v[2:5]
	v_mfma_f32_16x16x32_bf16 v[2:5], v[142:145], v[166:169], v[2:5]
	s_setprio 0
	s_nop 0
	v_add_u32_e32 v142, 0x18000, v214
	v_add_u32_e32 v158, 0x1c000, v214
	ds_read_b128 v[130:133], v142
	ds_read_b128 v[134:137], v142 offset:1024
	ds_read_b128 v[138:141], v142 offset:2048
	ds_read_b128 v[142:145], v142 offset:3072
	ds_read_b128 v[146:149], v158
	ds_read_b128 v[150:153], v158 offset:1024
	ds_read_b128 v[154:157], v158 offset:2048
	ds_read_b128 v[158:161], v158 offset:3072
	ds_read_b128 v[162:165], v215 offset:32768
	ds_read_b128 v[166:169], v215 offset:33792
	ds_read_b128 v[170:173], v215 offset:34816
	ds_read_b128 v[174:177], v215 offset:35840
	ds_read_b128 v[178:181], v215 offset:36864
	ds_read_b128 v[182:185], v215 offset:37888
	ds_read_b128 v[186:189], v215 offset:38912
	ds_read_b128 v[190:193], v215 offset:39936
	s_add_u32 s38, s38, 0x4000
	s_addc_u32 s39, s39, 0
	s_mov_b32 m0, s59
	s_nop 0
	global_load_lds_dwordx4 v195, s[38:39]
	s_add_u32 m0, s59, 0x2000
	s_nop 0
	global_load_lds_dwordx4 v208, s[38:39]
	s_waitcnt vmcnt(8)
	s_waitcnt lgkmcnt(0)
	s_setprio 1
	s_barrier
	v_mfma_f32_16x16x32_bf16 v[126:129], v[130:133], v[162:165], v[126:129]
	v_mfma_f32_16x16x32_bf16 v[126:129], v[134:137], v[166:169], v[126:129]
	s_waitcnt lgkmcnt(5)
	v_mfma_f32_16x16x32_bf16 v[118:121], v[130:133], v[170:173], v[118:121]
	v_mfma_f32_16x16x32_bf16 v[118:121], v[134:137], v[174:177], v[118:121]
	s_waitcnt lgkmcnt(3)
	v_mfma_f32_16x16x32_bf16 v[110:113], v[130:133], v[178:181], v[110:113]
	v_mfma_f32_16x16x32_bf16 v[110:113], v[134:137], v[182:185], v[110:113]
	s_waitcnt lgkmcnt(1)
	v_mfma_f32_16x16x32_bf16 v[102:105], v[130:133], v[186:189], v[102:105]
	v_mfma_f32_16x16x32_bf16 v[102:105], v[134:137], v[190:193], v[102:105]
	v_mfma_f32_16x16x32_bf16 v[122:125], v[138:141], v[162:165], v[122:125]
	v_mfma_f32_16x16x32_bf16 v[122:125], v[142:145], v[166:169], v[122:125]
	v_mfma_f32_16x16x32_bf16 v[114:117], v[138:141], v[170:173], v[114:117]
	v_mfma_f32_16x16x32_bf16 v[114:117], v[142:145], v[174:177], v[114:117]
	v_mfma_f32_16x16x32_bf16 v[106:109], v[138:141], v[178:181], v[106:109]
	v_mfma_f32_16x16x32_bf16 v[106:109], v[142:145], v[182:185], v[106:109]
	s_waitcnt lgkmcnt(0)
	v_mfma_f32_16x16x32_bf16 v[98:101], v[138:141], v[186:189], v[98:101]
	v_mfma_f32_16x16x32_bf16 v[98:101], v[142:145], v[190:193], v[98:101]
	s_setprio 0
	s_setprio 1
	v_mfma_f32_16x16x32_bf16 v[94:97], v[146:149], v[162:165], v[94:97]
	v_mfma_f32_16x16x32_bf16 v[94:97], v[150:153], v[166:169], v[94:97]
	v_mfma_f32_16x16x32_bf16 v[86:89], v[146:149], v[170:173], v[86:89]
	v_mfma_f32_16x16x32_bf16 v[86:89], v[150:153], v[174:177], v[86:89]
	v_mfma_f32_16x16x32_bf16 v[78:81], v[146:149], v[178:181], v[78:81]
	v_mfma_f32_16x16x32_bf16 v[78:81], v[150:153], v[182:185], v[78:81]
	v_mfma_f32_16x16x32_bf16 v[70:73], v[146:149], v[186:189], v[70:73]
	v_mfma_f32_16x16x32_bf16 v[70:73], v[150:153], v[190:193], v[70:73]
	v_mfma_f32_16x16x32_bf16 v[90:93], v[154:157], v[162:165], v[90:93]
	v_mfma_f32_16x16x32_bf16 v[90:93], v[158:161], v[166:169], v[90:93]
	v_mfma_f32_16x16x32_bf16 v[82:85], v[154:157], v[170:173], v[82:85]
	v_mfma_f32_16x16x32_bf16 v[82:85], v[158:161], v[174:177], v[82:85]
	v_mfma_f32_16x16x32_bf16 v[74:77], v[154:157], v[178:181], v[74:77]
	v_mfma_f32_16x16x32_bf16 v[74:77], v[158:161], v[182:185], v[74:77]
	s_setprio 2
	s_barrier
	v_mfma_f32_16x16x32_bf16 v[66:69], v[154:157], v[186:189], v[66:69]
	v_mfma_f32_16x16x32_bf16 v[66:69], v[158:161], v[190:193], v[66:69]
	s_setprio 0
	s_nop 0
	ds_read_b128 v[162:165], v215 offset:49152
	ds_read_b128 v[166:169], v215 offset:50176
	ds_read_b128 v[170:173], v215 offset:51200
	ds_read_b128 v[174:177], v215 offset:52224
	ds_read_b128 v[178:181], v215 offset:53248
	ds_read_b128 v[182:185], v215 offset:54272
	ds_read_b128 v[186:189], v215 offset:55296
	ds_read_b128 v[190:193], v215 offset:56320
	s_mov_b32 m0, s63
	s_nop 0
	global_load_lds_dwordx4 v195, s[42:43]
	s_add_u32 m0, s63, 0x2000
	s_nop 0
	global_load_lds_dwordx4 v208, s[42:43]
	s_add_u32 s14, s14, 0xc000
	s_addc_u32 s15, s15, 0
	s_mov_b32 m0, s65
	s_nop 0
	global_load_lds_dwordx4 v195, s[14:15]
	s_add_u32 m0, s65, 0x2000
	s_nop 0
	global_load_lds_dwordx4 v208, s[14:15]
	s_nop 0
	s_mov_b32 m0, s64
	s_nop 0
	global_load_lds_dwordx4 v195, s[40:41]
	s_add_u32 m0, s64, 0x2000
	s_nop 0
	global_load_lds_dwordx4 v208, s[40:41]
	s_waitcnt vmcnt(8)
	s_waitcnt lgkmcnt(0)
	s_setprio 1
	s_barrier
	v_mfma_f32_16x16x32_bf16 v[62:65], v[130:133], v[162:165], v[62:65]
	v_mfma_f32_16x16x32_bf16 v[62:65], v[134:137], v[166:169], v[62:65]
	s_waitcnt lgkmcnt(5)
	v_mfma_f32_16x16x32_bf16 v[54:57], v[130:133], v[170:173], v[54:57]
	v_mfma_f32_16x16x32_bf16 v[54:57], v[134:137], v[174:177], v[54:57]
	s_waitcnt lgkmcnt(3)
	v_mfma_f32_16x16x32_bf16 v[46:49], v[130:133], v[178:181], v[46:49]
	v_mfma_f32_16x16x32_bf16 v[46:49], v[134:137], v[182:185], v[46:49]
	s_waitcnt lgkmcnt(1)
	v_mfma_f32_16x16x32_bf16 v[38:41], v[130:133], v[186:189], v[38:41]
	v_mfma_f32_16x16x32_bf16 v[38:41], v[134:137], v[190:193], v[38:41]
	v_mfma_f32_16x16x32_bf16 v[58:61], v[138:141], v[162:165], v[58:61]
	v_mfma_f32_16x16x32_bf16 v[58:61], v[142:145], v[166:169], v[58:61]
	v_mfma_f32_16x16x32_bf16 v[50:53], v[138:141], v[170:173], v[50:53]
	v_mfma_f32_16x16x32_bf16 v[50:53], v[142:145], v[174:177], v[50:53]
	v_mfma_f32_16x16x32_bf16 v[42:45], v[138:141], v[178:181], v[42:45]
	v_mfma_f32_16x16x32_bf16 v[42:45], v[142:145], v[182:185], v[42:45]
	s_waitcnt lgkmcnt(0)
	v_mfma_f32_16x16x32_bf16 v[34:37], v[138:141], v[186:189], v[34:37]
	v_mfma_f32_16x16x32_bf16 v[34:37], v[142:145], v[190:193], v[34:37]
	s_setprio 0
	s_setprio 1
	v_mfma_f32_16x16x32_bf16 v[30:33], v[146:149], v[162:165], v[30:33]
	v_mfma_f32_16x16x32_bf16 v[30:33], v[150:153], v[166:169], v[30:33]
	v_mfma_f32_16x16x32_bf16 v[22:25], v[146:149], v[170:173], v[22:25]
	v_mfma_f32_16x16x32_bf16 v[22:25], v[150:153], v[174:177], v[22:25]
	v_mfma_f32_16x16x32_bf16 v[14:17], v[146:149], v[178:181], v[14:17]
	v_mfma_f32_16x16x32_bf16 v[14:17], v[150:153], v[182:185], v[14:17]
	v_mfma_f32_16x16x32_bf16 v[6:9], v[146:149], v[186:189], v[6:9]
	v_mfma_f32_16x16x32_bf16 v[6:9], v[150:153], v[190:193], v[6:9]
	v_mfma_f32_16x16x32_bf16 v[26:29], v[154:157], v[162:165], v[26:29]
	v_mfma_f32_16x16x32_bf16 v[26:29], v[158:161], v[166:169], v[26:29]
	v_mfma_f32_16x16x32_bf16 v[18:21], v[154:157], v[170:173], v[18:21]
	v_mfma_f32_16x16x32_bf16 v[18:21], v[158:161], v[174:177], v[18:21]
	v_mfma_f32_16x16x32_bf16 v[10:13], v[154:157], v[178:181], v[10:13]
	v_mfma_f32_16x16x32_bf16 v[10:13], v[158:161], v[182:185], v[10:13]
	s_setprio 2
	s_barrier
	v_mfma_f32_16x16x32_bf16 v[2:5], v[154:157], v[186:189], v[2:5]
	v_mfma_f32_16x16x32_bf16 v[2:5], v[158:161], v[190:193], v[2:5]
	s_setprio 0
	s_nop 0
	s_cmp_gt_u32 s46, 41
	s_cbranch_scc1 .LBB0_2233
	v_mov_b32_e32 v130, v196
	s_mov_b32 s46, s22
	s_branch .LBB0_2208
